# nt extended: also hipcc's unrolled no-gain transposes (f32 W loads), all cache-conversion loads + their f32 rolled-row stores, final RMSNorm row loads and y stores
# speedup vs baseline: 1.0168x; 1.0018x over previous
; #define LAS __attribute__((address_space(3)))
; template <bool GU>
; __device__ __forceinline__ void transpose_item(const float* W, int K, int N, bf16* WT, const float* gs, LAS float* scr, int item, int lane) {
;     const int nblk = N / 32, kb = item / nblk, nb = item % nblk, k0 = 64 * kb, n0 = 32 * nb;
; #pragma unroll 16
;     for (int i = 0; i < 32; ++i) { const int kk = 2 * i + (lane >> 5); float w = W[(size_t)(k0 + kk) * N + n0 + (lane & 31)]; if (gs) w *= gs[k0 + kk]; scr[kk * 33 + (lane & 31)] = w; }
; __device__ __forceinline__ void conv_weights(LAS unsigned char* lds, unsigned char* ws, const PIn& I, const int l, const int wave, const int lane, const int gw, const int NGW, const int r_lo, const int r_hi) {
;     ...
;         if (r < I_OUT) { transpose_item<false>(I.w_out + (size_t)l * DM * DM, DM, DM, (bf16*)(wb + W_OUT), nullptr, scr, r, lane); continue; } r -= I_OUT;
.LBB0_18:
	s_lshl_b32 s4, s3, 1
	s_add_i32 s4, s4, 0x1f700
	s_and_b32 s5, s4, 0x1ffc0
	s_lshl_b32 s4, s3, 5
	s_and_b32 s4, s4, 0x3e0
	v_add_u32_e32 v46, s5, v1
	v_add_u32_e32 v48, s5, v2
	s_lshl_b32 s6, s4, 2
	v_ashrrev_i32_e32 v49, 31, v48
	v_ashrrev_i32_e32 v47, 31, v46
	v_add_u32_e32 v50, s5, v3
	v_add_u32_e32 v52, s5, v12
	v_add_u32_e32 v94, s5, v13
	v_add_u32_e32 v96, s5, v16
	v_add_u32_e32 v98, s5, v17
	v_add_u32_e32 v100, s5, v18
	v_lshl_add_u64 v[44:45], v[8:9], 0, s[6:7]
	v_lshlrev_b64 v[46:47], 12, v[46:47]
	v_lshlrev_b64 v[48:49], 12, v[48:49]
	v_ashrrev_i32_e32 v53, 31, v52
	v_ashrrev_i32_e32 v51, 31, v50
	v_ashrrev_i32_e32 v97, 31, v96
	v_ashrrev_i32_e32 v95, 31, v94
	v_ashrrev_i32_e32 v101, 31, v100
	v_ashrrev_i32_e32 v99, 31, v98
	v_lshl_add_u64 v[48:49], v[44:45], 0, v[48:49]
	v_lshl_add_u64 v[46:47], v[44:45], 0, v[46:47]
	v_lshlrev_b64 v[50:51], 12, v[50:51]
	v_lshlrev_b64 v[52:53], 12, v[52:53]
	v_lshlrev_b64 v[94:95], 12, v[94:95]
	v_lshlrev_b64 v[96:97], 12, v[96:97]
	v_lshlrev_b64 v[98:99], 12, v[98:99]
	v_lshlrev_b64 v[100:101], 12, v[100:101]
	v_lshl_add_u64 v[52:53], v[44:45], 0, v[52:53]
	v_lshl_add_u64 v[50:51], v[44:45], 0, v[50:51]
	v_lshl_add_u64 v[96:97], v[44:45], 0, v[96:97]
	v_lshl_add_u64 v[94:95], v[44:45], 0, v[94:95]
	v_lshl_add_u64 v[100:101], v[44:45], 0, v[100:101]
	v_lshl_add_u64 v[98:99], v[44:45], 0, v[98:99]
	global_load_dword v93, v[48:49], off nt
	global_load_dword v102, v[46:47], off nt
	global_load_dword v103, v[52:53], off nt
	global_load_dword v104, v[50:51], off nt
	global_load_dword v105, v[96:97], off nt
	global_load_dword v106, v[94:95], off nt
	global_load_dword v107, v[100:101], off nt
	global_load_dword v108, v[98:99], off nt
	v_add_u32_e32 v46, s5, v19
	v_add_u32_e32 v48, s5, v20
	v_ashrrev_i32_e32 v49, 31, v48
	v_ashrrev_i32_e32 v47, 31, v46
	v_add_u32_e32 v50, s5, v21
	v_add_u32_e32 v52, s5, v22
	v_add_u32_e32 v94, s5, v23
	v_add_u32_e32 v96, s5, v24
	v_add_u32_e32 v98, s5, v25
	v_add_u32_e32 v100, s5, v26
	v_lshlrev_b64 v[46:47], 12, v[46:47]
	v_lshlrev_b64 v[48:49], 12, v[48:49]
	v_ashrrev_i32_e32 v53, 31, v52
	v_ashrrev_i32_e32 v51, 31, v50
	v_ashrrev_i32_e32 v97, 31, v96
	v_ashrrev_i32_e32 v95, 31, v94
	v_ashrrev_i32_e32 v101, 31, v100
	v_ashrrev_i32_e32 v99, 31, v98
	v_lshl_add_u64 v[48:49], v[44:45], 0, v[48:49]
	v_lshl_add_u64 v[46:47], v[44:45], 0, v[46:47]
	v_lshlrev_b64 v[50:51], 12, v[50:51]
	v_lshlrev_b64 v[52:53], 12, v[52:53]
	v_lshlrev_b64 v[94:95], 12, v[94:95]
	v_lshlrev_b64 v[96:97], 12, v[96:97]
	v_lshlrev_b64 v[98:99], 12, v[98:99]
	v_lshlrev_b64 v[100:101], 12, v[100:101]
	v_lshl_add_u64 v[52:53], v[44:45], 0, v[52:53]
	v_lshl_add_u64 v[50:51], v[44:45], 0, v[50:51]
	v_lshl_add_u64 v[96:97], v[44:45], 0, v[96:97]
	v_lshl_add_u64 v[94:95], v[44:45], 0, v[94:95]
	v_lshl_add_u64 v[100:101], v[44:45], 0, v[100:101]
	v_lshl_add_u64 v[98:99], v[44:45], 0, v[98:99]
	global_load_dword v109, v[48:49], off nt
	global_load_dword v110, v[46:47], off nt
	global_load_dword v111, v[52:53], off nt
	global_load_dword v112, v[50:51], off nt
	global_load_dword v113, v[96:97], off nt
	global_load_dword v114, v[94:95], off nt
	global_load_dword v115, v[100:101], off nt
	global_load_dword v116, v[98:99], off nt
	v_add_u32_e32 v46, s5, v27
	v_add_u32_e32 v48, s5, v28
	v_ashrrev_i32_e32 v49, 31, v48
	v_ashrrev_i32_e32 v47, 31, v46
	v_add_u32_e32 v50, s5, v29
	v_add_u32_e32 v52, s5, v30
	v_add_u32_e32 v94, s5, v31
	v_add_u32_e32 v96, s5, v32
	v_add_u32_e32 v98, s5, v33
	v_add_u32_e32 v100, s5, v34
	v_lshlrev_b64 v[46:47], 12, v[46:47]
	v_lshlrev_b64 v[48:49], 12, v[48:49]
	v_ashrrev_i32_e32 v53, 31, v52
	v_ashrrev_i32_e32 v51, 31, v50
	v_ashrrev_i32_e32 v97, 31, v96
	v_ashrrev_i32_e32 v95, 31, v94
	v_ashrrev_i32_e32 v101, 31, v100
	v_ashrrev_i32_e32 v99, 31, v98
	v_lshl_add_u64 v[48:49], v[44:45], 0, v[48:49]
	v_lshl_add_u64 v[46:47], v[44:45], 0, v[46:47]
	v_lshlrev_b64 v[50:51], 12, v[50:51]
	v_lshlrev_b64 v[52:53], 12, v[52:53]
	v_lshlrev_b64 v[94:95], 12, v[94:95]
	v_lshlrev_b64 v[96:97], 12, v[96:97]
	v_lshlrev_b64 v[98:99], 12, v[98:99]
	v_lshlrev_b64 v[100:101], 12, v[100:101]
	v_lshl_add_u64 v[52:53], v[44:45], 0, v[52:53]
	v_lshl_add_u64 v[50:51], v[44:45], 0, v[50:51]
	v_lshl_add_u64 v[96:97], v[44:45], 0, v[96:97]
	v_lshl_add_u64 v[94:95], v[44:45], 0, v[94:95]
	v_lshl_add_u64 v[100:101], v[44:45], 0, v[100:101]
	v_lshl_add_u64 v[98:99], v[44:45], 0, v[98:99]
	global_load_dword v117, v[48:49], off nt
	global_load_dword v118, v[46:47], off nt
	global_load_dword v119, v[52:53], off nt
	global_load_dword v120, v[50:51], off nt
	global_load_dword v121, v[96:97], off nt
	global_load_dword v122, v[94:95], off nt
	global_load_dword v123, v[100:101], off nt
	global_load_dword v124, v[98:99], off nt
	v_add_u32_e32 v46, s5, v35
	v_add_u32_e32 v48, s5, v36
	v_ashrrev_i32_e32 v49, 31, v48
	v_ashrrev_i32_e32 v47, 31, v46
	v_add_u32_e32 v50, s5, v37
	v_add_u32_e32 v52, s5, v38
	v_add_u32_e32 v94, s5, v39
	v_add_u32_e32 v96, s5, v40
	v_add_u32_e32 v98, s5, v41
	v_add_u32_e32 v100, s5, v42
	v_lshlrev_b64 v[46:47], 12, v[46:47]
	v_lshlrev_b64 v[48:49], 12, v[48:49]
	v_ashrrev_i32_e32 v53, 31, v52
	v_ashrrev_i32_e32 v51, 31, v50
	v_ashrrev_i32_e32 v97, 31, v96
	v_ashrrev_i32_e32 v95, 31, v94
	v_ashrrev_i32_e32 v101, 31, v100
	v_ashrrev_i32_e32 v99, 31, v98
	v_lshl_add_u64 v[48:49], v[44:45], 0, v[48:49]
	v_lshl_add_u64 v[46:47], v[44:45], 0, v[46:47]
	v_lshlrev_b64 v[50:51], 12, v[50:51]
	v_lshlrev_b64 v[52:53], 12, v[52:53]
	v_lshlrev_b64 v[94:95], 12, v[94:95]
	v_lshlrev_b64 v[96:97], 12, v[96:97]
	v_lshlrev_b64 v[98:99], 12, v[98:99]
	v_lshlrev_b64 v[100:101], 12, v[100:101]
	v_lshl_add_u64 v[52:53], v[44:45], 0, v[52:53]
	v_lshl_add_u64 v[50:51], v[44:45], 0, v[50:51]
	v_lshl_add_u64 v[96:97], v[44:45], 0, v[96:97]
	v_lshl_add_u64 v[94:95], v[44:45], 0, v[94:95]
	v_lshl_add_u64 v[100:101], v[44:45], 0, v[100:101]
	v_lshl_add_u64 v[44:45], v[44:45], 0, v[98:99]
	global_load_dword v98, v[48:49], off nt
	global_load_dword v99, v[46:47], off nt
	global_load_dword v125, v[52:53], off nt
	global_load_dword v126, v[50:51], off nt
	s_nop 0
	global_load_dword v46, v[96:97], off nt
	global_load_dword v47, v[94:95], off nt
	global_load_dword v48, v[100:101], off nt
	global_load_dword v49, v[44:45], off nt
	v_add_u32_e32 v44, v54, v60
	s_waitcnt vmcnt(31)
; #define LAS __attribute__((address_space(3)))
; __device__ __forceinline__ unsigned cvt_pk(float lo, float hi) { unsigned r; asm("v_cvt_pk_bf16_f32 %0, %1, %2" : "=v"(r) : "v"(lo), "v"(hi)); return r; }
; template <bool GU>
; __device__ __forceinline__ void transpose_item(const float* W, int K, int N, bf16* WT, const float* gs, LAS float* scr, int item, int lane) {
;     const int nblk = N / 32, kb = item / nblk, nb = item % nblk, k0 = 64 * kb, n0 = 32 * nb;
;     ...
;     for (int i = 0; i < 32; ++i) { const int kk = 2 * i + (lane >> 5); float w = W[(size_t)(k0 + kk) * N + n0 + (lane & 31)]; if (gs) w *= gs[k0 + kk]; scr[kk * 33 + (lane & 31)] = w; }
;     asm volatile("s_waitcnt lgkmcnt(0)" ::: "memory");
;     int d0 = n0;
;     if (GU) { const int f = (n0 < FF) ? n0 : n0 - FF; d0 = 256 * (f >> 7) + (f & 127) + ((n0 < FF) ? 0 : 128); }
;     const int c = lane & 7;
; #pragma unroll
;     for (int j = 0; j < 4; ++j) { const int n = (lane >> 3) + 8 * j; const LAS float* s = scr + (8 * c) * 33 + n;
;         v4u o; o.x = cvt_pk(s[0 * 33], s[1 * 33]); o.y = cvt_pk(s[2 * 33], s[3 * 33]); o.z = cvt_pk(s[4 * 33], s[5 * 33]); o.w = cvt_pk(s[6 * 33], s[7 * 33]);
;         *(v4u*)(WT + (size_t)(d0 + n) * K + k0 + 8 * c) = o; }
;     asm volatile("s_waitcnt lgkmcnt(0)" ::: "memory");
	ds_write_b32 v44, v93
	s_waitcnt vmcnt(30)
	ds_write_b32 v62, v102
	s_waitcnt vmcnt(29)
	ds_write_b32 v63, v103
	s_waitcnt vmcnt(28)
	ds_write_b32 v64, v104
	s_waitcnt vmcnt(27)
	ds_write_b32 v65, v105
	s_waitcnt vmcnt(26)
	ds_write_b32 v66, v106
	s_waitcnt vmcnt(25)
	ds_write_b32 v67, v107
	s_waitcnt vmcnt(24)
	ds_write_b32 v68, v108
	s_waitcnt vmcnt(23)
	ds_write_b32 v69, v109
	s_waitcnt vmcnt(22)
	ds_write_b32 v70, v110
	s_waitcnt vmcnt(21)
	ds_write_b32 v71, v111
	s_waitcnt vmcnt(20)
	ds_write_b32 v72, v112
	s_waitcnt vmcnt(19)
	ds_write_b32 v73, v113
	s_waitcnt vmcnt(18)
	ds_write_b32 v74, v114
	s_waitcnt vmcnt(17)
	ds_write_b32 v75, v115
	s_waitcnt vmcnt(16)
	ds_write_b32 v76, v116
	s_waitcnt vmcnt(15)
	ds_write_b32 v77, v117
	s_waitcnt vmcnt(14)
	ds_write_b32 v78, v118
	s_waitcnt vmcnt(13)
	ds_write_b32 v79, v119
	s_waitcnt vmcnt(12)
	ds_write_b32 v80, v120
	s_waitcnt vmcnt(11)
	ds_write_b32 v81, v121
	s_waitcnt vmcnt(10)
	ds_write_b32 v82, v122
	s_waitcnt vmcnt(9)
	ds_write_b32 v83, v123
	s_waitcnt vmcnt(8)
	ds_write_b32 v84, v124
	s_waitcnt vmcnt(7)
	ds_write_b32 v85, v98
	s_waitcnt vmcnt(6)
	ds_write_b32 v86, v99
	s_waitcnt vmcnt(5)
	ds_write_b32 v87, v125
	s_waitcnt vmcnt(4)
	ds_write_b32 v88, v126
	s_waitcnt vmcnt(3)
	ds_write_b32 v89, v46
	s_waitcnt vmcnt(2)
	ds_write_b32 v90, v47
	s_waitcnt vmcnt(1)
	ds_write_b32 v91, v48
	s_waitcnt vmcnt(0)
	ds_write_b32 v92, v49
	s_waitcnt lgkmcnt(0)
	ds_read2_b32 v[48:49], v56 offset0:33 offset1:41
	ds_read2_b32 v[50:51], v56 offset1:8
	ds_read2_b32 v[52:53], v56 offset0:66 offset1:74
	ds_read2_b32 v[94:95], v56 offset0:99 offset1:107
	ds_read2_b32 v[96:97], v56 offset0:132 offset1:140
	ds_read2_b32 v[98:99], v56 offset0:165 offset1:173
	ds_read2_b32 v[100:101], v56 offset0:198 offset1:206
	ds_read2_b32 v[102:103], v56 offset0:231 offset1:239
	v_add_u32_e32 v106, s4, v55
	s_lshl_b32 s6, s5, 1
	v_ashrrev_i32_e32 v107, 31, v106
	v_lshl_add_u64 v[104:105], v[4:5], 0, s[6:7]
	v_lshlrev_b64 v[106:107], 11, v[106:107]
	s_waitcnt lgkmcnt(6)
	v_cvt_pk_bf16_f32 v44, v50, v48
	v_lshl_add_u64 v[106:107], v[104:105], 0, v[106:107]
	v_add_u32_e32 v48, s4, v57
	s_waitcnt lgkmcnt(4)
	v_cvt_pk_bf16_f32 v45, v52, v94
	s_waitcnt lgkmcnt(2)
	v_cvt_pk_bf16_f32 v46, v96, v98
	s_waitcnt lgkmcnt(0)
	v_cvt_pk_bf16_f32 v47, v100, v102
	global_store_dwordx4 v[106:107], v[44:47], off
	s_nop 1
	v_cvt_pk_bf16_f32 v44, v51, v49
	v_ashrrev_i32_e32 v49, 31, v48
	v_lshlrev_b64 v[48:49], 11, v[48:49]
	v_cvt_pk_bf16_f32 v45, v53, v95
	v_cvt_pk_bf16_f32 v46, v97, v99
	v_cvt_pk_bf16_f32 v47, v101, v103
	v_lshl_add_u64 v[48:49], v[104:105], 0, v[48:49]
	ds_read2_b32 v[50:51], v56 offset0:16 offset1:24
	ds_read2_b32 v[52:53], v56 offset0:49 offset1:57
	ds_read2_b32 v[94:95], v56 offset0:82 offset1:90
	ds_read2_b32 v[96:97], v56 offset0:115 offset1:123
	ds_read2_b32 v[98:99], v56 offset0:148 offset1:156
	ds_read2_b32 v[100:101], v56 offset0:181 offset1:189
	ds_read2_b32 v[102:103], v56 offset0:214 offset1:222
	ds_read2_b32 v[106:107], v56 offset0:247 offset1:255
	global_store_dwordx4 v[48:49], v[44:47], off
	v_add_u32_e32 v48, s4, v58
	v_ashrrev_i32_e32 v49, 31, v48
	v_lshlrev_b64 v[48:49], 11, v[48:49]
	v_lshl_add_u64 v[48:49], v[104:105], 0, v[48:49]
	s_waitcnt lgkmcnt(6)
	v_cvt_pk_bf16_f32 v44, v50, v52
	s_waitcnt lgkmcnt(4)
	v_cvt_pk_bf16_f32 v45, v94, v96
	s_waitcnt lgkmcnt(2)
	v_cvt_pk_bf16_f32 v46, v98, v100
	s_waitcnt lgkmcnt(0)
	v_cvt_pk_bf16_f32 v47, v102, v106
	global_store_dwordx4 v[48:49], v[44:47], off
	v_add_u32_e32 v48, s4, v59
	v_ashrrev_i32_e32 v49, 31, v48
	v_lshlrev_b64 v[48:49], 11, v[48:49]
	v_lshl_add_u64 v[48:49], v[104:105], 0, v[48:49]
	v_cvt_pk_bf16_f32 v44, v51, v53
	v_cvt_pk_bf16_f32 v45, v95, v97
	v_cvt_pk_bf16_f32 v46, v99, v101
	v_cvt_pk_bf16_f32 v47, v103, v107
	global_store_dwordx4 v[48:49], v[44:47], off
	s_waitcnt lgkmcnt(0)
	s_cbranch_execnz .LBB0_15
.LBB0_19:
	s_mul_hi_i32 s4, s3, 0x38e38e39
	s_lshr_b32 s5, s4, 31
	s_ashr_i32 s4, s4, 4
	s_add_i32 s4, s4, s5
	s_mul_i32 s5, s4, 0x48
	s_sub_i32 s5, s3, s5
	s_lshl_b32 s12, s5, 5
	s_lshl_b32 s14, s4, 6
	s_ashr_i32 s13, s12, 31
	s_lshl_b64 s[4:5], s[12:13], 2
	v_add_u32_e32 v50, s14, v14
	s_ashr_i32 s15, s14, 31
	v_ashrrev_i32_e32 v51, 31, v50
	v_mov_b64_e32 v[52:53], s[4:5]
	v_lshl_add_u64 v[44:45], v[10:11], 0, s[4:5]
	v_lshl_add_u64 v[46:47], v[14:15], 0, s[14:15]
	v_lshl_add_u64 v[48:49], v[50:51], 2, s[76:77]
	v_mad_i64_i32 v[50:51], s[4:5], v50, s2, v[52:53]
	v_add_u32_e32 v93, s14, v25
	v_lshl_add_u64 v[46:47], v[46:47], 2, s[76:77]
	v_lshl_add_u64 v[50:51], v[10:11], 0, v[50:51]
	s_mov_b64 s[16:17], 0
	v_mov_b32_e32 v94, v61
	s_andn2_b64 vcc, exec, s[8:9]
	s_cbranch_vccnz .LBB0_21
; template <bool GU>
; __device__ __forceinline__ void transpose_item(const float* W, int K, int N, bf16* WT, const float* gs, LAS float* scr, int item, int lane) {
;     ...
;     for (int i = 0; i < 32; ++i) { const int kk = 2 * i + (lane >> 5); float w = W[(size_t)(k0 + kk) * N + n0 + (lane & 31)]; if (gs) w *= gs[k0 + kk]; scr[kk * 33 + (lane & 31)] = w; }
	s_mov_b64 s[58:59], 0x4800
	v_mov_b32_e32 v234, v50
	v_mov_b32_e32 v235, v51
	v_mov_b32_e32 v236, v48
	v_mov_b32_e32 v237, v49
	global_load_dword v166, v[234:235], off nt
	v_lshl_add_u64 v[234:235], v[234:235], 0, s[58:59]
	global_load_dword v167, v[234:235], off nt
	v_lshl_add_u64 v[234:235], v[234:235], 0, s[58:59]
	global_load_dword v168, v[234:235], off nt
	v_lshl_add_u64 v[234:235], v[234:235], 0, s[58:59]
	global_load_dword v169, v[234:235], off nt
	v_lshl_add_u64 v[234:235], v[234:235], 0, s[58:59]
	global_load_dword v170, v[234:235], off nt
	v_lshl_add_u64 v[234:235], v[234:235], 0, s[58:59]
	global_load_dword v171, v[234:235], off nt
	v_lshl_add_u64 v[234:235], v[234:235], 0, s[58:59]
	global_load_dword v172, v[234:235], off nt
	v_lshl_add_u64 v[234:235], v[234:235], 0, s[58:59]
	global_load_dword v173, v[234:235], off nt
	v_lshl_add_u64 v[234:235], v[234:235], 0, s[58:59]
	global_load_dword v174, v[234:235], off nt
	v_lshl_add_u64 v[234:235], v[234:235], 0, s[58:59]
	global_load_dword v175, v[234:235], off nt
	v_lshl_add_u64 v[234:235], v[234:235], 0, s[58:59]
	global_load_dword v176, v[234:235], off nt
	v_lshl_add_u64 v[234:235], v[234:235], 0, s[58:59]
	global_load_dword v177, v[234:235], off nt
	v_lshl_add_u64 v[234:235], v[234:235], 0, s[58:59]
	global_load_dword v178, v[234:235], off nt
	v_lshl_add_u64 v[234:235], v[234:235], 0, s[58:59]
	global_load_dword v179, v[234:235], off nt
	v_lshl_add_u64 v[234:235], v[234:235], 0, s[58:59]
	global_load_dword v180, v[234:235], off nt
	v_lshl_add_u64 v[234:235], v[234:235], 0, s[58:59]
	global_load_dword v181, v[234:235], off nt
	v_lshl_add_u64 v[234:235], v[234:235], 0, s[58:59]
	global_load_dword v182, v[234:235], off nt
	v_lshl_add_u64 v[234:235], v[234:235], 0, s[58:59]
	global_load_dword v183, v[234:235], off nt
	v_lshl_add_u64 v[234:235], v[234:235], 0, s[58:59]
	global_load_dword v184, v[234:235], off nt
	v_lshl_add_u64 v[234:235], v[234:235], 0, s[58:59]
	global_load_dword v185, v[234:235], off nt
	v_lshl_add_u64 v[234:235], v[234:235], 0, s[58:59]
	global_load_dword v186, v[234:235], off nt
	v_lshl_add_u64 v[234:235], v[234:235], 0, s[58:59]
	global_load_dword v187, v[234:235], off nt
	v_lshl_add_u64 v[234:235], v[234:235], 0, s[58:59]
	global_load_dword v188, v[234:235], off nt
	v_lshl_add_u64 v[234:235], v[234:235], 0, s[58:59]
	global_load_dword v189, v[234:235], off nt
	v_lshl_add_u64 v[234:235], v[234:235], 0, s[58:59]
	global_load_dword v190, v[234:235], off nt
	v_lshl_add_u64 v[234:235], v[234:235], 0, s[58:59]
	global_load_dword v191, v[234:235], off nt
	v_lshl_add_u64 v[234:235], v[234:235], 0, s[58:59]
	global_load_dword v192, v[234:235], off nt
	v_lshl_add_u64 v[234:235], v[234:235], 0, s[58:59]
	global_load_dword v193, v[234:235], off nt
	v_lshl_add_u64 v[234:235], v[234:235], 0, s[58:59]
	global_load_dword v194, v[234:235], off nt
	v_lshl_add_u64 v[234:235], v[234:235], 0, s[58:59]
	global_load_dword v195, v[234:235], off nt
	v_lshl_add_u64 v[234:235], v[234:235], 0, s[58:59]
	global_load_dword v199, v[234:235], off nt
	v_lshl_add_u64 v[234:235], v[234:235], 0, s[58:59]
	global_load_dword v200, v[234:235], off nt
	global_load_dword v201, v[236:237], off nt
	global_load_dword v202, v[236:237], off offset:8
	global_load_dword v203, v[236:237], off offset:16
	global_load_dword v204, v[236:237], off offset:24
	global_load_dword v205, v[236:237], off offset:32
	global_load_dword v206, v[236:237], off offset:40
	global_load_dword v207, v[236:237], off offset:48
	global_load_dword v208, v[236:237], off offset:56
	global_load_dword v209, v[236:237], off offset:64
	global_load_dword v210, v[236:237], off offset:72
	global_load_dword v211, v[236:237], off offset:80
	global_load_dword v212, v[236:237], off offset:88
	global_load_dword v213, v[236:237], off offset:96
	global_load_dword v214, v[236:237], off offset:104
	global_load_dword v215, v[236:237], off offset:112
	global_load_dword v216, v[236:237], off offset:120
	global_load_dword v217, v[236:237], off offset:128
	global_load_dword v218, v[236:237], off offset:136
	global_load_dword v219, v[236:237], off offset:144
	global_load_dword v220, v[236:237], off offset:152
	global_load_dword v221, v[236:237], off offset:160
	global_load_dword v222, v[236:237], off offset:168
	global_load_dword v223, v[236:237], off offset:176
	global_load_dword v224, v[236:237], off offset:184
	global_load_dword v225, v[236:237], off offset:192
	global_load_dword v226, v[236:237], off offset:200
	global_load_dword v227, v[236:237], off offset:208
	global_load_dword v228, v[236:237], off offset:216
	global_load_dword v229, v[236:237], off offset:224
	global_load_dword v230, v[236:237], off offset:232
	global_load_dword v231, v[236:237], off offset:240
	global_load_dword v232, v[236:237], off offset:248
	s_waitcnt vmcnt(31)
; template <bool GU>
; __device__ __forceinline__ void transpose_item(const float* W, int K, int N, bf16* WT, const float* gs, LAS float* scr, int item, int lane) {
;     ...
;     for (int i = 0; i < 32; ++i) { const int kk = 2 * i + (lane >> 5); float w = W[(size_t)(k0 + kk) * N + n0 + (lane & 31)]; if (gs) w *= gs[k0 + kk]; scr[kk * 33 + (lane & 31)] = w; }
	v_mul_f32_e32 v166, v166, v201
	ds_write_b32 v94, v166
	s_waitcnt vmcnt(30)
	v_mul_f32_e32 v167, v167, v202
	ds_write_b32 v94, v167 offset:264
	s_waitcnt vmcnt(29)
	v_mul_f32_e32 v168, v168, v203
	ds_write_b32 v94, v168 offset:528
	s_waitcnt vmcnt(28)
	v_mul_f32_e32 v169, v169, v204
	ds_write_b32 v94, v169 offset:792
	s_waitcnt vmcnt(27)
	v_mul_f32_e32 v170, v170, v205
	ds_write_b32 v94, v170 offset:1056
	s_waitcnt vmcnt(26)
	v_mul_f32_e32 v171, v171, v206
	ds_write_b32 v94, v171 offset:1320
	s_waitcnt vmcnt(25)
	v_mul_f32_e32 v172, v172, v207
	ds_write_b32 v94, v172 offset:1584
	s_waitcnt vmcnt(24)
	v_mul_f32_e32 v173, v173, v208
	ds_write_b32 v94, v173 offset:1848
	s_waitcnt vmcnt(23)
	v_mul_f32_e32 v174, v174, v209
	ds_write_b32 v94, v174 offset:2112
	s_waitcnt vmcnt(22)
	v_mul_f32_e32 v175, v175, v210
	ds_write_b32 v94, v175 offset:2376
	s_waitcnt vmcnt(21)
	v_mul_f32_e32 v176, v176, v211
	ds_write_b32 v94, v176 offset:2640
	s_waitcnt vmcnt(20)
	v_mul_f32_e32 v177, v177, v212
	ds_write_b32 v94, v177 offset:2904
	s_waitcnt vmcnt(19)
	v_mul_f32_e32 v178, v178, v213
	ds_write_b32 v94, v178 offset:3168
	s_waitcnt vmcnt(18)
	v_mul_f32_e32 v179, v179, v214
	ds_write_b32 v94, v179 offset:3432
	s_waitcnt vmcnt(17)
	v_mul_f32_e32 v180, v180, v215
	ds_write_b32 v94, v180 offset:3696
	s_waitcnt vmcnt(16)
	v_mul_f32_e32 v181, v181, v216
	ds_write_b32 v94, v181 offset:3960
	s_waitcnt vmcnt(15)
	v_mul_f32_e32 v182, v182, v217
	ds_write_b32 v94, v182 offset:4224
	s_waitcnt vmcnt(14)
	v_mul_f32_e32 v183, v183, v218
	ds_write_b32 v94, v183 offset:4488
	s_waitcnt vmcnt(13)
	v_mul_f32_e32 v184, v184, v219
	ds_write_b32 v94, v184 offset:4752
	s_waitcnt vmcnt(12)
	v_mul_f32_e32 v185, v185, v220
	ds_write_b32 v94, v185 offset:5016
	s_waitcnt vmcnt(11)
	v_mul_f32_e32 v186, v186, v221
	ds_write_b32 v94, v186 offset:5280
	s_waitcnt vmcnt(10)
	v_mul_f32_e32 v187, v187, v222
	ds_write_b32 v94, v187 offset:5544
	s_waitcnt vmcnt(9)
	v_mul_f32_e32 v188, v188, v223
	ds_write_b32 v94, v188 offset:5808
	s_waitcnt vmcnt(8)
	v_mul_f32_e32 v189, v189, v224
	ds_write_b32 v94, v189 offset:6072
	s_waitcnt vmcnt(7)
	v_mul_f32_e32 v190, v190, v225
	ds_write_b32 v94, v190 offset:6336
	s_waitcnt vmcnt(6)
	v_mul_f32_e32 v191, v191, v226
	ds_write_b32 v94, v191 offset:6600
	s_waitcnt vmcnt(5)
	v_mul_f32_e32 v192, v192, v227
	ds_write_b32 v94, v192 offset:6864
	s_waitcnt vmcnt(4)
	v_mul_f32_e32 v193, v193, v228
	ds_write_b32 v94, v193 offset:7128
	s_waitcnt vmcnt(3)
	v_mul_f32_e32 v194, v194, v229
	ds_write_b32 v94, v194 offset:7392
	s_waitcnt vmcnt(2)
	v_mul_f32_e32 v195, v195, v230
	ds_write_b32 v94, v195 offset:7656
	s_waitcnt vmcnt(1)
	v_mul_f32_e32 v199, v199, v231
	ds_write_b32 v94, v199 offset:7920
	s_waitcnt vmcnt(0)
	v_mul_f32_e32 v200, v200, v232
	ds_write_b32 v94, v200 offset:8184
	s_branch .LBB0_14

; template <bool GU>
; __device__ __forceinline__ void transpose_item(const float* W, int K, int N, bf16* WT, const float* gs, LAS float* scr, int item, int lane) {
;     const int nblk = N / 32, kb = item / nblk, nb = item % nblk, k0 = 64 * kb, n0 = 32 * nb;
; #pragma unroll 16
;     for (int i = 0; i < 32; ++i) { const int kk = 2 * i + (lane >> 5); float w = W[(size_t)(k0 + kk) * N + n0 + (lane & 31)]; if (gs) w *= gs[k0 + kk]; scr[kk * 33 + (lane & 31)] = w; }
.LBB0_21:
	global_load_dword v52, v[50:51], off nt
	v_cndmask_b32_e64 v53, 0, 1, s[8:9]
	v_cmp_ne_u32_e64 s[4:5], 1, v53
	s_andn2_b64 vcc, exec, s[8:9]
	s_cbranch_vccnz .LBB0_23
	v_lshl_add_u64 v[96:97], v[48:49], 0, s[16:17]
	global_load_dword v53, v[96:97], off nt
	s_waitcnt vmcnt(0)
	v_mul_f32_e32 v52, v52, v53
.LBB0_23:
	v_subrev_u32_e32 v53, 28, v93
	v_mad_i64_i32 v[96:97], s[18:19], v53, s2, v[44:45]
	global_load_dword v95, v[96:97], off nt
	s_waitcnt vmcnt(1)
	ds_write_b32 v94, v52
	s_and_b64 vcc, exec, s[4:5]
	v_lshl_add_u64 v[52:53], v[46:47], 0, s[16:17]
	s_cbranch_vccnz .LBB0_25
	global_load_dword v96, v[52:53], off offset:8
	s_waitcnt vmcnt(0)
	v_mul_f32_e32 v95, v95, v96
.LBB0_25:
	v_subrev_u32_e32 v96, 26, v93
	v_mad_i64_i32 v[96:97], s[18:19], v96, s2, v[44:45]
	global_load_dword v96, v[96:97], off nt
	s_and_b64 vcc, exec, s[4:5]
	s_waitcnt vmcnt(1)
	ds_write_b32 v94, v95 offset:264
	s_cbranch_vccnz .LBB0_27
	global_load_dword v95, v[52:53], off offset:16
	s_waitcnt vmcnt(0)
	v_mul_f32_e32 v96, v96, v95
.LBB0_27:
	v_subrev_u32_e32 v95, 24, v93
	v_mad_i64_i32 v[98:99], s[18:19], v95, s2, v[44:45]
	global_load_dword v95, v[98:99], off nt
	s_and_b64 vcc, exec, s[4:5]
	s_waitcnt vmcnt(1)
	ds_write_b32 v94, v96 offset:528
	s_cbranch_vccnz .LBB0_29
	global_load_dword v96, v[52:53], off offset:24
	s_waitcnt vmcnt(0)
	v_mul_f32_e32 v95, v95, v96
.LBB0_29:
	v_subrev_u32_e32 v96, 22, v93
	v_mad_i64_i32 v[96:97], s[18:19], v96, s2, v[44:45]
	global_load_dword v96, v[96:97], off nt
	s_and_b64 vcc, exec, s[4:5]
	s_waitcnt vmcnt(1)
	ds_write_b32 v94, v95 offset:792
	s_cbranch_vccnz .LBB0_31
	global_load_dword v95, v[52:53], off offset:32
	s_waitcnt vmcnt(0)
	v_mul_f32_e32 v96, v96, v95
.LBB0_31:
	v_subrev_u32_e32 v95, 20, v93
	v_mad_i64_i32 v[98:99], s[18:19], v95, s2, v[44:45]
	global_load_dword v95, v[98:99], off nt
	s_and_b64 vcc, exec, s[4:5]
	s_waitcnt vmcnt(1)
	ds_write_b32 v94, v96 offset:1056
	s_cbranch_vccnz .LBB0_33
	global_load_dword v96, v[52:53], off offset:40
	s_waitcnt vmcnt(0)
	v_mul_f32_e32 v95, v95, v96
.LBB0_33:
	v_subrev_u32_e32 v96, 18, v93
	v_mad_i64_i32 v[96:97], s[18:19], v96, s2, v[44:45]
	global_load_dword v96, v[96:97], off nt
	s_and_b64 vcc, exec, s[4:5]
	s_waitcnt vmcnt(1)
	ds_write_b32 v94, v95 offset:1320
	s_cbranch_vccnz .LBB0_35
	global_load_dword v95, v[52:53], off offset:48
	s_waitcnt vmcnt(0)
	v_mul_f32_e32 v96, v96, v95
.LBB0_35:
	v_add_u32_e32 v95, -16, v93
	v_mad_i64_i32 v[98:99], s[18:19], v95, s2, v[44:45]
	global_load_dword v95, v[98:99], off nt
	s_and_b64 vcc, exec, s[4:5]
	s_waitcnt vmcnt(1)
	ds_write_b32 v94, v96 offset:1584
	s_cbranch_vccnz .LBB0_37
	global_load_dword v96, v[52:53], off offset:56
	s_waitcnt vmcnt(0)
	v_mul_f32_e32 v95, v95, v96
.LBB0_37:
	v_add_u32_e32 v96, -14, v93
	v_mad_i64_i32 v[96:97], s[18:19], v96, s2, v[44:45]
	global_load_dword v96, v[96:97], off nt
	s_and_b64 vcc, exec, s[4:5]
	s_waitcnt vmcnt(1)
	ds_write_b32 v94, v95 offset:1848
	s_cbranch_vccnz .LBB0_39
	global_load_dword v95, v[52:53], off offset:64
	s_waitcnt vmcnt(0)
	v_mul_f32_e32 v96, v96, v95
.LBB0_39:
	v_add_u32_e32 v95, -12, v93
	v_mad_i64_i32 v[98:99], s[18:19], v95, s2, v[44:45]
	global_load_dword v95, v[98:99], off nt
	s_and_b64 vcc, exec, s[4:5]
	s_waitcnt vmcnt(1)
	ds_write_b32 v94, v96 offset:2112
	s_cbranch_vccnz .LBB0_41
	global_load_dword v96, v[52:53], off offset:72
	s_waitcnt vmcnt(0)
	v_mul_f32_e32 v95, v95, v96
.LBB0_41:
	v_add_u32_e32 v96, -10, v93
	v_mad_i64_i32 v[96:97], s[18:19], v96, s2, v[44:45]
	global_load_dword v96, v[96:97], off nt
	s_and_b64 vcc, exec, s[4:5]
	s_waitcnt vmcnt(1)
	ds_write_b32 v94, v95 offset:2376
	s_cbranch_vccnz .LBB0_43
	global_load_dword v95, v[52:53], off offset:80
	s_waitcnt vmcnt(0)
	v_mul_f32_e32 v96, v96, v95
.LBB0_43:
	v_add_u32_e32 v95, -8, v93
	v_mad_i64_i32 v[98:99], s[18:19], v95, s2, v[44:45]
	global_load_dword v95, v[98:99], off nt
	s_and_b64 vcc, exec, s[4:5]
	s_waitcnt vmcnt(1)
	ds_write_b32 v94, v96 offset:2640
	s_cbranch_vccnz .LBB0_45
	global_load_dword v96, v[52:53], off offset:88
	s_waitcnt vmcnt(0)
	v_mul_f32_e32 v95, v95, v96
.LBB0_45:
	v_add_u32_e32 v96, -6, v93
	v_mad_i64_i32 v[96:97], s[18:19], v96, s2, v[44:45]
	global_load_dword v96, v[96:97], off nt
	s_and_b64 vcc, exec, s[4:5]
	s_waitcnt vmcnt(1)
	ds_write_b32 v94, v95 offset:2904
	s_cbranch_vccnz .LBB0_47
	global_load_dword v95, v[52:53], off offset:96
	s_waitcnt vmcnt(0)
	v_mul_f32_e32 v96, v96, v95
.LBB0_47:
	v_add_u32_e32 v95, -4, v93
	v_mad_i64_i32 v[98:99], s[18:19], v95, s2, v[44:45]
	global_load_dword v95, v[98:99], off nt
	s_and_b64 vcc, exec, s[4:5]
	s_waitcnt vmcnt(1)
	ds_write_b32 v94, v96 offset:3168
	s_cbranch_vccnz .LBB0_49
	global_load_dword v96, v[52:53], off offset:104
	s_waitcnt vmcnt(0)
	v_mul_f32_e32 v95, v95, v96
.LBB0_49:
	v_add_u32_e32 v96, -2, v93
	v_mad_i64_i32 v[96:97], s[18:19], v96, s2, v[44:45]
	global_load_dword v96, v[96:97], off nt
	s_and_b64 vcc, exec, s[4:5]
	s_waitcnt vmcnt(1)
	ds_write_b32 v94, v95 offset:3432
	s_cbranch_vccnz .LBB0_51
	global_load_dword v95, v[52:53], off offset:112
	s_waitcnt vmcnt(0)
	v_mul_f32_e32 v96, v96, v95
.LBB0_51:
	v_mad_i64_i32 v[98:99], s[18:19], v93, s2, v[44:45]
	global_load_dword v95, v[98:99], off nt
	s_and_b64 vcc, exec, s[4:5]
	s_waitcnt vmcnt(1)
	ds_write_b32 v94, v96 offset:3696
	s_cbranch_vccnz .LBB0_20
	global_load_dword v52, v[52:53], off offset:120
	s_waitcnt vmcnt(0)
	v_mul_f32_e32 v95, v95, v52
	s_branch .LBB0_20

; __device__ __forceinline__ unsigned cvt_pk(float lo, float hi) { unsigned r; asm("v_cvt_pk_bf16_f32 %0, %1, %2" : "=v"(r) : "v"(lo), "v"(hi)); return r; }
;     ...
;     for (size_t i = gtid * 8; i < NA; i += gth * 8) {
;         const size_t gi = (size_t)l * NA + i;
;         const f32x4 a = *(const f32x4*)(I.cak + gi), b = *(const f32x4*)(I.cak + gi + 4), c = *(const f32x4*)(I.cav + gi), d = *(const f32x4*)(I.cav + gi + 4);
;         v4u w; w.x = cvt_pk(a[0], a[1]); w.y = cvt_pk(a[2], a[3]); w.z = cvt_pk(b[0], b[1]); w.w = cvt_pk(b[2], b[3]);
;         *(v4u*)((bf16*)(ws + WS_CKA) + gi) = w;
;         w.x = cvt_pk(c[0], c[1]); w.y = cvt_pk(c[2], c[3]); w.z = cvt_pk(d[0], d[1]); w.w = cvt_pk(d[2], d[3]);
;         *(v4u*)((bf16*)(ws + WS_CVA) + gi) = w;
;         if (((i >> 9) & 511) >= 64) { float* dk = out + O_AKS + gi - 32768; float* dv = out + O_AVS + gi - 32768;
;             *(f32x4*)dk = a; *(f32x4*)(dk + 4) = b; *(f32x4*)dv = c; *(f32x4*)(dv + 4) = d; }
;     }
.LBB0_294:
	v_lshl_add_u64 v[0:1], s[12:13], 0, v[18:19]
	global_load_dwordx4 v[4:7], v[0:1], off offset:-16 nt
	s_nop 0
	global_load_dwordx4 v[0:3], v[0:1], off nt
	v_lshl_add_u64 v[8:9], s[14:15], 0, v[18:19]
	s_waitcnt lgkmcnt(0)
	global_load_dwordx4 v[12:15], v[8:9], off offset:-16 nt
	s_nop 0
	global_load_dwordx4 v[8:11], v[8:9], off nt
	v_add_co_u32_e32 v36, vcc, 0x1000000, v22
	v_and_b32_e32 v24, 0x38000, v26
	s_nop 0
	v_addc_co_u32_e32 v37, vcc, 0, v23, vcc
	v_cmp_ne_u64_e32 vcc, 0, v[24:25]
	s_waitcnt vmcnt(3)
	v_cvt_pk_bf16_f32 v28, v4, v5
	v_cvt_pk_bf16_f32 v29, v6, v7
	s_waitcnt vmcnt(2)
	v_cvt_pk_bf16_f32 v30, v0, v1
	v_cvt_pk_bf16_f32 v31, v2, v3
	s_waitcnt vmcnt(1)
	v_cvt_pk_bf16_f32 v32, v12, v13
	v_cvt_pk_bf16_f32 v33, v14, v15
	s_waitcnt vmcnt(0)
	v_cvt_pk_bf16_f32 v34, v8, v9
	v_cvt_pk_bf16_f32 v35, v10, v11
	global_store_dwordx4 v[22:23], v[28:31], off
	global_store_dwordx4 v[36:37], v[32:35], off
	s_and_saveexec_b64 s[52:53], vcc
	s_cbranch_execz .LBB0_293
	v_lshl_add_u64 v[28:29], s[42:43], 0, v[18:19]
	v_add_co_u32_e32 v30, vcc, 0x8c60000, v28
	s_nop 1
	v_addc_co_u32_e32 v31, vcc, 0, v29, vcc
	global_store_dwordx4 v[30:31], v[4:7], off nt
	global_store_dwordx4 v[30:31], v[0:3], off offset:16 nt
	s_nop 1
	v_add_co_u32_e32 v0, vcc, 0xac60000, v28
	s_nop 1
	v_addc_co_u32_e32 v1, vcc, 0, v29, vcc
	global_store_dwordx4 v[0:1], v[12:15], off nt
	global_store_dwordx4 v[0:1], v[8:11], off offset:16 nt
	s_branch .LBB0_293

; __device__ __forceinline__ unsigned cvt_pk(float lo, float hi) { unsigned r; asm("v_cvt_pk_bf16_f32 %0, %1, %2" : "=v"(r) : "v"(lo), "v"(hi)); return r; }
;     ...
;     for (size_t i = gtid * 8; i < NB; i += gth * 8) {
;         const size_t gi = (size_t)l * NB + i;
;         const f32x4 a = *(const f32x4*)(I.cbk + gi), b = *(const f32x4*)(I.cbk + gi + 4), c = *(const f32x4*)(I.cbv + gi), d = *(const f32x4*)(I.cbv + gi + 4);
;         v4u w; w.x = cvt_pk(a[0], a[1]); w.y = cvt_pk(a[2], a[3]); w.z = cvt_pk(b[0], b[1]); w.w = cvt_pk(b[2], b[3]);
;         *(v4u*)((bf16*)(ws + WS_CKB) + gi) = w;
;         w.x = cvt_pk(c[0], c[1]); w.y = cvt_pk(c[2], c[3]); w.z = cvt_pk(d[0], d[1]); w.w = cvt_pk(d[2], d[3]);
;         *(v4u*)((bf16*)(ws + WS_CVB) + gi) = w;
;         if (((i >> 7) & 127) >= 64) { float* dk = out + O_BKS + gi - 8192; float* dv = out + O_BVS + gi - 8192;
;             *(f32x4*)dk = a; *(f32x4*)(dk + 4) = b; *(f32x4*)dv = c; *(f32x4*)(dv + 4) = d; }
;     }
.LBB0_299:
	v_lshl_add_u64 v[0:1], s[12:13], 0, v[18:19]
	global_load_dwordx4 v[4:7], v[0:1], off offset:-16 nt
	s_nop 0
	global_load_dwordx4 v[0:3], v[0:1], off nt
	v_lshl_add_u64 v[8:9], s[6:7], 0, v[18:19]
	s_waitcnt lgkmcnt(0)
	global_load_dwordx4 v[12:15], v[8:9], off offset:-16 nt
	s_nop 0
	global_load_dwordx4 v[8:11], v[8:9], off nt
	v_add_co_u32_e32 v30, vcc, 0x100000, v20
	v_and_b32_e32 v32, 0x2000, v16
	s_nop 0
	v_addc_co_u32_e32 v31, vcc, 0, v21, vcc
	v_cmp_ne_u32_e32 vcc, 0, v32
	s_waitcnt vmcnt(3)
	v_cvt_pk_bf16_f32 v22, v4, v5
	v_cvt_pk_bf16_f32 v23, v6, v7
	s_waitcnt vmcnt(2)
	v_cvt_pk_bf16_f32 v24, v0, v1
	v_cvt_pk_bf16_f32 v25, v2, v3
	s_waitcnt vmcnt(1)
	v_cvt_pk_bf16_f32 v26, v12, v13
	v_cvt_pk_bf16_f32 v27, v14, v15
	s_waitcnt vmcnt(0)
	v_cvt_pk_bf16_f32 v28, v8, v9
	v_cvt_pk_bf16_f32 v29, v10, v11
	global_store_dwordx4 v[20:21], v[22:25], off
	global_store_dwordx4 v[30:31], v[26:29], off
	s_and_saveexec_b64 s[42:43], vcc
	s_cbranch_execz .LBB0_298
	v_lshl_add_u64 v[22:23], s[40:41], 0, v[18:19]
	v_add_co_u32_e32 v24, vcc, 0xcc78000, v22
	s_nop 1
	v_addc_co_u32_e32 v25, vcc, 0, v23, vcc
	global_store_dwordx4 v[24:25], v[4:7], off nt
	global_store_dwordx4 v[24:25], v[0:3], off offset:16 nt
	s_nop 1
	v_add_co_u32_e32 v0, vcc, 0xce78000, v22
	s_nop 1
	v_addc_co_u32_e32 v1, vcc, 0, v23, vcc
	global_store_dwordx4 v[0:1], v[12:15], off nt
	global_store_dwordx4 v[0:1], v[8:11], off offset:16 nt
	s_branch .LBB0_298

; #define LAS __attribute__((address_space(3)))
; template <bool GU>
; __device__ __forceinline__ void transpose_item(const float* W, int K, int N, bf16* WT, const float* gs, LAS float* scr, int item, int lane) {
;     const int nblk = N / 32, kb = item / nblk, nb = item % nblk, k0 = 64 * kb, n0 = 32 * nb;
; #pragma unroll 16
;     for (int i = 0; i < 32; ++i) { const int kk = 2 * i + (lane >> 5); float w = W[(size_t)(k0 + kk) * N + n0 + (lane & 31)]; if (gs) w *= gs[k0 + kk]; scr[kk * 33 + (lane & 31)] = w; }
; __device__ __forceinline__ void conv_weights(LAS unsigned char* lds, unsigned char* ws, const PIn& I, const int l, const int wave, const int lane, const int gw, const int NGW, const int r_lo, const int r_hi) {
;     ...
;         transpose_item<false>(I.w_pg + (size_t)l * DM * DM, DM, DM, (bf16*)(wb + W_PG), nullptr, scr, r, lane);
.LBB0_486:
	s_cmpk_gt_u32 s1, 0x67f
	s_cbranch_scc0 .LBB0_534
	s_cmpk_gt_u32 s1, 0x117f
	s_cbranch_scc0 .LBB0_497
	s_cmpk_gt_u32 s1, 0x16ff
	s_cbranch_scc0 .LBB0_494
	s_lshl_b32 s9, s1, 1
	s_cmpk_gt_u32 s1, 0x177f
	s_cbranch_scc0 .LBB0_491
	s_add_i32 s6, s9, 0x1d100
	s_and_b32 s7, s6, 0x1ffc0
	s_lshl_b32 s6, s1, 5
	s_and_b32 s6, s6, 0x3e0
	v_add_u32_e32 v64, s7, v0
	s_lshl_b32 s10, s6, 2
	v_add_u32_e32 v62, s7, v1
	v_ashrrev_i32_e32 v65, 31, v64
	v_add_u32_e32 v66, s7, v25
	v_add_u32_e32 v68, s7, v24
	v_add_u32_e32 v70, s7, v27
	v_add_u32_e32 v72, s7, v26
	v_add_u32_e32 v74, s7, v29
	v_add_u32_e32 v76, s7, v28
	v_lshl_add_u64 v[60:61], v[14:15], 0, s[10:11]
	v_ashrrev_i32_e32 v63, 31, v62
	v_lshlrev_b64 v[64:65], 12, v[64:65]
	v_ashrrev_i32_e32 v69, 31, v68
	v_ashrrev_i32_e32 v67, 31, v66
	v_ashrrev_i32_e32 v73, 31, v72
	v_ashrrev_i32_e32 v71, 31, v70
	v_ashrrev_i32_e32 v77, 31, v76
	v_ashrrev_i32_e32 v75, 31, v74
	v_lshlrev_b64 v[62:63], 12, v[62:63]
	v_lshl_add_u64 v[64:65], v[60:61], 0, v[64:65]
	v_lshlrev_b64 v[66:67], 12, v[66:67]
	v_lshlrev_b64 v[68:69], 12, v[68:69]
	v_lshlrev_b64 v[70:71], 12, v[70:71]
	v_lshlrev_b64 v[72:73], 12, v[72:73]
	v_lshlrev_b64 v[74:75], 12, v[74:75]
	v_lshlrev_b64 v[76:77], 12, v[76:77]
	v_lshl_add_u64 v[62:63], v[60:61], 0, v[62:63]
	v_lshl_add_u64 v[68:69], v[60:61], 0, v[68:69]
	v_lshl_add_u64 v[66:67], v[60:61], 0, v[66:67]
	v_lshl_add_u64 v[72:73], v[60:61], 0, v[72:73]
	v_lshl_add_u64 v[70:71], v[60:61], 0, v[70:71]
	v_lshl_add_u64 v[76:77], v[60:61], 0, v[76:77]
	v_lshl_add_u64 v[74:75], v[60:61], 0, v[74:75]
	global_load_dword v78, v[64:65], off nt
	global_load_dword v79, v[62:63], off nt
	global_load_dword v80, v[68:69], off nt
	global_load_dword v81, v[66:67], off nt
	global_load_dword v82, v[72:73], off nt
	global_load_dword v83, v[70:71], off nt
	global_load_dword v84, v[76:77], off nt
	global_load_dword v85, v[74:75], off nt
	v_add_u32_e32 v64, s7, v30
	v_add_u32_e32 v62, s7, v31
	v_ashrrev_i32_e32 v65, 31, v64
	v_add_u32_e32 v66, s7, v33
	v_add_u32_e32 v68, s7, v32
	v_add_u32_e32 v70, s7, v35
	v_add_u32_e32 v72, s7, v34
	v_add_u32_e32 v74, s7, v37
	v_add_u32_e32 v76, s7, v36
	v_ashrrev_i32_e32 v63, 31, v62
	v_lshlrev_b64 v[64:65], 12, v[64:65]
	v_ashrrev_i32_e32 v69, 31, v68
	v_ashrrev_i32_e32 v67, 31, v66
	v_ashrrev_i32_e32 v73, 31, v72
	v_ashrrev_i32_e32 v71, 31, v70
	v_ashrrev_i32_e32 v77, 31, v76
	v_ashrrev_i32_e32 v75, 31, v74
	v_lshlrev_b64 v[62:63], 12, v[62:63]
	v_lshl_add_u64 v[64:65], v[60:61], 0, v[64:65]
	v_lshlrev_b64 v[66:67], 12, v[66:67]
	v_lshlrev_b64 v[68:69], 12, v[68:69]
	v_lshlrev_b64 v[70:71], 12, v[70:71]
	v_lshlrev_b64 v[72:73], 12, v[72:73]
	v_lshlrev_b64 v[74:75], 12, v[74:75]
	v_lshlrev_b64 v[76:77], 12, v[76:77]
	v_lshl_add_u64 v[62:63], v[60:61], 0, v[62:63]
	v_lshl_add_u64 v[68:69], v[60:61], 0, v[68:69]
	v_lshl_add_u64 v[66:67], v[60:61], 0, v[66:67]
	v_lshl_add_u64 v[72:73], v[60:61], 0, v[72:73]
	v_lshl_add_u64 v[70:71], v[60:61], 0, v[70:71]
	v_lshl_add_u64 v[76:77], v[60:61], 0, v[76:77]
	v_lshl_add_u64 v[74:75], v[60:61], 0, v[74:75]
	global_load_dword v86, v[64:65], off nt
	global_load_dword v87, v[62:63], off nt
	global_load_dword v88, v[68:69], off nt
	global_load_dword v89, v[66:67], off nt
	global_load_dword v90, v[72:73], off nt
	global_load_dword v91, v[70:71], off nt
	global_load_dword v92, v[76:77], off nt
	global_load_dword v93, v[74:75], off nt
	v_add_u32_e32 v64, s7, v38
	v_add_u32_e32 v66, s7, v41
	v_add_u32_e32 v68, s7, v40
	v_add_u32_e32 v74, s7, v45
	v_add_u32_e32 v76, s7, v44
	v_add_u32_e32 v62, s7, v39
	v_ashrrev_i32_e32 v65, 31, v64
	v_ashrrev_i32_e32 v69, 31, v68
	v_ashrrev_i32_e32 v67, 31, v66
	v_add_u32_e32 v70, s7, v43
	v_add_u32_e32 v72, s7, v42
	v_ashrrev_i32_e32 v77, 31, v76
	v_ashrrev_i32_e32 v75, 31, v74
	v_ashrrev_i32_e32 v63, 31, v62
	v_lshlrev_b64 v[64:65], 12, v[64:65]
	v_lshlrev_b64 v[66:67], 12, v[66:67]
	v_lshlrev_b64 v[68:69], 12, v[68:69]
	v_ashrrev_i32_e32 v73, 31, v72
	v_ashrrev_i32_e32 v71, 31, v70
	v_lshlrev_b64 v[74:75], 12, v[74:75]
	v_lshlrev_b64 v[76:77], 12, v[76:77]
	v_lshlrev_b64 v[62:63], 12, v[62:63]
	v_lshl_add_u64 v[64:65], v[60:61], 0, v[64:65]
	v_lshl_add_u64 v[68:69], v[60:61], 0, v[68:69]
	v_lshl_add_u64 v[66:67], v[60:61], 0, v[66:67]
	v_lshlrev_b64 v[70:71], 12, v[70:71]
	v_lshlrev_b64 v[72:73], 12, v[72:73]
	v_lshl_add_u64 v[76:77], v[60:61], 0, v[76:77]
	v_lshl_add_u64 v[74:75], v[60:61], 0, v[74:75]
	v_lshl_add_u64 v[62:63], v[60:61], 0, v[62:63]
	v_lshl_add_u64 v[72:73], v[60:61], 0, v[72:73]
	v_lshl_add_u64 v[70:71], v[60:61], 0, v[70:71]
	global_load_dword v94, v[64:65], off nt
	global_load_dword v95, v[62:63], off nt
	global_load_dword v96, v[68:69], off nt
	global_load_dword v97, v[66:67], off nt
	global_load_dword v137, v[72:73], off nt
	global_load_dword v138, v[70:71], off nt
	s_nop 0
	global_load_dword v76, v[76:77], off nt
	s_nop 0
	global_load_dword v74, v[74:75], off nt
	v_add_u32_e32 v64, s7, v46
	v_add_u32_e32 v66, s7, v49
	v_add_u32_e32 v68, s7, v48
	v_add_u32_e32 v62, s7, v47
	v_ashrrev_i32_e32 v65, 31, v64
	v_ashrrev_i32_e32 v69, 31, v68
	v_ashrrev_i32_e32 v67, 31, v66
	v_add_u32_e32 v70, s7, v51
	v_add_u32_e32 v72, s7, v50
	v_ashrrev_i32_e32 v63, 31, v62
	v_lshlrev_b64 v[64:65], 12, v[64:65]
	v_lshlrev_b64 v[66:67], 12, v[66:67]
	v_lshlrev_b64 v[68:69], 12, v[68:69]
	v_ashrrev_i32_e32 v73, 31, v72
	v_ashrrev_i32_e32 v71, 31, v70
	v_lshlrev_b64 v[62:63], 12, v[62:63]
	v_lshl_add_u64 v[64:65], v[60:61], 0, v[64:65]
	v_lshl_add_u64 v[68:69], v[60:61], 0, v[68:69]
	v_lshl_add_u64 v[66:67], v[60:61], 0, v[66:67]
	v_lshlrev_b64 v[70:71], 12, v[70:71]
	v_lshlrev_b64 v[72:73], 12, v[72:73]
	v_lshl_add_u64 v[62:63], v[60:61], 0, v[62:63]
	v_lshl_add_u64 v[72:73], v[60:61], 0, v[72:73]
	v_lshl_add_u64 v[70:71], v[60:61], 0, v[70:71]
	global_load_dword v75, v[64:65], off nt
	global_load_dword v77, v[62:63], off nt
	s_nop 0
	global_load_dword v68, v[68:69], off nt
	s_nop 0
	global_load_dword v66, v[66:67], off nt
	s_nop 0
	global_load_dword v67, v[72:73], off nt
	global_load_dword v69, v[70:71], off nt
	v_add_u32_e32 v64, s7, v52
	v_add_u32_e32 v62, s7, v53
	v_ashrrev_i32_e32 v65, 31, v64
	v_ashrrev_i32_e32 v63, 31, v62
	v_lshlrev_b64 v[64:65], 12, v[64:65]
	v_lshlrev_b64 v[62:63], 12, v[62:63]
	v_lshl_add_u64 v[64:65], v[60:61], 0, v[64:65]
	global_load_dword v64, v[64:65], off nt
	v_lshl_add_u64 v[60:61], v[60:61], 0, v[62:63]
	global_load_dword v60, v[60:61], off nt
	v_add_u32_e32 v61, v98, v104
	s_waitcnt vmcnt(31)
; #define LAS __attribute__((address_space(3)))
; __device__ __forceinline__ unsigned cvt_pk(float lo, float hi) { unsigned r; asm("v_cvt_pk_bf16_f32 %0, %1, %2" : "=v"(r) : "v"(lo), "v"(hi)); return r; }
; template <bool GU>
; __device__ __forceinline__ void transpose_item(const float* W, int K, int N, bf16* WT, const float* gs, LAS float* scr, int item, int lane) {
;     ...
;     for (int i = 0; i < 32; ++i) { const int kk = 2 * i + (lane >> 5); float w = W[(size_t)(k0 + kk) * N + n0 + (lane & 31)]; if (gs) w *= gs[k0 + kk]; scr[kk * 33 + (lane & 31)] = w; }
;     asm volatile("s_waitcnt lgkmcnt(0)" ::: "memory");
;     int d0 = n0;
;     if (GU) { const int f = (n0 < FF) ? n0 : n0 - FF; d0 = 256 * (f >> 7) + (f & 127) + ((n0 < FF) ? 0 : 128); }
;     const int c = lane & 7;
; #pragma unroll
;     for (int j = 0; j < 4; ++j) { const int n = (lane >> 3) + 8 * j; const LAS float* s = scr + (8 * c) * 33 + n;
;         v4u o; o.x = cvt_pk(s[0 * 33], s[1 * 33]); o.y = cvt_pk(s[2 * 33], s[3 * 33]); o.z = cvt_pk(s[4 * 33], s[5 * 33]); o.w = cvt_pk(s[6 * 33], s[7 * 33]);
;         *(v4u*)(WT + (size_t)(d0 + n) * K + k0 + 8 * c) = o; }
;     asm volatile("s_waitcnt lgkmcnt(0)" ::: "memory");
	ds_write_b32 v61, v78
	v_add_u32_e32 v61, v98, v105
	s_waitcnt vmcnt(30)
	ds_write_b32 v61, v79
	v_add_u32_e32 v61, v98, v106
	s_waitcnt vmcnt(29)
	ds_write_b32 v61, v80
	v_add_u32_e32 v61, v98, v107
	s_waitcnt vmcnt(28)
	ds_write_b32 v61, v81
	v_add_u32_e32 v61, v98, v108
	s_waitcnt vmcnt(27)
	ds_write_b32 v61, v82
	v_add_u32_e32 v61, v98, v109
	s_waitcnt vmcnt(26)
	ds_write_b32 v61, v83
	v_add_u32_e32 v61, v98, v110
	s_waitcnt vmcnt(25)
	ds_write_b32 v61, v84
	v_add_u32_e32 v61, v98, v111
	s_waitcnt vmcnt(24)
	ds_write_b32 v61, v85
	v_add_u32_e32 v61, v98, v112
	s_waitcnt vmcnt(23)
	ds_write_b32 v61, v86
	v_add_u32_e32 v61, v98, v113
	s_waitcnt vmcnt(22)
	ds_write_b32 v61, v87
	v_add_u32_e32 v61, v98, v114
	s_waitcnt vmcnt(21)
	ds_write_b32 v61, v88
	v_add_u32_e32 v61, v98, v115
	s_waitcnt vmcnt(20)
	ds_write_b32 v61, v89
	v_add_u32_e32 v61, v98, v116
	s_waitcnt vmcnt(19)
	ds_write_b32 v61, v90
	v_add_u32_e32 v61, v98, v117
	s_waitcnt vmcnt(18)
	ds_write_b32 v61, v91
	v_add_u32_e32 v61, v98, v118
	s_waitcnt vmcnt(17)
	ds_write_b32 v61, v92
	v_add_u32_e32 v61, v98, v119
	s_waitcnt vmcnt(16)
	ds_write_b32 v61, v93
	v_add_u32_e32 v61, v98, v120
	v_add_u32_e32 v82, s6, v99
	s_lshl_b32 s10, s7, 1
	v_ashrrev_i32_e32 v83, 31, v82
	v_lshl_add_u64 v[80:81], v[2:3], 0, s[10:11]
	s_waitcnt vmcnt(15)
	ds_write_b32 v61, v94
	v_add_u32_e32 v61, v98, v121
	s_waitcnt vmcnt(14)
	ds_write_b32 v61, v95
	v_add_u32_e32 v61, v98, v122
	s_waitcnt vmcnt(13)
	ds_write_b32 v61, v96
	v_add_u32_e32 v61, v98, v123
	s_waitcnt vmcnt(12)
	ds_write_b32 v61, v97
	v_add_u32_e32 v61, v98, v124
	s_waitcnt vmcnt(11)
	ds_write_b32 v61, v137
	v_add_u32_e32 v61, v98, v125
	s_waitcnt vmcnt(10)
	ds_write_b32 v61, v138
	v_add_u32_e32 v61, v98, v126
	s_waitcnt vmcnt(9)
	ds_write_b32 v61, v76
	v_add_u32_e32 v61, v98, v127
	s_waitcnt vmcnt(8)
	ds_write_b32 v61, v74
	v_add_u32_e32 v61, v98, v128
	v_lshlrev_b64 v[82:83], 11, v[82:83]
	v_lshl_add_u64 v[82:83], v[80:81], 0, v[82:83]
	s_waitcnt vmcnt(7)
	ds_write_b32 v61, v75
	v_add_u32_e32 v61, v98, v129
	s_waitcnt vmcnt(6)
	ds_write_b32 v61, v77
	v_add_u32_e32 v61, v98, v130
	s_waitcnt vmcnt(5)
	ds_write_b32 v61, v68
	v_add_u32_e32 v61, v98, v131
	s_waitcnt vmcnt(4)
	ds_write_b32 v61, v66
	v_add_u32_e32 v61, v98, v132
	s_waitcnt vmcnt(3)
	ds_write_b32 v61, v67
	v_add_u32_e32 v61, v98, v133
	s_waitcnt vmcnt(2)
	ds_write_b32 v61, v69
	v_add_u32_e32 v61, v98, v134
	s_waitcnt vmcnt(1)
	ds_write_b32 v61, v64
	v_add_u32_e32 v61, v98, v135
	s_waitcnt vmcnt(0)
	ds_write_b32 v61, v60
	s_waitcnt lgkmcnt(0)
	ds_read2_b32 v[64:65], v100 offset0:33 offset1:41
	ds_read2_b32 v[66:67], v100 offset1:8
	ds_read2_b32 v[68:69], v100 offset0:66 offset1:74
	ds_read2_b32 v[70:71], v100 offset0:99 offset1:107
	ds_read2_b32 v[72:73], v100 offset0:132 offset1:140
	ds_read2_b32 v[74:75], v100 offset0:165 offset1:173
	ds_read2_b32 v[76:77], v100 offset0:198 offset1:206
	ds_read2_b32 v[78:79], v100 offset0:231 offset1:239
	s_waitcnt lgkmcnt(6)
	v_cvt_pk_bf16_f32 v60, v66, v64
	v_add_u32_e32 v64, s6, v101
	s_waitcnt lgkmcnt(4)
	v_cvt_pk_bf16_f32 v61, v68, v70
	s_waitcnt lgkmcnt(2)
	v_cvt_pk_bf16_f32 v62, v72, v74
	s_waitcnt lgkmcnt(0)
	v_cvt_pk_bf16_f32 v63, v76, v78
	global_store_dwordx4 v[82:83], v[60:63], off
	s_nop 1
	v_cvt_pk_bf16_f32 v60, v67, v65
	v_ashrrev_i32_e32 v65, 31, v64
	v_lshlrev_b64 v[64:65], 11, v[64:65]
	v_cvt_pk_bf16_f32 v61, v69, v71
	v_cvt_pk_bf16_f32 v62, v73, v75
	v_cvt_pk_bf16_f32 v63, v77, v79
	v_lshl_add_u64 v[64:65], v[80:81], 0, v[64:65]
	ds_read2_b32 v[66:67], v100 offset0:16 offset1:24
	ds_read2_b32 v[68:69], v100 offset0:49 offset1:57
	ds_read2_b32 v[70:71], v100 offset0:82 offset1:90
	ds_read2_b32 v[72:73], v100 offset0:115 offset1:123
	ds_read2_b32 v[74:75], v100 offset0:148 offset1:156
	ds_read2_b32 v[76:77], v100 offset0:181 offset1:189
	ds_read2_b32 v[78:79], v100 offset0:214 offset1:222
	ds_read2_b32 v[82:83], v100 offset0:247 offset1:255
	global_store_dwordx4 v[64:65], v[60:63], off
	v_add_u32_e32 v64, s6, v102
	v_ashrrev_i32_e32 v65, 31, v64
	v_lshlrev_b64 v[64:65], 11, v[64:65]
	v_lshl_add_u64 v[64:65], v[80:81], 0, v[64:65]
	s_waitcnt lgkmcnt(6)
	v_cvt_pk_bf16_f32 v60, v66, v68
	s_waitcnt lgkmcnt(4)
	v_cvt_pk_bf16_f32 v61, v70, v72
	s_waitcnt lgkmcnt(2)
	v_cvt_pk_bf16_f32 v62, v74, v76
	s_waitcnt lgkmcnt(0)
	v_cvt_pk_bf16_f32 v63, v78, v82
	global_store_dwordx4 v[64:65], v[60:63], off
	v_add_u32_e32 v64, s6, v103
	v_ashrrev_i32_e32 v65, 31, v64
	v_lshlrev_b64 v[64:65], 11, v[64:65]
	v_lshl_add_u64 v[64:65], v[80:81], 0, v[64:65]
	v_cvt_pk_bf16_f32 v60, v67, v69
	v_cvt_pk_bf16_f32 v61, v71, v73
	v_cvt_pk_bf16_f32 v62, v75, v77
	v_cvt_pk_bf16_f32 v63, v79, v83
	global_store_dwordx4 v[64:65], v[60:63], off
	s_waitcnt lgkmcnt(0)
	s_mov_b64 s[6:7], 0
; #define LAS __attribute__((address_space(3)))
; template <bool GU>
; __device__ __forceinline__ void transpose_item(const float* W, int K, int N, bf16* WT, const float* gs, LAS float* scr, int item, int lane) {
;     const int nblk = N / 32, kb = item / nblk, nb = item % nblk, k0 = 64 * kb, n0 = 32 * nb;
; #pragma unroll 16
;     for (int i = 0; i < 32; ++i) { const int kk = 2 * i + (lane >> 5); float w = W[(size_t)(k0 + kk) * N + n0 + (lane & 31)]; if (gs) w *= gs[k0 + kk]; scr[kk * 33 + (lane & 31)] = w; }
; __device__ __forceinline__ void conv_weights(LAS unsigned char* lds, unsigned char* ws, const PIn& I, const int l, const int wave, const int lane, const int gw, const int NGW, const int r_lo, const int r_hi) {
;     ...
;         if (r < I_PP) { transpose_item<false>(I.w_pp + (size_t)l * DPLE * DM, DPLE, DM, (bf16*)(wb + W_PP), nullptr, scr, r, lane); continue; } r -= I_PP;
.LBB0_491:
	s_andn2_b64 vcc, exec, s[6:7]
	s_cbranch_vccnz .LBB0_493
	s_and_b32 s7, s9, 0x1c0
	s_lshl_b32 s6, s1, 5
	s_and_b32 s6, s6, 0x3e0
	v_add_u32_e32 v64, s7, v0
	s_lshl_b32 s10, s6, 2
	v_add_u32_e32 v62, s7, v1
	v_ashrrev_i32_e32 v65, 31, v64
	v_add_u32_e32 v66, s7, v25
	v_add_u32_e32 v68, s7, v24
	v_add_u32_e32 v70, s7, v27
	v_add_u32_e32 v72, s7, v26
	v_add_u32_e32 v74, s7, v29
	v_add_u32_e32 v76, s7, v28
	v_lshl_add_u64 v[60:61], v[16:17], 0, s[10:11]
	v_ashrrev_i32_e32 v63, 31, v62
	v_lshlrev_b64 v[64:65], 12, v[64:65]
	v_ashrrev_i32_e32 v69, 31, v68
	v_ashrrev_i32_e32 v67, 31, v66
	v_ashrrev_i32_e32 v73, 31, v72
	v_ashrrev_i32_e32 v71, 31, v70
	v_ashrrev_i32_e32 v77, 31, v76
	v_ashrrev_i32_e32 v75, 31, v74
	v_lshlrev_b64 v[62:63], 12, v[62:63]
	v_lshl_add_u64 v[64:65], v[60:61], 0, v[64:65]
	v_lshlrev_b64 v[66:67], 12, v[66:67]
	v_lshlrev_b64 v[68:69], 12, v[68:69]
	v_lshlrev_b64 v[70:71], 12, v[70:71]
	v_lshlrev_b64 v[72:73], 12, v[72:73]
	v_lshlrev_b64 v[74:75], 12, v[74:75]
	v_lshlrev_b64 v[76:77], 12, v[76:77]
	v_lshl_add_u64 v[62:63], v[60:61], 0, v[62:63]
	v_lshl_add_u64 v[68:69], v[60:61], 0, v[68:69]
	v_lshl_add_u64 v[66:67], v[60:61], 0, v[66:67]
	v_lshl_add_u64 v[72:73], v[60:61], 0, v[72:73]
	v_lshl_add_u64 v[70:71], v[60:61], 0, v[70:71]
	v_lshl_add_u64 v[76:77], v[60:61], 0, v[76:77]
	v_lshl_add_u64 v[74:75], v[60:61], 0, v[74:75]
	global_load_dword v78, v[64:65], off nt
	global_load_dword v79, v[62:63], off nt
	global_load_dword v80, v[68:69], off nt
	global_load_dword v81, v[66:67], off nt
	global_load_dword v82, v[72:73], off nt
	global_load_dword v83, v[70:71], off nt
	global_load_dword v84, v[76:77], off nt
	global_load_dword v85, v[74:75], off nt
	v_add_u32_e32 v64, s7, v30
	v_add_u32_e32 v62, s7, v31
	v_ashrrev_i32_e32 v65, 31, v64
	v_add_u32_e32 v66, s7, v33
	v_add_u32_e32 v68, s7, v32
	v_add_u32_e32 v70, s7, v35
	v_add_u32_e32 v72, s7, v34
	v_add_u32_e32 v74, s7, v37
	v_add_u32_e32 v76, s7, v36
	v_ashrrev_i32_e32 v63, 31, v62
	v_lshlrev_b64 v[64:65], 12, v[64:65]
	v_ashrrev_i32_e32 v69, 31, v68
	v_ashrrev_i32_e32 v67, 31, v66
	v_ashrrev_i32_e32 v73, 31, v72
	v_ashrrev_i32_e32 v71, 31, v70
	v_ashrrev_i32_e32 v77, 31, v76
	v_ashrrev_i32_e32 v75, 31, v74
	v_lshlrev_b64 v[62:63], 12, v[62:63]
	v_lshl_add_u64 v[64:65], v[60:61], 0, v[64:65]
	v_lshlrev_b64 v[66:67], 12, v[66:67]
	v_lshlrev_b64 v[68:69], 12, v[68:69]
	v_lshlrev_b64 v[70:71], 12, v[70:71]
	v_lshlrev_b64 v[72:73], 12, v[72:73]
	v_lshlrev_b64 v[74:75], 12, v[74:75]
	v_lshlrev_b64 v[76:77], 12, v[76:77]
	v_lshl_add_u64 v[62:63], v[60:61], 0, v[62:63]
	v_lshl_add_u64 v[68:69], v[60:61], 0, v[68:69]
	v_lshl_add_u64 v[66:67], v[60:61], 0, v[66:67]
	v_lshl_add_u64 v[72:73], v[60:61], 0, v[72:73]
	v_lshl_add_u64 v[70:71], v[60:61], 0, v[70:71]
	v_lshl_add_u64 v[76:77], v[60:61], 0, v[76:77]
	v_lshl_add_u64 v[74:75], v[60:61], 0, v[74:75]
	global_load_dword v86, v[64:65], off nt
	global_load_dword v87, v[62:63], off nt
	global_load_dword v88, v[68:69], off nt
	global_load_dword v89, v[66:67], off nt
	global_load_dword v90, v[72:73], off nt
	global_load_dword v91, v[70:71], off nt
	global_load_dword v92, v[76:77], off nt
	global_load_dword v93, v[74:75], off nt
	v_add_u32_e32 v64, s7, v38
	v_add_u32_e32 v66, s7, v41
	v_add_u32_e32 v68, s7, v40
	v_add_u32_e32 v74, s7, v45
	v_add_u32_e32 v76, s7, v44
	v_add_u32_e32 v62, s7, v39
	v_ashrrev_i32_e32 v65, 31, v64
	v_ashrrev_i32_e32 v69, 31, v68
	v_ashrrev_i32_e32 v67, 31, v66
	v_add_u32_e32 v70, s7, v43
	v_add_u32_e32 v72, s7, v42
	v_ashrrev_i32_e32 v77, 31, v76
	v_ashrrev_i32_e32 v75, 31, v74
	v_ashrrev_i32_e32 v63, 31, v62
	v_lshlrev_b64 v[64:65], 12, v[64:65]
	v_lshlrev_b64 v[66:67], 12, v[66:67]
	v_lshlrev_b64 v[68:69], 12, v[68:69]
	v_ashrrev_i32_e32 v73, 31, v72
	v_ashrrev_i32_e32 v71, 31, v70
	v_lshlrev_b64 v[74:75], 12, v[74:75]
	v_lshlrev_b64 v[76:77], 12, v[76:77]
	v_lshlrev_b64 v[62:63], 12, v[62:63]
	v_lshl_add_u64 v[64:65], v[60:61], 0, v[64:65]
	v_lshl_add_u64 v[68:69], v[60:61], 0, v[68:69]
	v_lshl_add_u64 v[66:67], v[60:61], 0, v[66:67]
	v_lshlrev_b64 v[70:71], 12, v[70:71]
	v_lshlrev_b64 v[72:73], 12, v[72:73]
	v_lshl_add_u64 v[76:77], v[60:61], 0, v[76:77]
	v_lshl_add_u64 v[74:75], v[60:61], 0, v[74:75]
	v_lshl_add_u64 v[62:63], v[60:61], 0, v[62:63]
	v_lshl_add_u64 v[72:73], v[60:61], 0, v[72:73]
	v_lshl_add_u64 v[70:71], v[60:61], 0, v[70:71]
	global_load_dword v94, v[64:65], off nt
	global_load_dword v95, v[62:63], off nt
	global_load_dword v96, v[68:69], off nt
	global_load_dword v97, v[66:67], off nt
	global_load_dword v137, v[72:73], off nt
	global_load_dword v138, v[70:71], off nt
	s_nop 0
	global_load_dword v76, v[76:77], off nt
	s_nop 0
	global_load_dword v74, v[74:75], off nt
	v_add_u32_e32 v64, s7, v46
	v_add_u32_e32 v66, s7, v49
	v_add_u32_e32 v68, s7, v48
	v_add_u32_e32 v62, s7, v47
	v_ashrrev_i32_e32 v65, 31, v64
	v_ashrrev_i32_e32 v69, 31, v68
	v_ashrrev_i32_e32 v67, 31, v66
	v_add_u32_e32 v70, s7, v51
	v_add_u32_e32 v72, s7, v50
	v_ashrrev_i32_e32 v63, 31, v62
	v_lshlrev_b64 v[64:65], 12, v[64:65]
	v_lshlrev_b64 v[66:67], 12, v[66:67]
	v_lshlrev_b64 v[68:69], 12, v[68:69]
	v_ashrrev_i32_e32 v73, 31, v72
	v_ashrrev_i32_e32 v71, 31, v70
	v_lshlrev_b64 v[62:63], 12, v[62:63]
	v_lshl_add_u64 v[64:65], v[60:61], 0, v[64:65]
	v_lshl_add_u64 v[68:69], v[60:61], 0, v[68:69]
	v_lshl_add_u64 v[66:67], v[60:61], 0, v[66:67]
	v_lshlrev_b64 v[70:71], 12, v[70:71]
	v_lshlrev_b64 v[72:73], 12, v[72:73]
	v_lshl_add_u64 v[62:63], v[60:61], 0, v[62:63]
	v_lshl_add_u64 v[72:73], v[60:61], 0, v[72:73]
	v_lshl_add_u64 v[70:71], v[60:61], 0, v[70:71]
	global_load_dword v75, v[64:65], off nt
	global_load_dword v77, v[62:63], off nt
	s_nop 0
	global_load_dword v68, v[68:69], off nt
	s_nop 0
	global_load_dword v66, v[66:67], off nt
	s_nop 0
	global_load_dword v67, v[72:73], off nt
	global_load_dword v69, v[70:71], off nt
	v_add_u32_e32 v64, s7, v52
	v_add_u32_e32 v62, s7, v53
	v_ashrrev_i32_e32 v65, 31, v64
	v_ashrrev_i32_e32 v63, 31, v62
	v_lshlrev_b64 v[64:65], 12, v[64:65]
	v_lshlrev_b64 v[62:63], 12, v[62:63]
	v_lshl_add_u64 v[64:65], v[60:61], 0, v[64:65]
	global_load_dword v64, v[64:65], off nt
	v_lshl_add_u64 v[60:61], v[60:61], 0, v[62:63]
	global_load_dword v60, v[60:61], off nt
	v_add_u32_e32 v61, v98, v104
	s_waitcnt vmcnt(31)
; #define LAS __attribute__((address_space(3)))
; __device__ __forceinline__ unsigned cvt_pk(float lo, float hi) { unsigned r; asm("v_cvt_pk_bf16_f32 %0, %1, %2" : "=v"(r) : "v"(lo), "v"(hi)); return r; }
; template <bool GU>
; __device__ __forceinline__ void transpose_item(const float* W, int K, int N, bf16* WT, const float* gs, LAS float* scr, int item, int lane) {
;     ...
;     for (int i = 0; i < 32; ++i) { const int kk = 2 * i + (lane >> 5); float w = W[(size_t)(k0 + kk) * N + n0 + (lane & 31)]; if (gs) w *= gs[k0 + kk]; scr[kk * 33 + (lane & 31)] = w; }
;     asm volatile("s_waitcnt lgkmcnt(0)" ::: "memory");
;     int d0 = n0;
;     if (GU) { const int f = (n0 < FF) ? n0 : n0 - FF; d0 = 256 * (f >> 7) + (f & 127) + ((n0 < FF) ? 0 : 128); }
;     const int c = lane & 7;
; #pragma unroll
;     for (int j = 0; j < 4; ++j) { const int n = (lane >> 3) + 8 * j; const LAS float* s = scr + (8 * c) * 33 + n;
;         v4u o; o.x = cvt_pk(s[0 * 33], s[1 * 33]); o.y = cvt_pk(s[2 * 33], s[3 * 33]); o.z = cvt_pk(s[4 * 33], s[5 * 33]); o.w = cvt_pk(s[6 * 33], s[7 * 33]);
;         *(v4u*)(WT + (size_t)(d0 + n) * K + k0 + 8 * c) = o; }
;     asm volatile("s_waitcnt lgkmcnt(0)" ::: "memory");
	ds_write_b32 v61, v78
	v_add_u32_e32 v61, v98, v105
	s_waitcnt vmcnt(30)
	ds_write_b32 v61, v79
	v_add_u32_e32 v61, v98, v106
	s_waitcnt vmcnt(29)
	ds_write_b32 v61, v80
	v_add_u32_e32 v61, v98, v107
	s_waitcnt vmcnt(28)
	ds_write_b32 v61, v81
	v_add_u32_e32 v61, v98, v108
	s_waitcnt vmcnt(27)
	ds_write_b32 v61, v82
	v_add_u32_e32 v61, v98, v109
	s_waitcnt vmcnt(26)
	ds_write_b32 v61, v83
	v_add_u32_e32 v61, v98, v110
	s_waitcnt vmcnt(25)
	ds_write_b32 v61, v84
	v_add_u32_e32 v61, v98, v111
	s_waitcnt vmcnt(24)
	ds_write_b32 v61, v85
	v_add_u32_e32 v61, v98, v112
	s_waitcnt vmcnt(23)
	ds_write_b32 v61, v86
	v_add_u32_e32 v61, v98, v113
	s_waitcnt vmcnt(22)
	ds_write_b32 v61, v87
	v_add_u32_e32 v61, v98, v114
	s_waitcnt vmcnt(21)
	ds_write_b32 v61, v88
	v_add_u32_e32 v61, v98, v115
	s_waitcnt vmcnt(20)
	ds_write_b32 v61, v89
	v_add_u32_e32 v61, v98, v116
	s_waitcnt vmcnt(19)
	ds_write_b32 v61, v90
	v_add_u32_e32 v61, v98, v117
	s_waitcnt vmcnt(18)
	ds_write_b32 v61, v91
	v_add_u32_e32 v61, v98, v118
	s_waitcnt vmcnt(17)
	ds_write_b32 v61, v92
	v_add_u32_e32 v61, v98, v119
	s_waitcnt vmcnt(16)
	ds_write_b32 v61, v93
	v_add_u32_e32 v61, v98, v120
	v_add_u32_e32 v82, s6, v99
	s_lshl_b32 s10, s7, 1
	v_ashrrev_i32_e32 v83, 31, v82
	v_lshl_add_u64 v[80:81], v[4:5], 0, s[10:11]
	s_waitcnt vmcnt(15)
	ds_write_b32 v61, v94
	v_add_u32_e32 v61, v98, v121
	s_waitcnt vmcnt(14)
	ds_write_b32 v61, v95
	v_add_u32_e32 v61, v98, v122
	s_waitcnt vmcnt(13)
	ds_write_b32 v61, v96
	v_add_u32_e32 v61, v98, v123
	s_waitcnt vmcnt(12)
	ds_write_b32 v61, v97
	v_add_u32_e32 v61, v98, v124
	s_waitcnt vmcnt(11)
	ds_write_b32 v61, v137
	v_add_u32_e32 v61, v98, v125
	s_waitcnt vmcnt(10)
	ds_write_b32 v61, v138
	v_add_u32_e32 v61, v98, v126
	s_waitcnt vmcnt(9)
	ds_write_b32 v61, v76
	v_add_u32_e32 v61, v98, v127
	s_waitcnt vmcnt(8)
	ds_write_b32 v61, v74
	v_add_u32_e32 v61, v98, v128
	v_lshlrev_b64 v[82:83], 9, v[82:83]
	v_lshl_add_u64 v[82:83], v[80:81], 0, v[82:83]
	s_waitcnt vmcnt(7)
	ds_write_b32 v61, v75
	v_add_u32_e32 v61, v98, v129
	s_waitcnt vmcnt(6)
	ds_write_b32 v61, v77
	v_add_u32_e32 v61, v98, v130
	s_waitcnt vmcnt(5)
	ds_write_b32 v61, v68
	v_add_u32_e32 v61, v98, v131
	s_waitcnt vmcnt(4)
	ds_write_b32 v61, v66
	v_add_u32_e32 v61, v98, v132
	s_waitcnt vmcnt(3)
	ds_write_b32 v61, v67
	v_add_u32_e32 v61, v98, v133
	s_waitcnt vmcnt(2)
	ds_write_b32 v61, v69
	v_add_u32_e32 v61, v98, v134
	s_waitcnt vmcnt(1)
	ds_write_b32 v61, v64
	v_add_u32_e32 v61, v98, v135
	s_waitcnt vmcnt(0)
	ds_write_b32 v61, v60
	s_waitcnt lgkmcnt(0)
	ds_read2_b32 v[64:65], v100 offset0:33 offset1:41
	ds_read2_b32 v[66:67], v100 offset1:8
	ds_read2_b32 v[68:69], v100 offset0:66 offset1:74
	ds_read2_b32 v[70:71], v100 offset0:99 offset1:107
	ds_read2_b32 v[72:73], v100 offset0:132 offset1:140
	ds_read2_b32 v[74:75], v100 offset0:165 offset1:173
	ds_read2_b32 v[76:77], v100 offset0:198 offset1:206
	ds_read2_b32 v[78:79], v100 offset0:231 offset1:239
	s_waitcnt lgkmcnt(6)
	v_cvt_pk_bf16_f32 v60, v66, v64
	v_add_u32_e32 v64, s6, v101
	s_waitcnt lgkmcnt(4)
	v_cvt_pk_bf16_f32 v61, v68, v70
	s_waitcnt lgkmcnt(2)
	v_cvt_pk_bf16_f32 v62, v72, v74
	s_waitcnt lgkmcnt(0)
	v_cvt_pk_bf16_f32 v63, v76, v78
	global_store_dwordx4 v[82:83], v[60:63], off
	s_nop 1
	v_cvt_pk_bf16_f32 v60, v67, v65
	v_ashrrev_i32_e32 v65, 31, v64
	v_lshlrev_b64 v[64:65], 9, v[64:65]
	v_cvt_pk_bf16_f32 v61, v69, v71
	v_cvt_pk_bf16_f32 v62, v73, v75
	v_cvt_pk_bf16_f32 v63, v77, v79
	v_lshl_add_u64 v[64:65], v[80:81], 0, v[64:65]
	ds_read2_b32 v[66:67], v100 offset0:16 offset1:24
	ds_read2_b32 v[68:69], v100 offset0:49 offset1:57
	ds_read2_b32 v[70:71], v100 offset0:82 offset1:90
	ds_read2_b32 v[72:73], v100 offset0:115 offset1:123
	ds_read2_b32 v[74:75], v100 offset0:148 offset1:156
	ds_read2_b32 v[76:77], v100 offset0:181 offset1:189
	ds_read2_b32 v[78:79], v100 offset0:214 offset1:222
	ds_read2_b32 v[82:83], v100 offset0:247 offset1:255
	global_store_dwordx4 v[64:65], v[60:63], off
	v_add_u32_e32 v64, s6, v102
	v_ashrrev_i32_e32 v65, 31, v64
	v_lshlrev_b64 v[64:65], 9, v[64:65]
	v_lshl_add_u64 v[64:65], v[80:81], 0, v[64:65]
	s_waitcnt lgkmcnt(6)
	v_cvt_pk_bf16_f32 v60, v66, v68
	s_waitcnt lgkmcnt(4)
	v_cvt_pk_bf16_f32 v61, v70, v72
	s_waitcnt lgkmcnt(2)
	v_cvt_pk_bf16_f32 v62, v74, v76
	s_waitcnt lgkmcnt(0)
	v_cvt_pk_bf16_f32 v63, v78, v82
	global_store_dwordx4 v[64:65], v[60:63], off
	v_add_u32_e32 v64, s6, v103
	v_ashrrev_i32_e32 v65, 31, v64
	v_lshlrev_b64 v[64:65], 9, v[64:65]
	v_lshl_add_u64 v[64:65], v[80:81], 0, v[64:65]
	v_cvt_pk_bf16_f32 v60, v67, v69
	v_cvt_pk_bf16_f32 v61, v71, v73
	v_cvt_pk_bf16_f32 v62, v75, v77
	v_cvt_pk_bf16_f32 v63, v79, v83
	global_store_dwordx4 v[64:65], v[60:63], off
	s_waitcnt lgkmcnt(0)

; #define LAS __attribute__((address_space(3)))
; template <bool GU>
; __device__ __forceinline__ void transpose_item(const float* W, int K, int N, bf16* WT, const float* gs, LAS float* scr, int item, int lane) {
;     const int nblk = N / 32, kb = item / nblk, nb = item % nblk, k0 = 64 * kb, n0 = 32 * nb;
; #pragma unroll 16
;     for (int i = 0; i < 32; ++i) { const int kk = 2 * i + (lane >> 5); float w = W[(size_t)(k0 + kk) * N + n0 + (lane & 31)]; if (gs) w *= gs[k0 + kk]; scr[kk * 33 + (lane & 31)] = w; }
; __device__ __forceinline__ void conv_weights(LAS unsigned char* lds, unsigned char* ws, const PIn& I, const int l, const int wave, const int lane, const int gw, const int NGW, const int r_lo, const int r_hi) {
;     ...
;         if (r < I_D) { transpose_item<false>(I.w_d + (size_t)l * FF * DM, FF, DM, (bf16*)(wb + W_D), nullptr, scr, r, lane); continue; } r -= I_D;
.LBB0_494:
	s_andn2_b64 vcc, exec, s[6:7]
	s_cbranch_vccnz .LBB0_496
	s_lshl_b32 s6, s1, 1
	s_add_i32 s6, s6, 0x1dd00
	s_and_b32 s7, s6, 0x1ffc0
	s_lshl_b32 s6, s1, 5
	s_and_b32 s6, s6, 0x3e0
	v_add_u32_e32 v64, s7, v0
	s_lshl_b32 s10, s6, 2
	v_add_u32_e32 v62, s7, v1
	v_ashrrev_i32_e32 v65, 31, v64
	v_add_u32_e32 v66, s7, v25
	v_add_u32_e32 v68, s7, v24
	v_add_u32_e32 v70, s7, v27
	v_add_u32_e32 v72, s7, v26
	v_add_u32_e32 v74, s7, v29
	v_add_u32_e32 v76, s7, v28
	v_lshl_add_u64 v[60:61], v[18:19], 0, s[10:11]
	v_ashrrev_i32_e32 v63, 31, v62
	v_lshlrev_b64 v[64:65], 12, v[64:65]
	v_ashrrev_i32_e32 v69, 31, v68
	v_ashrrev_i32_e32 v67, 31, v66
	v_ashrrev_i32_e32 v73, 31, v72
	v_ashrrev_i32_e32 v71, 31, v70
	v_ashrrev_i32_e32 v77, 31, v76
	v_ashrrev_i32_e32 v75, 31, v74
	v_lshlrev_b64 v[62:63], 12, v[62:63]
	v_lshl_add_u64 v[64:65], v[60:61], 0, v[64:65]
	v_lshlrev_b64 v[66:67], 12, v[66:67]
	v_lshlrev_b64 v[68:69], 12, v[68:69]
	v_lshlrev_b64 v[70:71], 12, v[70:71]
	v_lshlrev_b64 v[72:73], 12, v[72:73]
	v_lshlrev_b64 v[74:75], 12, v[74:75]
	v_lshlrev_b64 v[76:77], 12, v[76:77]
	v_lshl_add_u64 v[62:63], v[60:61], 0, v[62:63]
	v_lshl_add_u64 v[68:69], v[60:61], 0, v[68:69]
	v_lshl_add_u64 v[66:67], v[60:61], 0, v[66:67]
	v_lshl_add_u64 v[72:73], v[60:61], 0, v[72:73]
	v_lshl_add_u64 v[70:71], v[60:61], 0, v[70:71]
	v_lshl_add_u64 v[76:77], v[60:61], 0, v[76:77]
	v_lshl_add_u64 v[74:75], v[60:61], 0, v[74:75]
	global_load_dword v78, v[64:65], off nt
	global_load_dword v79, v[62:63], off nt
	global_load_dword v80, v[68:69], off nt
	global_load_dword v81, v[66:67], off nt
	global_load_dword v82, v[72:73], off nt
	global_load_dword v83, v[70:71], off nt
	global_load_dword v84, v[76:77], off nt
	global_load_dword v85, v[74:75], off nt
	v_add_u32_e32 v64, s7, v30
	v_add_u32_e32 v62, s7, v31
	v_ashrrev_i32_e32 v65, 31, v64
	v_add_u32_e32 v66, s7, v33
	v_add_u32_e32 v68, s7, v32
	v_add_u32_e32 v70, s7, v35
	v_add_u32_e32 v72, s7, v34
	v_add_u32_e32 v74, s7, v37
	v_add_u32_e32 v76, s7, v36
	v_ashrrev_i32_e32 v63, 31, v62
	v_lshlrev_b64 v[64:65], 12, v[64:65]
	v_ashrrev_i32_e32 v69, 31, v68
	v_ashrrev_i32_e32 v67, 31, v66
	v_ashrrev_i32_e32 v73, 31, v72
	v_ashrrev_i32_e32 v71, 31, v70
	v_ashrrev_i32_e32 v77, 31, v76
	v_ashrrev_i32_e32 v75, 31, v74
	v_lshlrev_b64 v[62:63], 12, v[62:63]
	v_lshl_add_u64 v[64:65], v[60:61], 0, v[64:65]
	v_lshlrev_b64 v[66:67], 12, v[66:67]
	v_lshlrev_b64 v[68:69], 12, v[68:69]
	v_lshlrev_b64 v[70:71], 12, v[70:71]
	v_lshlrev_b64 v[72:73], 12, v[72:73]
	v_lshlrev_b64 v[74:75], 12, v[74:75]
	v_lshlrev_b64 v[76:77], 12, v[76:77]
	v_lshl_add_u64 v[62:63], v[60:61], 0, v[62:63]
	v_lshl_add_u64 v[68:69], v[60:61], 0, v[68:69]
	v_lshl_add_u64 v[66:67], v[60:61], 0, v[66:67]
	v_lshl_add_u64 v[72:73], v[60:61], 0, v[72:73]
	v_lshl_add_u64 v[70:71], v[60:61], 0, v[70:71]
	v_lshl_add_u64 v[76:77], v[60:61], 0, v[76:77]
	v_lshl_add_u64 v[74:75], v[60:61], 0, v[74:75]
	global_load_dword v86, v[64:65], off nt
	global_load_dword v87, v[62:63], off nt
	global_load_dword v88, v[68:69], off nt
	global_load_dword v89, v[66:67], off nt
	global_load_dword v90, v[72:73], off nt
	global_load_dword v91, v[70:71], off nt
	global_load_dword v92, v[76:77], off nt
	global_load_dword v93, v[74:75], off nt
	v_add_u32_e32 v64, s7, v38
	v_add_u32_e32 v66, s7, v41
	v_add_u32_e32 v68, s7, v40
	v_add_u32_e32 v74, s7, v45
	v_add_u32_e32 v76, s7, v44
	v_add_u32_e32 v62, s7, v39
	v_ashrrev_i32_e32 v65, 31, v64
	v_ashrrev_i32_e32 v69, 31, v68
	v_ashrrev_i32_e32 v67, 31, v66
	v_add_u32_e32 v70, s7, v43
	v_add_u32_e32 v72, s7, v42
	v_ashrrev_i32_e32 v77, 31, v76
	v_ashrrev_i32_e32 v75, 31, v74
	v_ashrrev_i32_e32 v63, 31, v62
	v_lshlrev_b64 v[64:65], 12, v[64:65]
	v_lshlrev_b64 v[66:67], 12, v[66:67]
	v_lshlrev_b64 v[68:69], 12, v[68:69]
	v_ashrrev_i32_e32 v73, 31, v72
	v_ashrrev_i32_e32 v71, 31, v70
	v_lshlrev_b64 v[74:75], 12, v[74:75]
	v_lshlrev_b64 v[76:77], 12, v[76:77]
	v_lshlrev_b64 v[62:63], 12, v[62:63]
	v_lshl_add_u64 v[64:65], v[60:61], 0, v[64:65]
	v_lshl_add_u64 v[68:69], v[60:61], 0, v[68:69]
	v_lshl_add_u64 v[66:67], v[60:61], 0, v[66:67]
	v_lshlrev_b64 v[70:71], 12, v[70:71]
	v_lshlrev_b64 v[72:73], 12, v[72:73]
	v_lshl_add_u64 v[76:77], v[60:61], 0, v[76:77]
	v_lshl_add_u64 v[74:75], v[60:61], 0, v[74:75]
	v_lshl_add_u64 v[62:63], v[60:61], 0, v[62:63]
	v_lshl_add_u64 v[72:73], v[60:61], 0, v[72:73]
	v_lshl_add_u64 v[70:71], v[60:61], 0, v[70:71]
	global_load_dword v94, v[64:65], off nt
	global_load_dword v95, v[62:63], off nt
	global_load_dword v96, v[68:69], off nt
	global_load_dword v97, v[66:67], off nt
	global_load_dword v137, v[72:73], off nt
	global_load_dword v138, v[70:71], off nt
	s_nop 0
	global_load_dword v76, v[76:77], off nt
	s_nop 0
	global_load_dword v74, v[74:75], off nt
	v_add_u32_e32 v64, s7, v46
	v_add_u32_e32 v66, s7, v49
	v_add_u32_e32 v68, s7, v48
	v_add_u32_e32 v62, s7, v47
	v_ashrrev_i32_e32 v65, 31, v64
	v_ashrrev_i32_e32 v69, 31, v68
	v_ashrrev_i32_e32 v67, 31, v66
	v_add_u32_e32 v70, s7, v51
	v_add_u32_e32 v72, s7, v50
	v_ashrrev_i32_e32 v63, 31, v62
	v_lshlrev_b64 v[64:65], 12, v[64:65]
	v_lshlrev_b64 v[66:67], 12, v[66:67]
	v_lshlrev_b64 v[68:69], 12, v[68:69]
	v_ashrrev_i32_e32 v73, 31, v72
	v_ashrrev_i32_e32 v71, 31, v70
	v_lshlrev_b64 v[62:63], 12, v[62:63]
	v_lshl_add_u64 v[64:65], v[60:61], 0, v[64:65]
	v_lshl_add_u64 v[68:69], v[60:61], 0, v[68:69]
	v_lshl_add_u64 v[66:67], v[60:61], 0, v[66:67]
	v_lshlrev_b64 v[70:71], 12, v[70:71]
	v_lshlrev_b64 v[72:73], 12, v[72:73]
	v_lshl_add_u64 v[62:63], v[60:61], 0, v[62:63]
	v_lshl_add_u64 v[72:73], v[60:61], 0, v[72:73]
	v_lshl_add_u64 v[70:71], v[60:61], 0, v[70:71]
	global_load_dword v75, v[64:65], off nt
	global_load_dword v77, v[62:63], off nt
	s_nop 0
	global_load_dword v68, v[68:69], off nt
	s_nop 0
	global_load_dword v66, v[66:67], off nt
	s_nop 0
	global_load_dword v67, v[72:73], off nt
	global_load_dword v69, v[70:71], off nt
	v_add_u32_e32 v64, s7, v52
	v_add_u32_e32 v62, s7, v53
	v_ashrrev_i32_e32 v65, 31, v64
	v_ashrrev_i32_e32 v63, 31, v62
	v_lshlrev_b64 v[64:65], 12, v[64:65]
	v_lshlrev_b64 v[62:63], 12, v[62:63]
	v_lshl_add_u64 v[64:65], v[60:61], 0, v[64:65]
	global_load_dword v64, v[64:65], off nt
	v_lshl_add_u64 v[60:61], v[60:61], 0, v[62:63]
	global_load_dword v60, v[60:61], off nt
	v_add_u32_e32 v61, v98, v104
	s_waitcnt vmcnt(31)
; #define LAS __attribute__((address_space(3)))
; __device__ __forceinline__ unsigned cvt_pk(float lo, float hi) { unsigned r; asm("v_cvt_pk_bf16_f32 %0, %1, %2" : "=v"(r) : "v"(lo), "v"(hi)); return r; }
; template <bool GU>
; __device__ __forceinline__ void transpose_item(const float* W, int K, int N, bf16* WT, const float* gs, LAS float* scr, int item, int lane) {
;     ...
;     for (int i = 0; i < 32; ++i) { const int kk = 2 * i + (lane >> 5); float w = W[(size_t)(k0 + kk) * N + n0 + (lane & 31)]; if (gs) w *= gs[k0 + kk]; scr[kk * 33 + (lane & 31)] = w; }
;     asm volatile("s_waitcnt lgkmcnt(0)" ::: "memory");
;     int d0 = n0;
;     if (GU) { const int f = (n0 < FF) ? n0 : n0 - FF; d0 = 256 * (f >> 7) + (f & 127) + ((n0 < FF) ? 0 : 128); }
;     const int c = lane & 7;
; #pragma unroll
;     for (int j = 0; j < 4; ++j) { const int n = (lane >> 3) + 8 * j; const LAS float* s = scr + (8 * c) * 33 + n;
;         v4u o; o.x = cvt_pk(s[0 * 33], s[1 * 33]); o.y = cvt_pk(s[2 * 33], s[3 * 33]); o.z = cvt_pk(s[4 * 33], s[5 * 33]); o.w = cvt_pk(s[6 * 33], s[7 * 33]);
;         *(v4u*)(WT + (size_t)(d0 + n) * K + k0 + 8 * c) = o; }
;     asm volatile("s_waitcnt lgkmcnt(0)" ::: "memory");
	ds_write_b32 v61, v78
	v_add_u32_e32 v61, v98, v105
	s_waitcnt vmcnt(30)
	ds_write_b32 v61, v79
	v_add_u32_e32 v61, v98, v106
	s_waitcnt vmcnt(29)
	ds_write_b32 v61, v80
	v_add_u32_e32 v61, v98, v107
	s_waitcnt vmcnt(28)
	ds_write_b32 v61, v81
	v_add_u32_e32 v61, v98, v108
	s_waitcnt vmcnt(27)
	ds_write_b32 v61, v82
	v_add_u32_e32 v61, v98, v109
	s_waitcnt vmcnt(26)
	ds_write_b32 v61, v83
	v_add_u32_e32 v61, v98, v110
	s_waitcnt vmcnt(25)
	ds_write_b32 v61, v84
	v_add_u32_e32 v61, v98, v111
	s_waitcnt vmcnt(24)
	ds_write_b32 v61, v85
	v_add_u32_e32 v61, v98, v112
	s_waitcnt vmcnt(23)
	ds_write_b32 v61, v86
	v_add_u32_e32 v61, v98, v113
	s_waitcnt vmcnt(22)
	ds_write_b32 v61, v87
	v_add_u32_e32 v61, v98, v114
	s_waitcnt vmcnt(21)
	ds_write_b32 v61, v88
	v_add_u32_e32 v61, v98, v115
	s_waitcnt vmcnt(20)
	ds_write_b32 v61, v89
	v_add_u32_e32 v61, v98, v116
	s_waitcnt vmcnt(19)
	ds_write_b32 v61, v90
	v_add_u32_e32 v61, v98, v117
	s_waitcnt vmcnt(18)
	ds_write_b32 v61, v91
	v_add_u32_e32 v61, v98, v118
	s_waitcnt vmcnt(17)
	ds_write_b32 v61, v92
	v_add_u32_e32 v61, v98, v119
	s_waitcnt vmcnt(16)
	ds_write_b32 v61, v93
	v_add_u32_e32 v61, v98, v120
	s_lshl_b32 s10, s7, 1
	v_lshl_add_u64 v[80:81], v[6:7], 0, s[10:11]
	s_waitcnt vmcnt(15)
	ds_write_b32 v61, v94
	v_add_u32_e32 v61, v98, v121
	s_waitcnt vmcnt(14)
	ds_write_b32 v61, v95
	v_add_u32_e32 v61, v98, v122
	s_waitcnt vmcnt(13)
	ds_write_b32 v61, v96
	v_add_u32_e32 v61, v98, v123
	s_waitcnt vmcnt(12)
	ds_write_b32 v61, v97
	v_add_u32_e32 v61, v98, v124
	s_waitcnt vmcnt(11)
	ds_write_b32 v61, v137
	v_add_u32_e32 v61, v98, v125
	s_waitcnt vmcnt(10)
	ds_write_b32 v61, v138
	v_add_u32_e32 v61, v98, v126
	s_waitcnt vmcnt(9)
	ds_write_b32 v61, v76
	v_add_u32_e32 v61, v98, v127
	s_waitcnt vmcnt(8)
	ds_write_b32 v61, v74
	v_add_u32_e32 v61, v98, v128
	s_waitcnt vmcnt(7)
	ds_write_b32 v61, v75
	v_add_u32_e32 v61, v98, v129
	s_waitcnt vmcnt(6)
	ds_write_b32 v61, v77
	v_add_u32_e32 v61, v98, v130
	s_waitcnt vmcnt(5)
	ds_write_b32 v61, v68
	v_add_u32_e32 v61, v98, v131
	s_waitcnt vmcnt(4)
	ds_write_b32 v61, v66
	v_add_u32_e32 v61, v98, v132
	s_waitcnt vmcnt(3)
	ds_write_b32 v61, v67
	v_add_u32_e32 v61, v98, v133
	s_waitcnt vmcnt(2)
	ds_write_b32 v61, v69
	v_add_u32_e32 v61, v98, v134
	s_waitcnt vmcnt(1)
	ds_write_b32 v61, v64
	v_add_u32_e32 v61, v98, v135
	s_waitcnt vmcnt(0)
	ds_write_b32 v61, v60
	s_waitcnt lgkmcnt(0)
	ds_read2_b32 v[64:65], v100 offset0:33 offset1:41
	ds_read2_b32 v[66:67], v100 offset1:8
	ds_read2_b32 v[68:69], v100 offset0:66 offset1:74
	ds_read2_b32 v[70:71], v100 offset0:99 offset1:107
	ds_read2_b32 v[72:73], v100 offset0:132 offset1:140
	ds_read2_b32 v[74:75], v100 offset0:165 offset1:173
	ds_read2_b32 v[76:77], v100 offset0:198 offset1:206
	ds_read2_b32 v[78:79], v100 offset0:231 offset1:239
	s_waitcnt lgkmcnt(6)
	v_cvt_pk_bf16_f32 v60, v66, v64
	v_add_u32_e32 v64, s6, v99
	v_mad_i64_i32 v[82:83], s[30:31], v64, s2, v[80:81]
	s_waitcnt lgkmcnt(4)
	v_cvt_pk_bf16_f32 v61, v68, v70
	s_waitcnt lgkmcnt(2)
	v_cvt_pk_bf16_f32 v62, v72, v74
	s_waitcnt lgkmcnt(0)
	v_cvt_pk_bf16_f32 v63, v76, v78
	global_store_dwordx4 v[82:83], v[60:63], off
	v_add_u32_e32 v64, s6, v101
	s_nop 0
	v_cvt_pk_bf16_f32 v60, v67, v65
	v_cvt_pk_bf16_f32 v61, v69, v71
	v_cvt_pk_bf16_f32 v62, v73, v75
	v_cvt_pk_bf16_f32 v63, v77, v79
	ds_read2_b32 v[66:67], v100 offset0:16 offset1:24
	ds_read2_b32 v[68:69], v100 offset0:49 offset1:57
	ds_read2_b32 v[70:71], v100 offset0:82 offset1:90
	ds_read2_b32 v[72:73], v100 offset0:115 offset1:123
	ds_read2_b32 v[74:75], v100 offset0:148 offset1:156
	ds_read2_b32 v[76:77], v100 offset0:181 offset1:189
	ds_read2_b32 v[78:79], v100 offset0:214 offset1:222
	ds_read2_b32 v[82:83], v100 offset0:247 offset1:255
	v_mad_i64_i32 v[64:65], s[30:31], v64, s2, v[80:81]
	global_store_dwordx4 v[64:65], v[60:63], off
	v_add_u32_e32 v64, s6, v102
	v_mad_i64_i32 v[64:65], s[30:31], v64, s2, v[80:81]
	s_waitcnt lgkmcnt(6)
	v_cvt_pk_bf16_f32 v60, v66, v68
	s_waitcnt lgkmcnt(4)
	v_cvt_pk_bf16_f32 v61, v70, v72
	s_waitcnt lgkmcnt(2)
	v_cvt_pk_bf16_f32 v62, v74, v76
	s_waitcnt lgkmcnt(0)
	v_cvt_pk_bf16_f32 v63, v78, v82
	global_store_dwordx4 v[64:65], v[60:63], off
	v_add_u32_e32 v64, s6, v103
	v_mad_i64_i32 v[64:65], s[6:7], v64, s2, v[80:81]
	v_cvt_pk_bf16_f32 v60, v67, v69
	v_cvt_pk_bf16_f32 v61, v71, v73
	v_cvt_pk_bf16_f32 v62, v75, v77
	v_cvt_pk_bf16_f32 v63, v79, v83
	global_store_dwordx4 v[64:65], v[60:63], off
	s_waitcnt lgkmcnt(0)

; #define LAS __attribute__((address_space(3)))
; template <bool GU>
; __device__ __forceinline__ void transpose_item(const float* W, int K, int N, bf16* WT, const float* gs, LAS float* scr, int item, int lane) {
;     const int nblk = N / 32, kb = item / nblk, nb = item % nblk, k0 = 64 * kb, n0 = 32 * nb;
; #pragma unroll 16
;     for (int i = 0; i < 32; ++i) { const int kk = 2 * i + (lane >> 5); float w = W[(size_t)(k0 + kk) * N + n0 + (lane & 31)]; if (gs) w *= gs[k0 + kk]; scr[kk * 33 + (lane & 31)] = w; }
; __device__ __forceinline__ void conv_weights(LAS unsigned char* lds, unsigned char* ws, const PIn& I, const int l, const int wave, const int lane, const int gw, const int NGW, const int r_lo, const int r_hi) {
;     ...
;         if (r < I_IN) { transpose_item<false>(I.w_in + (size_t)l * DM * NIN, DM, NIN, (bf16*)(wb + W_IN), I.g_mix + l * DM, scr, r, lane); continue; } r -= I_IN;
;         if (r < I_OUT) { transpose_item<false>(I.w_out + (size_t)l * DM * DM, DM, DM, (bf16*)(wb + W_OUT), nullptr, scr, r, lane); continue; } r -= I_OUT;
;         if (r < I_GU) { transpose_item<true>(I.w_gu + (size_t)l * DM * 2 * FF, DM, 2 * FF, (bf16*)(wb + W_GU), I.g_ffn + l * DM, scr, r, lane); continue; } r -= I_GU;
.LBB0_497:
	s_andn2_b64 vcc, exec, s[6:7]
	s_cbranch_vccnz .LBB0_533
	s_add_i32 s6, s1, 0xf980
	s_and_b32 s30, s6, 0xffff
	s_mul_i32 s7, s30, 0xba2f
	s_lshr_b32 s7, s7, 23
	s_mul_i32 s9, s7, 0xb0
	s_sub_i32 s29, s6, s9
	s_lshl_b32 s6, s29, 7
	s_lshl_b32 s9, s7, 6
	s_and_b32 s10, s6, 0x3ff80
	v_add_u32_e32 v60, s9, v37
	v_mov_b64_e32 v[94:95], s[10:11]
	v_mad_i64_i32 v[60:61], s[6:7], v60, s3, v[94:95]
	s_mul_hi_u32 s6, s30, 0x1745d18
	v_add_u32_e32 v64, s9, v36
	v_add_u32_e32 v66, s9, v35
	v_add_u32_e32 v68, s9, v34
	v_add_u32_e32 v70, s9, v33
	v_add_u32_e32 v72, s9, v32
	v_add_u32_e32 v74, s9, v31
	v_add_u32_e32 v76, s9, v30
	v_add_u32_e32 v78, s9, v29
	v_add_u32_e32 v80, s9, v28
	v_add_u32_e32 v82, s9, v27
	v_add_u32_e32 v84, s9, v26
	v_add_u32_e32 v86, s9, v25
	v_add_u32_e32 v88, s9, v24
	v_add_u32_e32 v90, s9, v1
	v_add_u32_e32 v96, s9, v54
	v_readlane_b32 s48, v249, 21
	s_lshl_b32 s10, s6, 8
	v_mad_i64_i32 v[64:65], s[6:7], v64, s3, v[94:95]
	v_mad_i64_i32 v[66:67], s[6:7], v66, s3, v[94:95]
	v_mad_i64_i32 v[68:69], s[6:7], v68, s3, v[94:95]
	v_mad_i64_i32 v[70:71], s[6:7], v70, s3, v[94:95]
	v_mad_i64_i32 v[72:73], s[6:7], v72, s3, v[94:95]
	v_mad_i64_i32 v[74:75], s[6:7], v74, s3, v[94:95]
	v_mad_i64_i32 v[76:77], s[6:7], v76, s3, v[94:95]
	v_mad_i64_i32 v[78:79], s[6:7], v78, s3, v[94:95]
	v_mad_i64_i32 v[80:81], s[6:7], v80, s3, v[94:95]
	v_mad_i64_i32 v[82:83], s[6:7], v82, s3, v[94:95]
	v_mad_i64_i32 v[84:85], s[6:7], v84, s3, v[94:95]
	v_mad_i64_i32 v[86:87], s[6:7], v86, s3, v[94:95]
	v_mad_i64_i32 v[88:89], s[6:7], v88, s3, v[94:95]
	v_mad_i64_i32 v[90:91], s[6:7], v90, s3, v[94:95]
	v_ashrrev_i32_e32 v97, 31, v96
	v_mad_i64_i32 v[94:95], s[6:7], v96, s3, v[94:95]
	v_readlane_b32 s62, v249, 35
	v_readlane_b32 s63, v249, 36
	s_lshl_b32 s36, s29, 5
	v_lshl_add_u64 v[60:61], v[56:57], 0, v[60:61]
	v_lshl_add_u64 v[62:63], v[58:59], 0, s[10:11]
	v_lshl_add_u64 v[64:65], v[56:57], 0, v[64:65]
	v_lshl_add_u64 v[66:67], v[56:57], 0, v[66:67]
	v_lshl_add_u64 v[68:69], v[56:57], 0, v[68:69]
	v_lshl_add_u64 v[70:71], v[56:57], 0, v[70:71]
	v_lshl_add_u64 v[72:73], v[56:57], 0, v[72:73]
	v_lshl_add_u64 v[74:75], v[56:57], 0, v[74:75]
	v_lshl_add_u64 v[76:77], v[56:57], 0, v[76:77]
	v_lshl_add_u64 v[78:79], v[56:57], 0, v[78:79]
	v_lshl_add_u64 v[80:81], v[56:57], 0, v[80:81]
	v_lshl_add_u64 v[82:83], v[56:57], 0, v[82:83]
	v_lshl_add_u64 v[84:85], v[56:57], 0, v[84:85]
	v_lshl_add_u64 v[86:87], v[56:57], 0, v[86:87]
	v_lshl_add_u64 v[88:89], v[56:57], 0, v[88:89]
	v_lshl_add_u64 v[90:91], v[56:57], 0, v[90:91]
	v_lshlrev_b64 v[92:93], 2, v[96:97]
	v_lshl_add_u64 v[94:95], v[56:57], 0, v[94:95]
	s_mov_b64 s[30:31], 0
	s_mov_b64 s[42:43], s[62:63]
	v_mov_b32_e32 v137, v136
	v_readlane_b32 s49, v249, 22
	v_readlane_b32 s50, v249, 23
	v_readlane_b32 s51, v249, 24
	v_readlane_b32 s52, v249, 25
	v_readlane_b32 s53, v249, 26
	v_readlane_b32 s54, v249, 27
	v_readlane_b32 s55, v249, 28
	v_readlane_b32 s56, v249, 29
	v_readlane_b32 s57, v249, 30
	v_readlane_b32 s58, v249, 31
	v_readlane_b32 s59, v249, 32
	v_readlane_b32 s60, v249, 33
	v_readlane_b32 s61, v249, 34
	s_andn2_b64 vcc, exec, s[12:13]
	s_cbranch_vccnz .LBB0_500
	s_mov_b64 s[58:59], 0xb000
	v_mov_b32_e32 v234, v94
	v_mov_b32_e32 v235, v95
	v_lshl_add_u64 v[236:237], s[42:43], 0, v[92:93]
	global_load_dword v166, v[234:235], off nt
	v_lshl_add_u64 v[234:235], v[234:235], 0, s[58:59]
	global_load_dword v167, v[234:235], off nt
	v_lshl_add_u64 v[234:235], v[234:235], 0, s[58:59]
	global_load_dword v168, v[234:235], off nt
	v_lshl_add_u64 v[234:235], v[234:235], 0, s[58:59]
	global_load_dword v169, v[234:235], off nt
	v_lshl_add_u64 v[234:235], v[234:235], 0, s[58:59]
	global_load_dword v170, v[234:235], off nt
	v_lshl_add_u64 v[234:235], v[234:235], 0, s[58:59]
	global_load_dword v171, v[234:235], off nt
	v_lshl_add_u64 v[234:235], v[234:235], 0, s[58:59]
	global_load_dword v172, v[234:235], off nt
	v_lshl_add_u64 v[234:235], v[234:235], 0, s[58:59]
	global_load_dword v173, v[234:235], off nt
	v_lshl_add_u64 v[234:235], v[234:235], 0, s[58:59]
	global_load_dword v174, v[234:235], off nt
	v_lshl_add_u64 v[234:235], v[234:235], 0, s[58:59]
	global_load_dword v175, v[234:235], off nt
	v_lshl_add_u64 v[234:235], v[234:235], 0, s[58:59]
	global_load_dword v176, v[234:235], off nt
	v_lshl_add_u64 v[234:235], v[234:235], 0, s[58:59]
	global_load_dword v177, v[234:235], off nt
	v_lshl_add_u64 v[234:235], v[234:235], 0, s[58:59]
	global_load_dword v178, v[234:235], off nt
	v_lshl_add_u64 v[234:235], v[234:235], 0, s[58:59]
	global_load_dword v179, v[234:235], off nt
	v_lshl_add_u64 v[234:235], v[234:235], 0, s[58:59]
	global_load_dword v180, v[234:235], off nt
	v_lshl_add_u64 v[234:235], v[234:235], 0, s[58:59]
	global_load_dword v181, v[234:235], off nt
	v_lshl_add_u64 v[234:235], v[234:235], 0, s[58:59]
	global_load_dword v182, v[234:235], off nt
	v_lshl_add_u64 v[234:235], v[234:235], 0, s[58:59]
	global_load_dword v183, v[234:235], off nt
	v_lshl_add_u64 v[234:235], v[234:235], 0, s[58:59]
	global_load_dword v184, v[234:235], off nt
	v_lshl_add_u64 v[234:235], v[234:235], 0, s[58:59]
	global_load_dword v185, v[234:235], off nt
	v_lshl_add_u64 v[234:235], v[234:235], 0, s[58:59]
	global_load_dword v186, v[234:235], off nt
	v_lshl_add_u64 v[234:235], v[234:235], 0, s[58:59]
	global_load_dword v187, v[234:235], off nt
	v_lshl_add_u64 v[234:235], v[234:235], 0, s[58:59]
; template <bool GU>
; __device__ __forceinline__ void transpose_item(const float* W, int K, int N, bf16* WT, const float* gs, LAS float* scr, int item, int lane) {
;     const int nblk = N / 32, kb = item / nblk, nb = item % nblk, k0 = 64 * kb, n0 = 32 * nb;
; #pragma unroll 16
;     for (int i = 0; i < 32; ++i) { const int kk = 2 * i + (lane >> 5); float w = W[(size_t)(k0 + kk) * N + n0 + (lane & 31)]; if (gs) w *= gs[k0 + kk]; scr[kk * 33 + (lane & 31)] = w; }
;     asm volatile("s_waitcnt lgkmcnt(0)" ::: "memory");
	global_load_dword v188, v[234:235], off nt
	v_lshl_add_u64 v[234:235], v[234:235], 0, s[58:59]
	global_load_dword v189, v[234:235], off nt
	v_lshl_add_u64 v[234:235], v[234:235], 0, s[58:59]
	global_load_dword v190, v[234:235], off nt
	v_lshl_add_u64 v[234:235], v[234:235], 0, s[58:59]
	global_load_dword v191, v[234:235], off nt
	v_lshl_add_u64 v[234:235], v[234:235], 0, s[58:59]
	global_load_dword v192, v[234:235], off nt
	v_lshl_add_u64 v[234:235], v[234:235], 0, s[58:59]
	global_load_dword v193, v[234:235], off nt
	v_lshl_add_u64 v[234:235], v[234:235], 0, s[58:59]
	global_load_dword v194, v[234:235], off nt
	v_lshl_add_u64 v[234:235], v[234:235], 0, s[58:59]
	global_load_dword v195, v[234:235], off nt
	v_lshl_add_u64 v[234:235], v[234:235], 0, s[58:59]
	global_load_dword v199, v[234:235], off nt
	v_lshl_add_u64 v[234:235], v[234:235], 0, s[58:59]
	global_load_dword v200, v[234:235], off nt
	global_load_dword v201, v[236:237], off nt
	global_load_dword v202, v[236:237], off offset:8
	global_load_dword v203, v[236:237], off offset:16
	global_load_dword v204, v[236:237], off offset:24
	global_load_dword v205, v[236:237], off offset:32
	global_load_dword v206, v[236:237], off offset:40
	global_load_dword v207, v[236:237], off offset:48
	global_load_dword v208, v[236:237], off offset:56
	global_load_dword v209, v[236:237], off offset:64
	global_load_dword v210, v[236:237], off offset:72
	global_load_dword v211, v[236:237], off offset:80
	global_load_dword v212, v[236:237], off offset:88
	global_load_dword v213, v[236:237], off offset:96
	global_load_dword v214, v[236:237], off offset:104
	global_load_dword v215, v[236:237], off offset:112
	global_load_dword v216, v[236:237], off offset:120
	global_load_dword v217, v[236:237], off offset:128
	global_load_dword v218, v[236:237], off offset:136
	global_load_dword v219, v[236:237], off offset:144
	global_load_dword v220, v[236:237], off offset:152
	global_load_dword v221, v[236:237], off offset:160
	global_load_dword v222, v[236:237], off offset:168
	global_load_dword v223, v[236:237], off offset:176
	global_load_dword v224, v[236:237], off offset:184
	global_load_dword v225, v[236:237], off offset:192
	global_load_dword v226, v[236:237], off offset:200
	global_load_dword v227, v[236:237], off offset:208
	global_load_dword v228, v[236:237], off offset:216
	global_load_dword v229, v[236:237], off offset:224
	global_load_dword v230, v[236:237], off offset:232
	global_load_dword v231, v[236:237], off offset:240
	global_load_dword v232, v[236:237], off offset:248
	s_waitcnt vmcnt(31)
	v_mul_f32_e32 v166, v166, v201
	ds_write_b32 v137, v166
	s_waitcnt vmcnt(30)
	v_mul_f32_e32 v167, v167, v202
	ds_write_b32 v137, v167 offset:264
	s_waitcnt vmcnt(29)
	v_mul_f32_e32 v168, v168, v203
	ds_write_b32 v137, v168 offset:528
	s_waitcnt vmcnt(28)
	v_mul_f32_e32 v169, v169, v204
	ds_write_b32 v137, v169 offset:792
	s_waitcnt vmcnt(27)
	v_mul_f32_e32 v170, v170, v205
	ds_write_b32 v137, v170 offset:1056
	s_waitcnt vmcnt(26)
	v_mul_f32_e32 v171, v171, v206
	ds_write_b32 v137, v171 offset:1320
	s_waitcnt vmcnt(25)
	v_mul_f32_e32 v172, v172, v207
	ds_write_b32 v137, v172 offset:1584
	s_waitcnt vmcnt(24)
	v_mul_f32_e32 v173, v173, v208
	ds_write_b32 v137, v173 offset:1848
	s_waitcnt vmcnt(23)
	v_mul_f32_e32 v174, v174, v209
	ds_write_b32 v137, v174 offset:2112
	s_waitcnt vmcnt(22)
	v_mul_f32_e32 v175, v175, v210
	ds_write_b32 v137, v175 offset:2376
	s_waitcnt vmcnt(21)
	v_mul_f32_e32 v176, v176, v211
	ds_write_b32 v137, v176 offset:2640
	s_waitcnt vmcnt(20)
	v_mul_f32_e32 v177, v177, v212
	ds_write_b32 v137, v177 offset:2904
	s_waitcnt vmcnt(19)
	v_mul_f32_e32 v178, v178, v213
	ds_write_b32 v137, v178 offset:3168
	s_waitcnt vmcnt(18)
	v_mul_f32_e32 v179, v179, v214
	ds_write_b32 v137, v179 offset:3432
	s_waitcnt vmcnt(17)
	v_mul_f32_e32 v180, v180, v215
	ds_write_b32 v137, v180 offset:3696
	s_waitcnt vmcnt(16)
	v_mul_f32_e32 v181, v181, v216
	ds_write_b32 v137, v181 offset:3960
	s_waitcnt vmcnt(15)
	v_mul_f32_e32 v182, v182, v217
	ds_write_b32 v137, v182 offset:4224
	s_waitcnt vmcnt(14)
	v_mul_f32_e32 v183, v183, v218
	ds_write_b32 v137, v183 offset:4488
	s_waitcnt vmcnt(13)
	v_mul_f32_e32 v184, v184, v219
	ds_write_b32 v137, v184 offset:4752
	s_waitcnt vmcnt(12)
	v_mul_f32_e32 v185, v185, v220
	ds_write_b32 v137, v185 offset:5016
	s_waitcnt vmcnt(11)
	v_mul_f32_e32 v186, v186, v221
	ds_write_b32 v137, v186 offset:5280
	s_waitcnt vmcnt(10)
	v_mul_f32_e32 v187, v187, v222
	ds_write_b32 v137, v187 offset:5544
	s_waitcnt vmcnt(9)
	v_mul_f32_e32 v188, v188, v223
	ds_write_b32 v137, v188 offset:5808
	s_waitcnt vmcnt(8)
	v_mul_f32_e32 v189, v189, v224
	ds_write_b32 v137, v189 offset:6072
	s_waitcnt vmcnt(7)
	v_mul_f32_e32 v190, v190, v225
	ds_write_b32 v137, v190 offset:6336
	s_waitcnt vmcnt(6)
	v_mul_f32_e32 v191, v191, v226
	ds_write_b32 v137, v191 offset:6600
	s_waitcnt vmcnt(5)
	v_mul_f32_e32 v192, v192, v227
	ds_write_b32 v137, v192 offset:6864
	s_waitcnt vmcnt(4)
	v_mul_f32_e32 v193, v193, v228
	ds_write_b32 v137, v193 offset:7128
	s_waitcnt vmcnt(3)
	v_mul_f32_e32 v194, v194, v229
	ds_write_b32 v137, v194 offset:7392
	s_waitcnt vmcnt(2)
	v_mul_f32_e32 v195, v195, v230
	ds_write_b32 v137, v195 offset:7656
	s_waitcnt vmcnt(1)
	v_mul_f32_e32 v199, v199, v231
	ds_write_b32 v137, v199 offset:7920
	s_waitcnt vmcnt(0)
	v_mul_f32_e32 v200, v200, v232
	ds_write_b32 v137, v200 offset:8184
	s_branch .LBB0_532

; template <bool GU>
; __device__ __forceinline__ void transpose_item(const float* W, int K, int N, bf16* WT, const float* gs, LAS float* scr, int item, int lane) {
;     ...
; #pragma unroll 16
;     for (int i = 0; i < 32; ++i) { const int kk = 2 * i + (lane >> 5); float w = W[(size_t)(k0 + kk) * N + n0 + (lane & 31)]; if (gs) w *= gs[k0 + kk]; scr[kk * 33 + (lane & 31)] = w; }
.LBB0_500:
	v_lshl_add_u64 v[96:97], v[94:95], 0, s[30:31]
	global_load_dword v96, v[96:97], off nt
	v_cndmask_b32_e64 v97, 0, 1, s[12:13]
	v_cmp_ne_u32_e64 s[6:7], 1, v97
	s_andn2_b64 vcc, exec, s[12:13]
	s_cbranch_vccnz .LBB0_502
	v_lshl_add_u64 v[138:139], s[42:43], 0, v[92:93]
	global_load_dword v97, v[138:139], off nt
	s_waitcnt vmcnt(0)
	v_mul_f32_e32 v96, v96, v97
.LBB0_502:
	s_waitcnt vmcnt(0)
	ds_write_b32 v137, v96
	v_lshl_add_u64 v[96:97], v[90:91], 0, s[30:31]
	global_load_dword v138, v[96:97], off nt
	s_and_b64 vcc, exec, s[6:7]
	v_lshl_add_u64 v[96:97], s[42:43], 0, v[62:63]
	s_cbranch_vccnz .LBB0_504
	global_load_dword v139, v[96:97], off offset:8
	s_waitcnt vmcnt(0)
	v_mul_f32_e32 v138, v138, v139
.LBB0_504:
	s_waitcnt vmcnt(0)
	ds_write_b32 v137, v138 offset:264
	v_lshl_add_u64 v[138:139], v[88:89], 0, s[30:31]
	global_load_dword v138, v[138:139], off nt
	s_and_b64 vcc, exec, s[6:7]
	s_cbranch_vccnz .LBB0_506
	global_load_dword v139, v[96:97], off offset:16
	s_waitcnt vmcnt(0)
	v_mul_f32_e32 v138, v138, v139
.LBB0_506:
	s_waitcnt vmcnt(0)
	ds_write_b32 v137, v138 offset:528
	v_lshl_add_u64 v[138:139], v[86:87], 0, s[30:31]
	global_load_dword v138, v[138:139], off nt
	s_and_b64 vcc, exec, s[6:7]
	s_cbranch_vccnz .LBB0_508
	global_load_dword v139, v[96:97], off offset:24
	s_waitcnt vmcnt(0)
	v_mul_f32_e32 v138, v138, v139
.LBB0_508:
	s_waitcnt vmcnt(0)
	ds_write_b32 v137, v138 offset:792
	v_lshl_add_u64 v[138:139], v[84:85], 0, s[30:31]
	global_load_dword v138, v[138:139], off nt
	s_and_b64 vcc, exec, s[6:7]
	s_cbranch_vccnz .LBB0_510
	global_load_dword v139, v[96:97], off offset:32
	s_waitcnt vmcnt(0)
	v_mul_f32_e32 v138, v138, v139
.LBB0_510:
	s_waitcnt vmcnt(0)
	ds_write_b32 v137, v138 offset:1056
	v_lshl_add_u64 v[138:139], v[82:83], 0, s[30:31]
	global_load_dword v138, v[138:139], off nt
	s_and_b64 vcc, exec, s[6:7]
	s_cbranch_vccnz .LBB0_512
	global_load_dword v139, v[96:97], off offset:40
	s_waitcnt vmcnt(0)
	v_mul_f32_e32 v138, v138, v139
.LBB0_512:
	s_waitcnt vmcnt(0)
	ds_write_b32 v137, v138 offset:1320
	v_lshl_add_u64 v[138:139], v[80:81], 0, s[30:31]
	global_load_dword v138, v[138:139], off nt
	s_and_b64 vcc, exec, s[6:7]
	s_cbranch_vccnz .LBB0_514
	global_load_dword v139, v[96:97], off offset:48
	s_waitcnt vmcnt(0)
	v_mul_f32_e32 v138, v138, v139
.LBB0_514:
	s_waitcnt vmcnt(0)
	ds_write_b32 v137, v138 offset:1584
	v_lshl_add_u64 v[138:139], v[78:79], 0, s[30:31]
	global_load_dword v138, v[138:139], off nt
	s_and_b64 vcc, exec, s[6:7]
	s_cbranch_vccnz .LBB0_516
	global_load_dword v139, v[96:97], off offset:56
	s_waitcnt vmcnt(0)
	v_mul_f32_e32 v138, v138, v139
.LBB0_516:
	s_waitcnt vmcnt(0)
	ds_write_b32 v137, v138 offset:1848
	v_lshl_add_u64 v[138:139], v[76:77], 0, s[30:31]
	global_load_dword v138, v[138:139], off nt
	s_and_b64 vcc, exec, s[6:7]
	s_cbranch_vccnz .LBB0_518
	global_load_dword v139, v[96:97], off offset:64
	s_waitcnt vmcnt(0)
	v_mul_f32_e32 v138, v138, v139
.LBB0_518:
	s_waitcnt vmcnt(0)
	ds_write_b32 v137, v138 offset:2112
	v_lshl_add_u64 v[138:139], v[74:75], 0, s[30:31]
	global_load_dword v138, v[138:139], off nt
	s_and_b64 vcc, exec, s[6:7]
	s_cbranch_vccnz .LBB0_520
	global_load_dword v139, v[96:97], off offset:72
	s_waitcnt vmcnt(0)
	v_mul_f32_e32 v138, v138, v139
.LBB0_520:
	s_waitcnt vmcnt(0)
	ds_write_b32 v137, v138 offset:2376
	v_lshl_add_u64 v[138:139], v[72:73], 0, s[30:31]
	global_load_dword v138, v[138:139], off nt
	s_and_b64 vcc, exec, s[6:7]
	s_cbranch_vccnz .LBB0_522
	global_load_dword v139, v[96:97], off offset:80
	s_waitcnt vmcnt(0)
	v_mul_f32_e32 v138, v138, v139
.LBB0_522:
	s_waitcnt vmcnt(0)
	ds_write_b32 v137, v138 offset:2640
	v_lshl_add_u64 v[138:139], v[70:71], 0, s[30:31]
	global_load_dword v138, v[138:139], off nt
	s_and_b64 vcc, exec, s[6:7]
	s_cbranch_vccnz .LBB0_524
	global_load_dword v139, v[96:97], off offset:88
	s_waitcnt vmcnt(0)
	v_mul_f32_e32 v138, v138, v139
.LBB0_524:
	s_waitcnt vmcnt(0)
	ds_write_b32 v137, v138 offset:2904
	v_lshl_add_u64 v[138:139], v[68:69], 0, s[30:31]
	global_load_dword v138, v[138:139], off nt
	s_and_b64 vcc, exec, s[6:7]
	s_cbranch_vccnz .LBB0_526
	global_load_dword v139, v[96:97], off offset:96
	s_waitcnt vmcnt(0)
	v_mul_f32_e32 v138, v138, v139
.LBB0_526:
	s_waitcnt vmcnt(0)
	ds_write_b32 v137, v138 offset:3168
	v_lshl_add_u64 v[138:139], v[66:67], 0, s[30:31]
	global_load_dword v138, v[138:139], off nt
	s_and_b64 vcc, exec, s[6:7]
	s_cbranch_vccnz .LBB0_528
	global_load_dword v139, v[96:97], off offset:104
	s_waitcnt vmcnt(0)
	v_mul_f32_e32 v138, v138, v139
.LBB0_528:
	s_waitcnt vmcnt(0)
	ds_write_b32 v137, v138 offset:3432
	v_lshl_add_u64 v[138:139], v[64:65], 0, s[30:31]
	global_load_dword v138, v[138:139], off nt
	s_and_b64 vcc, exec, s[6:7]
	s_cbranch_vccnz .LBB0_530
	global_load_dword v139, v[96:97], off offset:112
	s_waitcnt vmcnt(0)
	v_mul_f32_e32 v138, v138, v139
.LBB0_530:
	s_waitcnt vmcnt(0)
	ds_write_b32 v137, v138 offset:3696
	v_lshl_add_u64 v[138:139], v[60:61], 0, s[30:31]
	global_load_dword v138, v[138:139], off nt
	s_and_b64 vcc, exec, s[6:7]
	s_cbranch_vccnz .LBB0_499
	global_load_dword v96, v[96:97], off offset:120
	s_waitcnt vmcnt(0)
	v_mul_f32_e32 v138, v138, v96
	s_branch .LBB0_499

; template <bool GU>
; __device__ __forceinline__ void transpose_item(const float* W, int K, int N, bf16* WT, const float* gs, LAS float* scr, int item, int lane) {
;     const int nblk = N / 32, kb = item / nblk, nb = item % nblk, k0 = 64 * kb, n0 = 32 * nb;
; #pragma unroll 16
;     for (int i = 0; i < 32; ++i) { const int kk = 2 * i + (lane >> 5); float w = W[(size_t)(k0 + kk) * N + n0 + (lane & 31)]; if (gs) w *= gs[k0 + kk]; scr[kk * 33 + (lane & 31)] = w; }
; __device__ __forceinline__ void conv_weights(LAS unsigned char* lds, unsigned char* ws, const PIn& I, const int l, const int wave, const int lane, const int gw, const int NGW, const int r_lo, const int r_hi) {
;     ...
;         if (r < I_OUT) { transpose_item<false>(I.w_out + (size_t)l * DM * DM, DM, DM, (bf16*)(wb + W_OUT), nullptr, scr, r, lane); continue; } r -= I_OUT;
.LBB0_534:
	s_andn2_b64 vcc, exec, s[6:7]
	s_cbranch_vccnz .LBB0_536
	s_lshl_b32 s6, s1, 1
	s_add_i32 s6, s6, 0x1f700
	s_and_b32 s7, s6, 0x1ffc0
	s_lshl_b32 s6, s1, 5
	s_and_b32 s6, s6, 0x3e0
	v_add_u32_e32 v64, s7, v0
	s_lshl_b32 s10, s6, 2
	v_add_u32_e32 v62, s7, v1
	v_ashrrev_i32_e32 v65, 31, v64
	v_add_u32_e32 v66, s7, v25
	v_add_u32_e32 v68, s7, v24
	v_add_u32_e32 v70, s7, v27
	v_add_u32_e32 v72, s7, v26
	v_add_u32_e32 v74, s7, v29
	v_add_u32_e32 v76, s7, v28
	v_lshl_add_u64 v[60:61], v[20:21], 0, s[10:11]
	v_ashrrev_i32_e32 v63, 31, v62
	v_lshlrev_b64 v[64:65], 12, v[64:65]
	v_ashrrev_i32_e32 v69, 31, v68
	v_ashrrev_i32_e32 v67, 31, v66
	v_ashrrev_i32_e32 v73, 31, v72
	v_ashrrev_i32_e32 v71, 31, v70
	v_ashrrev_i32_e32 v77, 31, v76
	v_ashrrev_i32_e32 v75, 31, v74
	v_lshlrev_b64 v[62:63], 12, v[62:63]
	v_lshl_add_u64 v[64:65], v[60:61], 0, v[64:65]
	v_lshlrev_b64 v[66:67], 12, v[66:67]
	v_lshlrev_b64 v[68:69], 12, v[68:69]
	v_lshlrev_b64 v[70:71], 12, v[70:71]
	v_lshlrev_b64 v[72:73], 12, v[72:73]
	v_lshlrev_b64 v[74:75], 12, v[74:75]
	v_lshlrev_b64 v[76:77], 12, v[76:77]
	v_lshl_add_u64 v[62:63], v[60:61], 0, v[62:63]
	v_lshl_add_u64 v[68:69], v[60:61], 0, v[68:69]
	v_lshl_add_u64 v[66:67], v[60:61], 0, v[66:67]
	v_lshl_add_u64 v[72:73], v[60:61], 0, v[72:73]
	v_lshl_add_u64 v[70:71], v[60:61], 0, v[70:71]
	v_lshl_add_u64 v[76:77], v[60:61], 0, v[76:77]
	v_lshl_add_u64 v[74:75], v[60:61], 0, v[74:75]
	global_load_dword v78, v[64:65], off nt
	global_load_dword v79, v[62:63], off nt
	global_load_dword v80, v[68:69], off nt
	global_load_dword v81, v[66:67], off nt
	global_load_dword v82, v[72:73], off nt
	global_load_dword v83, v[70:71], off nt
	global_load_dword v84, v[76:77], off nt
	global_load_dword v85, v[74:75], off nt
	v_add_u32_e32 v64, s7, v30
	v_add_u32_e32 v62, s7, v31
	v_ashrrev_i32_e32 v65, 31, v64
	v_add_u32_e32 v66, s7, v33
	v_add_u32_e32 v68, s7, v32
	v_add_u32_e32 v70, s7, v35
	v_add_u32_e32 v72, s7, v34
	v_add_u32_e32 v74, s7, v37
	v_add_u32_e32 v76, s7, v36
	v_ashrrev_i32_e32 v63, 31, v62
	v_lshlrev_b64 v[64:65], 12, v[64:65]
	v_ashrrev_i32_e32 v69, 31, v68
	v_ashrrev_i32_e32 v67, 31, v66
	v_ashrrev_i32_e32 v73, 31, v72
	v_ashrrev_i32_e32 v71, 31, v70
	v_ashrrev_i32_e32 v77, 31, v76
	v_ashrrev_i32_e32 v75, 31, v74
	v_lshlrev_b64 v[62:63], 12, v[62:63]
	v_lshl_add_u64 v[64:65], v[60:61], 0, v[64:65]
	v_lshlrev_b64 v[66:67], 12, v[66:67]
	v_lshlrev_b64 v[68:69], 12, v[68:69]
	v_lshlrev_b64 v[70:71], 12, v[70:71]
	v_lshlrev_b64 v[72:73], 12, v[72:73]
	v_lshlrev_b64 v[74:75], 12, v[74:75]
	v_lshlrev_b64 v[76:77], 12, v[76:77]
	v_lshl_add_u64 v[62:63], v[60:61], 0, v[62:63]
	v_lshl_add_u64 v[68:69], v[60:61], 0, v[68:69]
	v_lshl_add_u64 v[66:67], v[60:61], 0, v[66:67]
	v_lshl_add_u64 v[72:73], v[60:61], 0, v[72:73]
	v_lshl_add_u64 v[70:71], v[60:61], 0, v[70:71]
	v_lshl_add_u64 v[76:77], v[60:61], 0, v[76:77]
	v_lshl_add_u64 v[74:75], v[60:61], 0, v[74:75]
	global_load_dword v86, v[64:65], off nt
	global_load_dword v87, v[62:63], off nt
	global_load_dword v88, v[68:69], off nt
	global_load_dword v89, v[66:67], off nt
	global_load_dword v90, v[72:73], off nt
	global_load_dword v91, v[70:71], off nt
	global_load_dword v92, v[76:77], off nt
	global_load_dword v93, v[74:75], off nt
	v_add_u32_e32 v64, s7, v38
	v_add_u32_e32 v66, s7, v41
	v_add_u32_e32 v68, s7, v40
	v_add_u32_e32 v74, s7, v45
	v_add_u32_e32 v76, s7, v44
	v_add_u32_e32 v62, s7, v39
	v_ashrrev_i32_e32 v65, 31, v64
	v_ashrrev_i32_e32 v69, 31, v68
	v_ashrrev_i32_e32 v67, 31, v66
	v_add_u32_e32 v70, s7, v43
	v_add_u32_e32 v72, s7, v42
	v_ashrrev_i32_e32 v77, 31, v76
	v_ashrrev_i32_e32 v75, 31, v74
	v_ashrrev_i32_e32 v63, 31, v62
	v_lshlrev_b64 v[64:65], 12, v[64:65]
	v_lshlrev_b64 v[66:67], 12, v[66:67]
	v_lshlrev_b64 v[68:69], 12, v[68:69]
	v_ashrrev_i32_e32 v73, 31, v72
	v_ashrrev_i32_e32 v71, 31, v70
	v_lshlrev_b64 v[74:75], 12, v[74:75]
	v_lshlrev_b64 v[76:77], 12, v[76:77]
	v_lshlrev_b64 v[62:63], 12, v[62:63]
	v_lshl_add_u64 v[64:65], v[60:61], 0, v[64:65]
	v_lshl_add_u64 v[68:69], v[60:61], 0, v[68:69]
	v_lshl_add_u64 v[66:67], v[60:61], 0, v[66:67]
	v_lshlrev_b64 v[70:71], 12, v[70:71]
	v_lshlrev_b64 v[72:73], 12, v[72:73]
	v_lshl_add_u64 v[76:77], v[60:61], 0, v[76:77]
	v_lshl_add_u64 v[74:75], v[60:61], 0, v[74:75]
	v_lshl_add_u64 v[62:63], v[60:61], 0, v[62:63]
	v_lshl_add_u64 v[72:73], v[60:61], 0, v[72:73]
	v_lshl_add_u64 v[70:71], v[60:61], 0, v[70:71]
	global_load_dword v94, v[64:65], off nt
	global_load_dword v95, v[62:63], off nt
	global_load_dword v96, v[68:69], off nt
	global_load_dword v97, v[66:67], off nt
	global_load_dword v137, v[72:73], off nt
	global_load_dword v138, v[70:71], off nt
	s_nop 0
	global_load_dword v76, v[76:77], off nt
	s_nop 0
	global_load_dword v74, v[74:75], off nt
	v_add_u32_e32 v64, s7, v46
	v_add_u32_e32 v66, s7, v49
	v_add_u32_e32 v68, s7, v48
	v_add_u32_e32 v62, s7, v47
	v_ashrrev_i32_e32 v65, 31, v64
	v_ashrrev_i32_e32 v69, 31, v68
	v_ashrrev_i32_e32 v67, 31, v66
	v_add_u32_e32 v70, s7, v51
	v_add_u32_e32 v72, s7, v50
	v_ashrrev_i32_e32 v63, 31, v62
	v_lshlrev_b64 v[64:65], 12, v[64:65]
	v_lshlrev_b64 v[66:67], 12, v[66:67]
	v_lshlrev_b64 v[68:69], 12, v[68:69]
	v_ashrrev_i32_e32 v73, 31, v72
	v_ashrrev_i32_e32 v71, 31, v70
	v_lshlrev_b64 v[62:63], 12, v[62:63]
	v_lshl_add_u64 v[64:65], v[60:61], 0, v[64:65]
	v_lshl_add_u64 v[68:69], v[60:61], 0, v[68:69]
	v_lshl_add_u64 v[66:67], v[60:61], 0, v[66:67]
	v_lshlrev_b64 v[70:71], 12, v[70:71]
	v_lshlrev_b64 v[72:73], 12, v[72:73]
	v_lshl_add_u64 v[62:63], v[60:61], 0, v[62:63]
	v_lshl_add_u64 v[72:73], v[60:61], 0, v[72:73]
	v_lshl_add_u64 v[70:71], v[60:61], 0, v[70:71]
	global_load_dword v75, v[64:65], off nt
	global_load_dword v77, v[62:63], off nt
	s_nop 0
	global_load_dword v68, v[68:69], off nt
	s_nop 0
	global_load_dword v66, v[66:67], off nt
	s_nop 0
	global_load_dword v67, v[72:73], off nt
	global_load_dword v69, v[70:71], off nt
	v_add_u32_e32 v64, s7, v52
	v_add_u32_e32 v62, s7, v53
	v_ashrrev_i32_e32 v65, 31, v64
	v_ashrrev_i32_e32 v63, 31, v62
	v_lshlrev_b64 v[64:65], 12, v[64:65]
	v_lshlrev_b64 v[62:63], 12, v[62:63]
	v_lshl_add_u64 v[64:65], v[60:61], 0, v[64:65]
	global_load_dword v64, v[64:65], off nt
	v_lshl_add_u64 v[60:61], v[60:61], 0, v[62:63]
	global_load_dword v60, v[60:61], off nt
	v_add_u32_e32 v61, v98, v104
	s_waitcnt vmcnt(31)
; #define LAS __attribute__((address_space(3)))
; __device__ __forceinline__ unsigned cvt_pk(float lo, float hi) { unsigned r; asm("v_cvt_pk_bf16_f32 %0, %1, %2" : "=v"(r) : "v"(lo), "v"(hi)); return r; }
; template <bool GU>
; __device__ __forceinline__ void transpose_item(const float* W, int K, int N, bf16* WT, const float* gs, LAS float* scr, int item, int lane) {
;     ...
;     for (int i = 0; i < 32; ++i) { const int kk = 2 * i + (lane >> 5); float w = W[(size_t)(k0 + kk) * N + n0 + (lane & 31)]; if (gs) w *= gs[k0 + kk]; scr[kk * 33 + (lane & 31)] = w; }
;     asm volatile("s_waitcnt lgkmcnt(0)" ::: "memory");
;     int d0 = n0;
;     if (GU) { const int f = (n0 < FF) ? n0 : n0 - FF; d0 = 256 * (f >> 7) + (f & 127) + ((n0 < FF) ? 0 : 128); }
;     const int c = lane & 7;
; #pragma unroll
;     for (int j = 0; j < 4; ++j) { const int n = (lane >> 3) + 8 * j; const LAS float* s = scr + (8 * c) * 33 + n;
;         v4u o; o.x = cvt_pk(s[0 * 33], s[1 * 33]); o.y = cvt_pk(s[2 * 33], s[3 * 33]); o.z = cvt_pk(s[4 * 33], s[5 * 33]); o.w = cvt_pk(s[6 * 33], s[7 * 33]);
;         *(v4u*)(WT + (size_t)(d0 + n) * K + k0 + 8 * c) = o; }
;     asm volatile("s_waitcnt lgkmcnt(0)" ::: "memory");
	ds_write_b32 v61, v78
	v_add_u32_e32 v61, v98, v105
	s_waitcnt vmcnt(30)
	ds_write_b32 v61, v79
	v_add_u32_e32 v61, v98, v106
	s_waitcnt vmcnt(29)
	ds_write_b32 v61, v80
	v_add_u32_e32 v61, v98, v107
	s_waitcnt vmcnt(28)
	ds_write_b32 v61, v81
	v_add_u32_e32 v61, v98, v108
	s_waitcnt vmcnt(27)
	ds_write_b32 v61, v82
	v_add_u32_e32 v61, v98, v109
	s_waitcnt vmcnt(26)
	ds_write_b32 v61, v83
	v_add_u32_e32 v61, v98, v110
	s_waitcnt vmcnt(25)
	ds_write_b32 v61, v84
	v_add_u32_e32 v61, v98, v111
	s_waitcnt vmcnt(24)
	ds_write_b32 v61, v85
	v_add_u32_e32 v61, v98, v112
	s_waitcnt vmcnt(23)
	ds_write_b32 v61, v86
	v_add_u32_e32 v61, v98, v113
	s_waitcnt vmcnt(22)
	ds_write_b32 v61, v87
	v_add_u32_e32 v61, v98, v114
	s_waitcnt vmcnt(21)
	ds_write_b32 v61, v88
	v_add_u32_e32 v61, v98, v115
	s_waitcnt vmcnt(20)
	ds_write_b32 v61, v89
	v_add_u32_e32 v61, v98, v116
	s_waitcnt vmcnt(19)
	ds_write_b32 v61, v90
	v_add_u32_e32 v61, v98, v117
	s_waitcnt vmcnt(18)
	ds_write_b32 v61, v91
	v_add_u32_e32 v61, v98, v118
	s_waitcnt vmcnt(17)
	ds_write_b32 v61, v92
	v_add_u32_e32 v61, v98, v119
	s_waitcnt vmcnt(16)
	ds_write_b32 v61, v93
	v_add_u32_e32 v61, v98, v120
	v_add_u32_e32 v82, s6, v99
	s_lshl_b32 s10, s7, 1
	v_ashrrev_i32_e32 v83, 31, v82
	v_lshl_add_u64 v[80:81], v[10:11], 0, s[10:11]
	s_waitcnt vmcnt(15)
	ds_write_b32 v61, v94
	v_add_u32_e32 v61, v98, v121
	s_waitcnt vmcnt(14)
	ds_write_b32 v61, v95
	v_add_u32_e32 v61, v98, v122
	s_waitcnt vmcnt(13)
	ds_write_b32 v61, v96
	v_add_u32_e32 v61, v98, v123
	s_waitcnt vmcnt(12)
	ds_write_b32 v61, v97
	v_add_u32_e32 v61, v98, v124
	s_waitcnt vmcnt(11)
	ds_write_b32 v61, v137
	v_add_u32_e32 v61, v98, v125
	s_waitcnt vmcnt(10)
	ds_write_b32 v61, v138
	v_add_u32_e32 v61, v98, v126
	s_waitcnt vmcnt(9)
	ds_write_b32 v61, v76
	v_add_u32_e32 v61, v98, v127
	s_waitcnt vmcnt(8)
	ds_write_b32 v61, v74
	v_add_u32_e32 v61, v98, v128
	v_lshlrev_b64 v[82:83], 11, v[82:83]
	v_lshl_add_u64 v[82:83], v[80:81], 0, v[82:83]
	s_waitcnt vmcnt(7)
	ds_write_b32 v61, v75
	v_add_u32_e32 v61, v98, v129
	s_waitcnt vmcnt(6)
	ds_write_b32 v61, v77
	v_add_u32_e32 v61, v98, v130
	s_waitcnt vmcnt(5)
	ds_write_b32 v61, v68
	v_add_u32_e32 v61, v98, v131
	s_waitcnt vmcnt(4)
	ds_write_b32 v61, v66
	v_add_u32_e32 v61, v98, v132
	s_waitcnt vmcnt(3)
	ds_write_b32 v61, v67
	v_add_u32_e32 v61, v98, v133
	s_waitcnt vmcnt(2)
	ds_write_b32 v61, v69
	v_add_u32_e32 v61, v98, v134
	s_waitcnt vmcnt(1)
	ds_write_b32 v61, v64
	v_add_u32_e32 v61, v98, v135
	s_waitcnt vmcnt(0)
	ds_write_b32 v61, v60
	s_waitcnt lgkmcnt(0)
	ds_read2_b32 v[64:65], v100 offset0:33 offset1:41
	ds_read2_b32 v[66:67], v100 offset1:8
	ds_read2_b32 v[68:69], v100 offset0:66 offset1:74
	ds_read2_b32 v[70:71], v100 offset0:99 offset1:107
	ds_read2_b32 v[72:73], v100 offset0:132 offset1:140
	ds_read2_b32 v[74:75], v100 offset0:165 offset1:173
	ds_read2_b32 v[76:77], v100 offset0:198 offset1:206
	ds_read2_b32 v[78:79], v100 offset0:231 offset1:239
	s_waitcnt lgkmcnt(6)
	v_cvt_pk_bf16_f32 v60, v66, v64
	v_add_u32_e32 v64, s6, v101
	s_waitcnt lgkmcnt(4)
	v_cvt_pk_bf16_f32 v61, v68, v70
	s_waitcnt lgkmcnt(2)
	v_cvt_pk_bf16_f32 v62, v72, v74
	s_waitcnt lgkmcnt(0)
	v_cvt_pk_bf16_f32 v63, v76, v78
	global_store_dwordx4 v[82:83], v[60:63], off
	s_nop 1
	v_cvt_pk_bf16_f32 v60, v67, v65
	v_ashrrev_i32_e32 v65, 31, v64
	v_lshlrev_b64 v[64:65], 11, v[64:65]
	v_cvt_pk_bf16_f32 v61, v69, v71
	v_cvt_pk_bf16_f32 v62, v73, v75
	v_cvt_pk_bf16_f32 v63, v77, v79
	v_lshl_add_u64 v[64:65], v[80:81], 0, v[64:65]
	ds_read2_b32 v[66:67], v100 offset0:16 offset1:24
	ds_read2_b32 v[68:69], v100 offset0:49 offset1:57
	ds_read2_b32 v[70:71], v100 offset0:82 offset1:90
	ds_read2_b32 v[72:73], v100 offset0:115 offset1:123
	ds_read2_b32 v[74:75], v100 offset0:148 offset1:156
	ds_read2_b32 v[76:77], v100 offset0:181 offset1:189
	ds_read2_b32 v[78:79], v100 offset0:214 offset1:222
	ds_read2_b32 v[82:83], v100 offset0:247 offset1:255
	global_store_dwordx4 v[64:65], v[60:63], off
	v_add_u32_e32 v64, s6, v102
	v_ashrrev_i32_e32 v65, 31, v64
	v_lshlrev_b64 v[64:65], 11, v[64:65]
	v_lshl_add_u64 v[64:65], v[80:81], 0, v[64:65]
	s_waitcnt lgkmcnt(6)
	v_cvt_pk_bf16_f32 v60, v66, v68
	s_waitcnt lgkmcnt(4)
	v_cvt_pk_bf16_f32 v61, v70, v72
	s_waitcnt lgkmcnt(2)
	v_cvt_pk_bf16_f32 v62, v74, v76
	s_waitcnt lgkmcnt(0)
	v_cvt_pk_bf16_f32 v63, v78, v82
	global_store_dwordx4 v[64:65], v[60:63], off
	v_add_u32_e32 v64, s6, v103
	v_ashrrev_i32_e32 v65, 31, v64
	v_lshlrev_b64 v[64:65], 11, v[64:65]
	v_lshl_add_u64 v[64:65], v[80:81], 0, v[64:65]
	v_cvt_pk_bf16_f32 v60, v67, v69
	v_cvt_pk_bf16_f32 v61, v71, v73
	v_cvt_pk_bf16_f32 v62, v75, v77
	v_cvt_pk_bf16_f32 v63, v79, v83
	global_store_dwordx4 v[64:65], v[60:63], off
	s_waitcnt lgkmcnt(0)

; template <bool GU>
; __device__ __forceinline__ void transpose_item(const float* W, int K, int N, bf16* WT, const float* gs, LAS float* scr, int item, int lane) {
;     ...
; #pragma unroll 16
;     for (int i = 0; i < 32; ++i) { const int kk = 2 * i + (lane >> 5); float w = W[(size_t)(k0 + kk) * N + n0 + (lane & 31)]; if (gs) w *= gs[k0 + kk]; scr[kk * 33 + (lane & 31)] = w; }
.LBB0_539:
	global_load_dword v68, v[66:67], off nt
	v_cndmask_b32_e64 v69, 0, 1, s[14:15]
	v_cmp_ne_u32_e64 s[6:7], 1, v69
	s_andn2_b64 vcc, exec, s[14:15]
	s_cbranch_vccnz .LBB0_541
	v_lshl_add_u64 v[72:73], v[64:65], 0, s[52:53]
	global_load_dword v69, v[72:73], off nt
	s_waitcnt vmcnt(0)
	v_mul_f32_e32 v68, v68, v69
.LBB0_541:
	s_waitcnt vmcnt(0)
	ds_write_b32 v71, v68
	v_subrev_u32_e32 v68, 28, v70
	v_mad_i64_i32 v[68:69], s[36:37], v68, s5, v[60:61]
	global_load_dword v72, v[68:69], off nt
	s_and_b64 vcc, exec, s[6:7]
	v_lshl_add_u64 v[68:69], v[62:63], 0, s[52:53]
	s_cbranch_vccnz .LBB0_543
	global_load_dword v73, v[68:69], off offset:8
	s_waitcnt vmcnt(0)
	v_mul_f32_e32 v72, v72, v73
.LBB0_543:
	s_waitcnt vmcnt(0)
	ds_write_b32 v71, v72 offset:264
	v_subrev_u32_e32 v72, 26, v70
	v_mad_i64_i32 v[72:73], s[36:37], v72, s5, v[60:61]
	global_load_dword v72, v[72:73], off nt
	s_and_b64 vcc, exec, s[6:7]
	s_cbranch_vccnz .LBB0_545
	global_load_dword v73, v[68:69], off offset:16
	s_waitcnt vmcnt(0)
	v_mul_f32_e32 v72, v72, v73
.LBB0_545:
	s_waitcnt vmcnt(0)
	ds_write_b32 v71, v72 offset:528
	v_subrev_u32_e32 v72, 24, v70
	v_mad_i64_i32 v[72:73], s[36:37], v72, s5, v[60:61]
	global_load_dword v72, v[72:73], off nt
	s_and_b64 vcc, exec, s[6:7]
	s_cbranch_vccnz .LBB0_547
	global_load_dword v73, v[68:69], off offset:24
	s_waitcnt vmcnt(0)
	v_mul_f32_e32 v72, v72, v73
.LBB0_547:
	s_waitcnt vmcnt(0)
	ds_write_b32 v71, v72 offset:792
	v_subrev_u32_e32 v72, 22, v70
	v_mad_i64_i32 v[72:73], s[36:37], v72, s5, v[60:61]
	global_load_dword v72, v[72:73], off nt
	s_and_b64 vcc, exec, s[6:7]
	s_cbranch_vccnz .LBB0_549
	global_load_dword v73, v[68:69], off offset:32
	s_waitcnt vmcnt(0)
	v_mul_f32_e32 v72, v72, v73
.LBB0_549:
	s_waitcnt vmcnt(0)
	ds_write_b32 v71, v72 offset:1056
	v_subrev_u32_e32 v72, 20, v70
	v_mad_i64_i32 v[72:73], s[36:37], v72, s5, v[60:61]
	global_load_dword v72, v[72:73], off nt
	s_and_b64 vcc, exec, s[6:7]
	s_cbranch_vccnz .LBB0_551
	global_load_dword v73, v[68:69], off offset:40
	s_waitcnt vmcnt(0)
	v_mul_f32_e32 v72, v72, v73
.LBB0_551:
	s_waitcnt vmcnt(0)
	ds_write_b32 v71, v72 offset:1320
	v_subrev_u32_e32 v72, 18, v70
	v_mad_i64_i32 v[72:73], s[36:37], v72, s5, v[60:61]
	global_load_dword v72, v[72:73], off nt
	s_and_b64 vcc, exec, s[6:7]
	s_cbranch_vccnz .LBB0_553
	global_load_dword v73, v[68:69], off offset:48
	s_waitcnt vmcnt(0)
	v_mul_f32_e32 v72, v72, v73
.LBB0_553:
	s_waitcnt vmcnt(0)
	ds_write_b32 v71, v72 offset:1584
	v_add_u32_e32 v72, -16, v70
	v_mad_i64_i32 v[72:73], s[36:37], v72, s5, v[60:61]
	global_load_dword v72, v[72:73], off nt
	s_and_b64 vcc, exec, s[6:7]
	s_cbranch_vccnz .LBB0_555
	global_load_dword v73, v[68:69], off offset:56
	s_waitcnt vmcnt(0)
	v_mul_f32_e32 v72, v72, v73
.LBB0_555:
	s_waitcnt vmcnt(0)
	ds_write_b32 v71, v72 offset:1848
	v_add_u32_e32 v72, -14, v70
	v_mad_i64_i32 v[72:73], s[36:37], v72, s5, v[60:61]
	global_load_dword v72, v[72:73], off nt
	s_and_b64 vcc, exec, s[6:7]
	s_cbranch_vccnz .LBB0_557
	global_load_dword v73, v[68:69], off offset:64
	s_waitcnt vmcnt(0)
	v_mul_f32_e32 v72, v72, v73
.LBB0_557:
	s_waitcnt vmcnt(0)
	ds_write_b32 v71, v72 offset:2112
	v_add_u32_e32 v72, -12, v70
	v_mad_i64_i32 v[72:73], s[36:37], v72, s5, v[60:61]
	global_load_dword v72, v[72:73], off nt
	s_and_b64 vcc, exec, s[6:7]
	s_cbranch_vccnz .LBB0_559
	global_load_dword v73, v[68:69], off offset:72
	s_waitcnt vmcnt(0)
	v_mul_f32_e32 v72, v72, v73
.LBB0_559:
	s_waitcnt vmcnt(0)
	ds_write_b32 v71, v72 offset:2376
	v_add_u32_e32 v72, -10, v70
	v_mad_i64_i32 v[72:73], s[36:37], v72, s5, v[60:61]
	global_load_dword v72, v[72:73], off nt
	s_and_b64 vcc, exec, s[6:7]
	s_cbranch_vccnz .LBB0_561
	global_load_dword v73, v[68:69], off offset:80
	s_waitcnt vmcnt(0)
	v_mul_f32_e32 v72, v72, v73
.LBB0_561:
	s_waitcnt vmcnt(0)
	ds_write_b32 v71, v72 offset:2640
	v_add_u32_e32 v72, -8, v70
	v_mad_i64_i32 v[72:73], s[36:37], v72, s5, v[60:61]
	global_load_dword v72, v[72:73], off nt
	s_and_b64 vcc, exec, s[6:7]
	s_cbranch_vccnz .LBB0_563
	global_load_dword v73, v[68:69], off offset:88
	s_waitcnt vmcnt(0)
	v_mul_f32_e32 v72, v72, v73
.LBB0_563:
	s_waitcnt vmcnt(0)
	ds_write_b32 v71, v72 offset:2904
	v_add_u32_e32 v72, -6, v70
	v_mad_i64_i32 v[72:73], s[36:37], v72, s5, v[60:61]
	global_load_dword v72, v[72:73], off nt
	s_and_b64 vcc, exec, s[6:7]
	s_cbranch_vccnz .LBB0_565
	global_load_dword v73, v[68:69], off offset:96
	s_waitcnt vmcnt(0)
	v_mul_f32_e32 v72, v72, v73
.LBB0_565:
	s_waitcnt vmcnt(0)
	ds_write_b32 v71, v72 offset:3168
	v_add_u32_e32 v72, -4, v70
	v_mad_i64_i32 v[72:73], s[36:37], v72, s5, v[60:61]
	global_load_dword v72, v[72:73], off nt
	s_and_b64 vcc, exec, s[6:7]
	s_cbranch_vccnz .LBB0_567
	global_load_dword v73, v[68:69], off offset:104
	s_waitcnt vmcnt(0)
	v_mul_f32_e32 v72, v72, v73
.LBB0_567:
	s_waitcnt vmcnt(0)
	ds_write_b32 v71, v72 offset:3432
	v_add_u32_e32 v72, -2, v70
	v_mad_i64_i32 v[72:73], s[36:37], v72, s5, v[60:61]
	global_load_dword v72, v[72:73], off nt
	s_and_b64 vcc, exec, s[6:7]
	s_cbranch_vccnz .LBB0_569
	global_load_dword v73, v[68:69], off offset:112
	s_waitcnt vmcnt(0)
	v_mul_f32_e32 v72, v72, v73
.LBB0_569:
	s_waitcnt vmcnt(0)
	ds_write_b32 v71, v72 offset:3696
	v_mad_i64_i32 v[72:73], s[36:37], v70, s5, v[60:61]
	global_load_dword v72, v[72:73], off nt
	s_and_b64 vcc, exec, s[6:7]
	s_cbranch_vccnz .LBB0_538
	global_load_dword v68, v[68:69], off offset:120
	s_waitcnt vmcnt(0)
	v_mul_f32_e32 v72, v72, v68
	s_branch .LBB0_538

; template <bool GU>
; __device__ __forceinline__ void transpose_item(const float* W, int K, int N, bf16* WT, const float* gs, LAS float* scr, int item, int lane) {
;     const int nblk = N / 32, kb = item / nblk, nb = item % nblk, k0 = 64 * kb, n0 = 32 * nb;
; #pragma unroll 16
;     for (int i = 0; i < 32; ++i) { const int kk = 2 * i + (lane >> 5); float w = W[(size_t)(k0 + kk) * N + n0 + (lane & 31)]; if (gs) w *= gs[k0 + kk]; scr[kk * 33 + (lane & 31)] = w; }
; __device__ __forceinline__ void conv_weights(LAS unsigned char* lds, unsigned char* ws, const PIn& I, const int l, const int wave, const int lane, const int gw, const int NGW, const int r_lo, const int r_hi) {
;     ...
;         transpose_item<false>(I.w_pg + (size_t)l * DM * DM, DM, DM, (bf16*)(wb + W_PG), nullptr, scr, r, lane);
.LBB0_707:
	s_cmpk_gt_u32 s0, 0x67f
	s_cbranch_scc0 .LBB0_755
	s_cmpk_gt_u32 s0, 0x117f
	s_cbranch_scc0 .LBB0_718
	s_cmpk_gt_u32 s0, 0x16ff
	s_cbranch_scc0 .LBB0_715
	s_lshl_b32 s40, s0, 1
	s_cmpk_gt_u32 s0, 0x177f
	s_cbranch_scc0 .LBB0_712
	s_add_i32 s6, s40, 0x1d100
	s_and_b32 s7, s6, 0x1ffc0
	s_lshl_b32 s6, s0, 5
	s_and_b32 s6, s6, 0x3e0
	v_add_u32_e32 v66, s7, v0
	s_lshl_b32 s10, s6, 2
	v_add_u32_e32 v64, s7, v1
	v_ashrrev_i32_e32 v67, 31, v66
	v_add_u32_e32 v68, s7, v27
	v_add_u32_e32 v70, s7, v26
	v_add_u32_e32 v72, s7, v29
	v_add_u32_e32 v74, s7, v28
	v_add_u32_e32 v76, s7, v31
	v_add_u32_e32 v78, s7, v30
	v_lshl_add_u64 v[62:63], v[16:17], 0, s[10:11]
	v_ashrrev_i32_e32 v65, 31, v64
	v_lshlrev_b64 v[66:67], 12, v[66:67]
	v_ashrrev_i32_e32 v71, 31, v70
	v_ashrrev_i32_e32 v69, 31, v68
	v_ashrrev_i32_e32 v75, 31, v74
	v_ashrrev_i32_e32 v73, 31, v72
	v_ashrrev_i32_e32 v79, 31, v78
	v_ashrrev_i32_e32 v77, 31, v76
	v_lshlrev_b64 v[64:65], 12, v[64:65]
	v_lshl_add_u64 v[66:67], v[62:63], 0, v[66:67]
	v_lshlrev_b64 v[68:69], 12, v[68:69]
	v_lshlrev_b64 v[70:71], 12, v[70:71]
	v_lshlrev_b64 v[72:73], 12, v[72:73]
	v_lshlrev_b64 v[74:75], 12, v[74:75]
	v_lshlrev_b64 v[76:77], 12, v[76:77]
	v_lshlrev_b64 v[78:79], 12, v[78:79]
	v_lshl_add_u64 v[64:65], v[62:63], 0, v[64:65]
	v_lshl_add_u64 v[70:71], v[62:63], 0, v[70:71]
	v_lshl_add_u64 v[68:69], v[62:63], 0, v[68:69]
	v_lshl_add_u64 v[74:75], v[62:63], 0, v[74:75]
	v_lshl_add_u64 v[72:73], v[62:63], 0, v[72:73]
	v_lshl_add_u64 v[78:79], v[62:63], 0, v[78:79]
	v_lshl_add_u64 v[76:77], v[62:63], 0, v[76:77]
	global_load_dword v80, v[66:67], off nt
	global_load_dword v81, v[64:65], off nt
	global_load_dword v82, v[70:71], off nt
	global_load_dword v83, v[68:69], off nt
	global_load_dword v84, v[74:75], off nt
	global_load_dword v85, v[72:73], off nt
	global_load_dword v86, v[78:79], off nt
	global_load_dword v87, v[76:77], off nt
	v_add_u32_e32 v66, s7, v32
	v_add_u32_e32 v64, s7, v33
	v_ashrrev_i32_e32 v67, 31, v66
	v_add_u32_e32 v68, s7, v35
	v_add_u32_e32 v70, s7, v34
	v_add_u32_e32 v72, s7, v37
	v_add_u32_e32 v74, s7, v36
	v_add_u32_e32 v76, s7, v39
	v_add_u32_e32 v78, s7, v38
	v_ashrrev_i32_e32 v65, 31, v64
	v_lshlrev_b64 v[66:67], 12, v[66:67]
	v_ashrrev_i32_e32 v71, 31, v70
	v_ashrrev_i32_e32 v69, 31, v68
	v_ashrrev_i32_e32 v75, 31, v74
	v_ashrrev_i32_e32 v73, 31, v72
	v_ashrrev_i32_e32 v79, 31, v78
	v_ashrrev_i32_e32 v77, 31, v76
	v_lshlrev_b64 v[64:65], 12, v[64:65]
	v_lshl_add_u64 v[66:67], v[62:63], 0, v[66:67]
	v_lshlrev_b64 v[68:69], 12, v[68:69]
	v_lshlrev_b64 v[70:71], 12, v[70:71]
	v_lshlrev_b64 v[72:73], 12, v[72:73]
	v_lshlrev_b64 v[74:75], 12, v[74:75]
	v_lshlrev_b64 v[76:77], 12, v[76:77]
	v_lshlrev_b64 v[78:79], 12, v[78:79]
	v_lshl_add_u64 v[64:65], v[62:63], 0, v[64:65]
	v_lshl_add_u64 v[70:71], v[62:63], 0, v[70:71]
	v_lshl_add_u64 v[68:69], v[62:63], 0, v[68:69]
	v_lshl_add_u64 v[74:75], v[62:63], 0, v[74:75]
	v_lshl_add_u64 v[72:73], v[62:63], 0, v[72:73]
	v_lshl_add_u64 v[78:79], v[62:63], 0, v[78:79]
	v_lshl_add_u64 v[76:77], v[62:63], 0, v[76:77]
	global_load_dword v88, v[66:67], off nt
	global_load_dword v89, v[64:65], off nt
	global_load_dword v90, v[70:71], off nt
	global_load_dword v91, v[68:69], off nt
	global_load_dword v92, v[74:75], off nt
	global_load_dword v93, v[72:73], off nt
	global_load_dword v94, v[78:79], off nt
	global_load_dword v95, v[76:77], off nt
	v_add_u32_e32 v66, s7, v40
	v_add_u32_e32 v68, s7, v43
	v_add_u32_e32 v70, s7, v42
	v_add_u32_e32 v76, s7, v47
	v_add_u32_e32 v78, s7, v46
	v_add_u32_e32 v64, s7, v41
	v_ashrrev_i32_e32 v67, 31, v66
	v_ashrrev_i32_e32 v71, 31, v70
	v_ashrrev_i32_e32 v69, 31, v68
	v_add_u32_e32 v72, s7, v45
	v_add_u32_e32 v74, s7, v44
	v_ashrrev_i32_e32 v79, 31, v78
	v_ashrrev_i32_e32 v77, 31, v76
	v_ashrrev_i32_e32 v65, 31, v64
	v_lshlrev_b64 v[66:67], 12, v[66:67]
	v_lshlrev_b64 v[68:69], 12, v[68:69]
	v_lshlrev_b64 v[70:71], 12, v[70:71]
	v_ashrrev_i32_e32 v75, 31, v74
	v_ashrrev_i32_e32 v73, 31, v72
	v_lshlrev_b64 v[76:77], 12, v[76:77]
	v_lshlrev_b64 v[78:79], 12, v[78:79]
	v_lshlrev_b64 v[64:65], 12, v[64:65]
	v_lshl_add_u64 v[66:67], v[62:63], 0, v[66:67]
	v_lshl_add_u64 v[70:71], v[62:63], 0, v[70:71]
	v_lshl_add_u64 v[68:69], v[62:63], 0, v[68:69]
	v_lshlrev_b64 v[72:73], 12, v[72:73]
	v_lshlrev_b64 v[74:75], 12, v[74:75]
	v_lshl_add_u64 v[78:79], v[62:63], 0, v[78:79]
	v_lshl_add_u64 v[76:77], v[62:63], 0, v[76:77]
	v_lshl_add_u64 v[64:65], v[62:63], 0, v[64:65]
	v_lshl_add_u64 v[74:75], v[62:63], 0, v[74:75]
	v_lshl_add_u64 v[72:73], v[62:63], 0, v[72:73]
	global_load_dword v96, v[66:67], off nt
	global_load_dword v97, v[64:65], off nt
	global_load_dword v98, v[70:71], off nt
	global_load_dword v99, v[68:69], off nt
	global_load_dword v100, v[74:75], off nt
	global_load_dword v101, v[72:73], off nt
	s_nop 0
	global_load_dword v78, v[78:79], off nt
	s_nop 0
	global_load_dword v76, v[76:77], off nt
	v_add_u32_e32 v66, s7, v48
	v_add_u32_e32 v68, s7, v51
	v_add_u32_e32 v70, s7, v50
	v_add_u32_e32 v64, s7, v49
	v_ashrrev_i32_e32 v67, 31, v66
	v_ashrrev_i32_e32 v71, 31, v70
	v_ashrrev_i32_e32 v69, 31, v68
	v_add_u32_e32 v72, s7, v53
	v_add_u32_e32 v74, s7, v52
	v_ashrrev_i32_e32 v65, 31, v64
	v_lshlrev_b64 v[66:67], 12, v[66:67]
	v_lshlrev_b64 v[68:69], 12, v[68:69]
	v_lshlrev_b64 v[70:71], 12, v[70:71]
	v_ashrrev_i32_e32 v75, 31, v74
	v_ashrrev_i32_e32 v73, 31, v72
	v_lshlrev_b64 v[64:65], 12, v[64:65]
	v_lshl_add_u64 v[66:67], v[62:63], 0, v[66:67]
	v_lshl_add_u64 v[70:71], v[62:63], 0, v[70:71]
	v_lshl_add_u64 v[68:69], v[62:63], 0, v[68:69]
	v_lshlrev_b64 v[72:73], 12, v[72:73]
	v_lshlrev_b64 v[74:75], 12, v[74:75]
	v_lshl_add_u64 v[64:65], v[62:63], 0, v[64:65]
	v_lshl_add_u64 v[74:75], v[62:63], 0, v[74:75]
	v_lshl_add_u64 v[72:73], v[62:63], 0, v[72:73]
	global_load_dword v77, v[66:67], off nt
	global_load_dword v79, v[64:65], off nt
	s_nop 0
	global_load_dword v70, v[70:71], off nt
	s_nop 0
	global_load_dword v68, v[68:69], off nt
	s_nop 0
	global_load_dword v69, v[74:75], off nt
	global_load_dword v71, v[72:73], off nt
	v_add_u32_e32 v66, s7, v54
	v_add_u32_e32 v64, s7, v55
	v_ashrrev_i32_e32 v67, 31, v66
	v_ashrrev_i32_e32 v65, 31, v64
	v_lshlrev_b64 v[66:67], 12, v[66:67]
	v_lshlrev_b64 v[64:65], 12, v[64:65]
	v_lshl_add_u64 v[66:67], v[62:63], 0, v[66:67]
	global_load_dword v66, v[66:67], off nt
	v_lshl_add_u64 v[62:63], v[62:63], 0, v[64:65]
	global_load_dword v62, v[62:63], off nt
	v_add_u32_e32 v63, v126, v132
	s_waitcnt vmcnt(31)
; #define LAS __attribute__((address_space(3)))
; __device__ __forceinline__ unsigned cvt_pk(float lo, float hi) { unsigned r; asm("v_cvt_pk_bf16_f32 %0, %1, %2" : "=v"(r) : "v"(lo), "v"(hi)); return r; }
; template <bool GU>
; __device__ __forceinline__ void transpose_item(const float* W, int K, int N, bf16* WT, const float* gs, LAS float* scr, int item, int lane) {
;     ...
;     for (int i = 0; i < 32; ++i) { const int kk = 2 * i + (lane >> 5); float w = W[(size_t)(k0 + kk) * N + n0 + (lane & 31)]; if (gs) w *= gs[k0 + kk]; scr[kk * 33 + (lane & 31)] = w; }
;     asm volatile("s_waitcnt lgkmcnt(0)" ::: "memory");
;     int d0 = n0;
;     if (GU) { const int f = (n0 < FF) ? n0 : n0 - FF; d0 = 256 * (f >> 7) + (f & 127) + ((n0 < FF) ? 0 : 128); }
;     const int c = lane & 7;
; #pragma unroll
;     for (int j = 0; j < 4; ++j) { const int n = (lane >> 3) + 8 * j; const LAS float* s = scr + (8 * c) * 33 + n;
;         v4u o; o.x = cvt_pk(s[0 * 33], s[1 * 33]); o.y = cvt_pk(s[2 * 33], s[3 * 33]); o.z = cvt_pk(s[4 * 33], s[5 * 33]); o.w = cvt_pk(s[6 * 33], s[7 * 33]);
;         *(v4u*)(WT + (size_t)(d0 + n) * K + k0 + 8 * c) = o; }
;     asm volatile("s_waitcnt lgkmcnt(0)" ::: "memory");
	ds_write_b32 v63, v80
	v_add_u32_e32 v63, v126, v133
	s_waitcnt vmcnt(30)
	ds_write_b32 v63, v81
	v_add_u32_e32 v63, v126, v134
	s_waitcnt vmcnt(29)
	ds_write_b32 v63, v82
	v_add_u32_e32 v63, v126, v135
	s_waitcnt vmcnt(28)
	ds_write_b32 v63, v83
	v_add_u32_e32 v63, v126, v136
	s_waitcnt vmcnt(27)
	ds_write_b32 v63, v84
	v_add_u32_e32 v63, v126, v137
	s_waitcnt vmcnt(26)
	ds_write_b32 v63, v85
	v_add_u32_e32 v63, v126, v138
	s_waitcnt vmcnt(25)
	ds_write_b32 v63, v86
	v_add_u32_e32 v63, v126, v139
	s_waitcnt vmcnt(24)
	ds_write_b32 v63, v87
	v_add_u32_e32 v63, v126, v140
	s_waitcnt vmcnt(23)
	ds_write_b32 v63, v88
	v_add_u32_e32 v63, v126, v141
	s_waitcnt vmcnt(22)
	ds_write_b32 v63, v89
	v_add_u32_e32 v63, v126, v142
	s_waitcnt vmcnt(21)
	ds_write_b32 v63, v90
	v_add_u32_e32 v63, v126, v143
	s_waitcnt vmcnt(20)
	ds_write_b32 v63, v91
	v_add_u32_e32 v63, v126, v144
	s_waitcnt vmcnt(19)
	ds_write_b32 v63, v92
	v_add_u32_e32 v63, v126, v145
	s_waitcnt vmcnt(18)
	ds_write_b32 v63, v93
	v_add_u32_e32 v63, v126, v146
	s_waitcnt vmcnt(17)
	ds_write_b32 v63, v94
	v_add_u32_e32 v63, v126, v147
	s_waitcnt vmcnt(16)
	ds_write_b32 v63, v95
	v_add_u32_e32 v63, v126, v148
	v_add_u32_e32 v84, s6, v127
	s_lshl_b32 s10, s7, 1
	v_ashrrev_i32_e32 v85, 31, v84
	v_lshl_add_u64 v[82:83], v[4:5], 0, s[10:11]
	s_waitcnt vmcnt(15)
	ds_write_b32 v63, v96
	v_add_u32_e32 v63, v126, v149
	s_waitcnt vmcnt(14)
	ds_write_b32 v63, v97
	v_add_u32_e32 v63, v126, v150
	s_waitcnt vmcnt(13)
	ds_write_b32 v63, v98
	v_add_u32_e32 v63, v126, v151
	s_waitcnt vmcnt(12)
	ds_write_b32 v63, v99
	v_add_u32_e32 v63, v126, v152
	s_waitcnt vmcnt(11)
	ds_write_b32 v63, v100
	v_add_u32_e32 v63, v126, v153
	s_waitcnt vmcnt(10)
	ds_write_b32 v63, v101
	v_add_u32_e32 v63, v126, v154
	s_waitcnt vmcnt(9)
	ds_write_b32 v63, v78
	v_add_u32_e32 v63, v126, v155
	s_waitcnt vmcnt(8)
	ds_write_b32 v63, v76
	v_add_u32_e32 v63, v126, v156
	v_lshlrev_b64 v[84:85], 11, v[84:85]
	v_lshl_add_u64 v[84:85], v[82:83], 0, v[84:85]
	s_waitcnt vmcnt(7)
	ds_write_b32 v63, v77
	v_add_u32_e32 v63, v126, v157
	s_waitcnt vmcnt(6)
	ds_write_b32 v63, v79
	v_add_u32_e32 v63, v126, v158
	s_waitcnt vmcnt(5)
	ds_write_b32 v63, v70
	v_add_u32_e32 v63, v126, v159
	s_waitcnt vmcnt(4)
	ds_write_b32 v63, v68
	v_add_u32_e32 v63, v126, v160
	s_waitcnt vmcnt(3)
	ds_write_b32 v63, v69
	v_add_u32_e32 v63, v126, v161
	s_waitcnt vmcnt(2)
	ds_write_b32 v63, v71
	v_add_u32_e32 v63, v126, v162
	s_waitcnt vmcnt(1)
	ds_write_b32 v63, v66
	v_add_u32_e32 v63, v126, v163
	s_waitcnt vmcnt(0)
	ds_write_b32 v63, v62
	s_waitcnt lgkmcnt(0)
	ds_read2_b32 v[66:67], v128 offset0:33 offset1:41
	ds_read2_b32 v[68:69], v128 offset1:8
	ds_read2_b32 v[70:71], v128 offset0:66 offset1:74
	ds_read2_b32 v[72:73], v128 offset0:99 offset1:107
	ds_read2_b32 v[74:75], v128 offset0:132 offset1:140
	ds_read2_b32 v[76:77], v128 offset0:165 offset1:173
	ds_read2_b32 v[78:79], v128 offset0:198 offset1:206
	ds_read2_b32 v[80:81], v128 offset0:231 offset1:239
	s_waitcnt lgkmcnt(6)
	v_cvt_pk_bf16_f32 v62, v68, v66
	v_add_u32_e32 v66, s6, v129
	s_waitcnt lgkmcnt(4)
	v_cvt_pk_bf16_f32 v63, v70, v72
	s_waitcnt lgkmcnt(2)
	v_cvt_pk_bf16_f32 v64, v74, v76
	s_waitcnt lgkmcnt(0)
	v_cvt_pk_bf16_f32 v65, v78, v80
	global_store_dwordx4 v[84:85], v[62:65], off
	s_nop 1
	v_cvt_pk_bf16_f32 v62, v69, v67
	v_ashrrev_i32_e32 v67, 31, v66
	v_lshlrev_b64 v[66:67], 11, v[66:67]
	v_cvt_pk_bf16_f32 v63, v71, v73
	v_cvt_pk_bf16_f32 v64, v75, v77
	v_cvt_pk_bf16_f32 v65, v79, v81
	v_lshl_add_u64 v[66:67], v[82:83], 0, v[66:67]
	ds_read2_b32 v[68:69], v128 offset0:16 offset1:24
	ds_read2_b32 v[70:71], v128 offset0:49 offset1:57
	ds_read2_b32 v[72:73], v128 offset0:82 offset1:90
	ds_read2_b32 v[74:75], v128 offset0:115 offset1:123
	ds_read2_b32 v[76:77], v128 offset0:148 offset1:156
	ds_read2_b32 v[78:79], v128 offset0:181 offset1:189
	ds_read2_b32 v[80:81], v128 offset0:214 offset1:222
	ds_read2_b32 v[84:85], v128 offset0:247 offset1:255
	global_store_dwordx4 v[66:67], v[62:65], off
	v_add_u32_e32 v66, s6, v130
	v_ashrrev_i32_e32 v67, 31, v66
	v_lshlrev_b64 v[66:67], 11, v[66:67]
	v_lshl_add_u64 v[66:67], v[82:83], 0, v[66:67]
	s_waitcnt lgkmcnt(6)
	v_cvt_pk_bf16_f32 v62, v68, v70
	s_waitcnt lgkmcnt(4)
	v_cvt_pk_bf16_f32 v63, v72, v74
	s_waitcnt lgkmcnt(2)
	v_cvt_pk_bf16_f32 v64, v76, v78
	s_waitcnt lgkmcnt(0)
	v_cvt_pk_bf16_f32 v65, v80, v84
	global_store_dwordx4 v[66:67], v[62:65], off
	v_add_u32_e32 v66, s6, v131
	v_ashrrev_i32_e32 v67, 31, v66
	v_lshlrev_b64 v[66:67], 11, v[66:67]
	v_lshl_add_u64 v[66:67], v[82:83], 0, v[66:67]
	v_cvt_pk_bf16_f32 v62, v69, v71
	v_cvt_pk_bf16_f32 v63, v73, v75
	v_cvt_pk_bf16_f32 v64, v77, v79
	v_cvt_pk_bf16_f32 v65, v81, v85
	global_store_dwordx4 v[66:67], v[62:65], off
	s_waitcnt lgkmcnt(0)
	s_mov_b64 s[6:7], 0
; template <bool GU>
; __device__ __forceinline__ void transpose_item(const float* W, int K, int N, bf16* WT, const float* gs, LAS float* scr, int item, int lane) {
;     const int nblk = N / 32, kb = item / nblk, nb = item % nblk, k0 = 64 * kb, n0 = 32 * nb;
; #pragma unroll 16
;     for (int i = 0; i < 32; ++i) { const int kk = 2 * i + (lane >> 5); float w = W[(size_t)(k0 + kk) * N + n0 + (lane & 31)]; if (gs) w *= gs[k0 + kk]; scr[kk * 33 + (lane & 31)] = w; }
; __device__ __forceinline__ void conv_weights(LAS unsigned char* lds, unsigned char* ws, const PIn& I, const int l, const int wave, const int lane, const int gw, const int NGW, const int r_lo, const int r_hi) {
;     ...
;         if (r < I_PP) { transpose_item<false>(I.w_pp + (size_t)l * DPLE * DM, DPLE, DM, (bf16*)(wb + W_PP), nullptr, scr, r, lane); continue; } r -= I_PP;
.LBB0_712:
	s_andn2_b64 vcc, exec, s[6:7]
	s_cbranch_vccnz .LBB0_714
	s_and_b32 s7, s40, 0x1c0
	s_lshl_b32 s6, s0, 5
	s_and_b32 s6, s6, 0x3e0
	v_add_u32_e32 v66, s7, v0
	s_lshl_b32 s10, s6, 2
	v_add_u32_e32 v64, s7, v1
	v_ashrrev_i32_e32 v67, 31, v66
	v_add_u32_e32 v68, s7, v27
	v_add_u32_e32 v70, s7, v26
	v_add_u32_e32 v72, s7, v29
	v_add_u32_e32 v74, s7, v28
	v_add_u32_e32 v76, s7, v31
	v_add_u32_e32 v78, s7, v30
	v_lshl_add_u64 v[62:63], v[18:19], 0, s[10:11]
	v_ashrrev_i32_e32 v65, 31, v64
	v_lshlrev_b64 v[66:67], 12, v[66:67]
	v_ashrrev_i32_e32 v71, 31, v70
	v_ashrrev_i32_e32 v69, 31, v68
	v_ashrrev_i32_e32 v75, 31, v74
	v_ashrrev_i32_e32 v73, 31, v72
	v_ashrrev_i32_e32 v79, 31, v78
	v_ashrrev_i32_e32 v77, 31, v76
	v_lshlrev_b64 v[64:65], 12, v[64:65]
	v_lshl_add_u64 v[66:67], v[62:63], 0, v[66:67]
	v_lshlrev_b64 v[68:69], 12, v[68:69]
	v_lshlrev_b64 v[70:71], 12, v[70:71]
	v_lshlrev_b64 v[72:73], 12, v[72:73]
	v_lshlrev_b64 v[74:75], 12, v[74:75]
	v_lshlrev_b64 v[76:77], 12, v[76:77]
	v_lshlrev_b64 v[78:79], 12, v[78:79]
	v_lshl_add_u64 v[64:65], v[62:63], 0, v[64:65]
	v_lshl_add_u64 v[70:71], v[62:63], 0, v[70:71]
	v_lshl_add_u64 v[68:69], v[62:63], 0, v[68:69]
	v_lshl_add_u64 v[74:75], v[62:63], 0, v[74:75]
	v_lshl_add_u64 v[72:73], v[62:63], 0, v[72:73]
	v_lshl_add_u64 v[78:79], v[62:63], 0, v[78:79]
	v_lshl_add_u64 v[76:77], v[62:63], 0, v[76:77]
	global_load_dword v80, v[66:67], off nt
	global_load_dword v81, v[64:65], off nt
	global_load_dword v82, v[70:71], off nt
	global_load_dword v83, v[68:69], off nt
	global_load_dword v84, v[74:75], off nt
	global_load_dword v85, v[72:73], off nt
	global_load_dword v86, v[78:79], off nt
	global_load_dword v87, v[76:77], off nt
	v_add_u32_e32 v66, s7, v32
	v_add_u32_e32 v64, s7, v33
	v_ashrrev_i32_e32 v67, 31, v66
	v_add_u32_e32 v68, s7, v35
	v_add_u32_e32 v70, s7, v34
	v_add_u32_e32 v72, s7, v37
	v_add_u32_e32 v74, s7, v36
	v_add_u32_e32 v76, s7, v39
	v_add_u32_e32 v78, s7, v38
	v_ashrrev_i32_e32 v65, 31, v64
	v_lshlrev_b64 v[66:67], 12, v[66:67]
	v_ashrrev_i32_e32 v71, 31, v70
	v_ashrrev_i32_e32 v69, 31, v68
	v_ashrrev_i32_e32 v75, 31, v74
	v_ashrrev_i32_e32 v73, 31, v72
	v_ashrrev_i32_e32 v79, 31, v78
	v_ashrrev_i32_e32 v77, 31, v76
	v_lshlrev_b64 v[64:65], 12, v[64:65]
	v_lshl_add_u64 v[66:67], v[62:63], 0, v[66:67]
	v_lshlrev_b64 v[68:69], 12, v[68:69]
	v_lshlrev_b64 v[70:71], 12, v[70:71]
	v_lshlrev_b64 v[72:73], 12, v[72:73]
	v_lshlrev_b64 v[74:75], 12, v[74:75]
	v_lshlrev_b64 v[76:77], 12, v[76:77]
	v_lshlrev_b64 v[78:79], 12, v[78:79]
	v_lshl_add_u64 v[64:65], v[62:63], 0, v[64:65]
	v_lshl_add_u64 v[70:71], v[62:63], 0, v[70:71]
	v_lshl_add_u64 v[68:69], v[62:63], 0, v[68:69]
	v_lshl_add_u64 v[74:75], v[62:63], 0, v[74:75]
	v_lshl_add_u64 v[72:73], v[62:63], 0, v[72:73]
	v_lshl_add_u64 v[78:79], v[62:63], 0, v[78:79]
	v_lshl_add_u64 v[76:77], v[62:63], 0, v[76:77]
	global_load_dword v88, v[66:67], off nt
	global_load_dword v89, v[64:65], off nt
	global_load_dword v90, v[70:71], off nt
	global_load_dword v91, v[68:69], off nt
	global_load_dword v92, v[74:75], off nt
	global_load_dword v93, v[72:73], off nt
	global_load_dword v94, v[78:79], off nt
	global_load_dword v95, v[76:77], off nt
	v_add_u32_e32 v66, s7, v40
	v_add_u32_e32 v68, s7, v43
	v_add_u32_e32 v70, s7, v42
	v_add_u32_e32 v76, s7, v47
	v_add_u32_e32 v78, s7, v46
	v_add_u32_e32 v64, s7, v41
	v_ashrrev_i32_e32 v67, 31, v66
	v_ashrrev_i32_e32 v71, 31, v70
	v_ashrrev_i32_e32 v69, 31, v68
	v_add_u32_e32 v72, s7, v45
	v_add_u32_e32 v74, s7, v44
	v_ashrrev_i32_e32 v79, 31, v78
	v_ashrrev_i32_e32 v77, 31, v76
	v_ashrrev_i32_e32 v65, 31, v64
	v_lshlrev_b64 v[66:67], 12, v[66:67]
	v_lshlrev_b64 v[68:69], 12, v[68:69]
	v_lshlrev_b64 v[70:71], 12, v[70:71]
	v_ashrrev_i32_e32 v75, 31, v74
	v_ashrrev_i32_e32 v73, 31, v72
	v_lshlrev_b64 v[76:77], 12, v[76:77]
	v_lshlrev_b64 v[78:79], 12, v[78:79]
	v_lshlrev_b64 v[64:65], 12, v[64:65]
	v_lshl_add_u64 v[66:67], v[62:63], 0, v[66:67]
	v_lshl_add_u64 v[70:71], v[62:63], 0, v[70:71]
	v_lshl_add_u64 v[68:69], v[62:63], 0, v[68:69]
	v_lshlrev_b64 v[72:73], 12, v[72:73]
	v_lshlrev_b64 v[74:75], 12, v[74:75]
	v_lshl_add_u64 v[78:79], v[62:63], 0, v[78:79]
	v_lshl_add_u64 v[76:77], v[62:63], 0, v[76:77]
	v_lshl_add_u64 v[64:65], v[62:63], 0, v[64:65]
	v_lshl_add_u64 v[74:75], v[62:63], 0, v[74:75]
	v_lshl_add_u64 v[72:73], v[62:63], 0, v[72:73]
	global_load_dword v96, v[66:67], off nt
	global_load_dword v97, v[64:65], off nt
	global_load_dword v98, v[70:71], off nt
	global_load_dword v99, v[68:69], off nt
	global_load_dword v100, v[74:75], off nt
	global_load_dword v101, v[72:73], off nt
	s_nop 0
	global_load_dword v78, v[78:79], off nt
	s_nop 0
	global_load_dword v76, v[76:77], off nt
	v_add_u32_e32 v66, s7, v48
	v_add_u32_e32 v68, s7, v51
	v_add_u32_e32 v70, s7, v50
	v_add_u32_e32 v64, s7, v49
	v_ashrrev_i32_e32 v67, 31, v66
	v_ashrrev_i32_e32 v71, 31, v70
	v_ashrrev_i32_e32 v69, 31, v68
	v_add_u32_e32 v72, s7, v53
	v_add_u32_e32 v74, s7, v52
	v_ashrrev_i32_e32 v65, 31, v64
	v_lshlrev_b64 v[66:67], 12, v[66:67]
	v_lshlrev_b64 v[68:69], 12, v[68:69]
	v_lshlrev_b64 v[70:71], 12, v[70:71]
	v_ashrrev_i32_e32 v75, 31, v74
	v_ashrrev_i32_e32 v73, 31, v72
	v_lshlrev_b64 v[64:65], 12, v[64:65]
	v_lshl_add_u64 v[66:67], v[62:63], 0, v[66:67]
	v_lshl_add_u64 v[70:71], v[62:63], 0, v[70:71]
	v_lshl_add_u64 v[68:69], v[62:63], 0, v[68:69]
	v_lshlrev_b64 v[72:73], 12, v[72:73]
	v_lshlrev_b64 v[74:75], 12, v[74:75]
	v_lshl_add_u64 v[64:65], v[62:63], 0, v[64:65]
	v_lshl_add_u64 v[74:75], v[62:63], 0, v[74:75]
	v_lshl_add_u64 v[72:73], v[62:63], 0, v[72:73]
	global_load_dword v77, v[66:67], off nt
	global_load_dword v79, v[64:65], off nt
	s_nop 0
	global_load_dword v70, v[70:71], off nt
	s_nop 0
	global_load_dword v68, v[68:69], off nt
	s_nop 0
	global_load_dword v69, v[74:75], off nt
	global_load_dword v71, v[72:73], off nt
	v_add_u32_e32 v66, s7, v54
	v_add_u32_e32 v64, s7, v55
	v_ashrrev_i32_e32 v67, 31, v66
	v_ashrrev_i32_e32 v65, 31, v64
	v_lshlrev_b64 v[66:67], 12, v[66:67]
	v_lshlrev_b64 v[64:65], 12, v[64:65]
	v_lshl_add_u64 v[66:67], v[62:63], 0, v[66:67]
	global_load_dword v66, v[66:67], off nt
	v_lshl_add_u64 v[62:63], v[62:63], 0, v[64:65]
	global_load_dword v62, v[62:63], off nt
	v_add_u32_e32 v63, v126, v132
	s_waitcnt vmcnt(31)
; #define LAS __attribute__((address_space(3)))
; __device__ __forceinline__ unsigned cvt_pk(float lo, float hi) { unsigned r; asm("v_cvt_pk_bf16_f32 %0, %1, %2" : "=v"(r) : "v"(lo), "v"(hi)); return r; }
; template <bool GU>
; __device__ __forceinline__ void transpose_item(const float* W, int K, int N, bf16* WT, const float* gs, LAS float* scr, int item, int lane) {
;     ...
;     for (int i = 0; i < 32; ++i) { const int kk = 2 * i + (lane >> 5); float w = W[(size_t)(k0 + kk) * N + n0 + (lane & 31)]; if (gs) w *= gs[k0 + kk]; scr[kk * 33 + (lane & 31)] = w; }
;     asm volatile("s_waitcnt lgkmcnt(0)" ::: "memory");
;     int d0 = n0;
;     if (GU) { const int f = (n0 < FF) ? n0 : n0 - FF; d0 = 256 * (f >> 7) + (f & 127) + ((n0 < FF) ? 0 : 128); }
;     const int c = lane & 7;
; #pragma unroll
;     for (int j = 0; j < 4; ++j) { const int n = (lane >> 3) + 8 * j; const LAS float* s = scr + (8 * c) * 33 + n;
;         v4u o; o.x = cvt_pk(s[0 * 33], s[1 * 33]); o.y = cvt_pk(s[2 * 33], s[3 * 33]); o.z = cvt_pk(s[4 * 33], s[5 * 33]); o.w = cvt_pk(s[6 * 33], s[7 * 33]);
;         *(v4u*)(WT + (size_t)(d0 + n) * K + k0 + 8 * c) = o; }
;     asm volatile("s_waitcnt lgkmcnt(0)" ::: "memory");
	ds_write_b32 v63, v80
	v_add_u32_e32 v63, v126, v133
	s_waitcnt vmcnt(30)
	ds_write_b32 v63, v81
	v_add_u32_e32 v63, v126, v134
	s_waitcnt vmcnt(29)
	ds_write_b32 v63, v82
	v_add_u32_e32 v63, v126, v135
	s_waitcnt vmcnt(28)
	ds_write_b32 v63, v83
	v_add_u32_e32 v63, v126, v136
	s_waitcnt vmcnt(27)
	ds_write_b32 v63, v84
	v_add_u32_e32 v63, v126, v137
	s_waitcnt vmcnt(26)
	ds_write_b32 v63, v85
	v_add_u32_e32 v63, v126, v138
	s_waitcnt vmcnt(25)
	ds_write_b32 v63, v86
	v_add_u32_e32 v63, v126, v139
	s_waitcnt vmcnt(24)
	ds_write_b32 v63, v87
	v_add_u32_e32 v63, v126, v140
	s_waitcnt vmcnt(23)
	ds_write_b32 v63, v88
	v_add_u32_e32 v63, v126, v141
	s_waitcnt vmcnt(22)
	ds_write_b32 v63, v89
	v_add_u32_e32 v63, v126, v142
	s_waitcnt vmcnt(21)
	ds_write_b32 v63, v90
	v_add_u32_e32 v63, v126, v143
	s_waitcnt vmcnt(20)
	ds_write_b32 v63, v91
	v_add_u32_e32 v63, v126, v144
	s_waitcnt vmcnt(19)
	ds_write_b32 v63, v92
	v_add_u32_e32 v63, v126, v145
	s_waitcnt vmcnt(18)
	ds_write_b32 v63, v93
	v_add_u32_e32 v63, v126, v146
	s_waitcnt vmcnt(17)
	ds_write_b32 v63, v94
	v_add_u32_e32 v63, v126, v147
	s_waitcnt vmcnt(16)
	ds_write_b32 v63, v95
	v_add_u32_e32 v63, v126, v148
	v_add_u32_e32 v84, s6, v127
	s_lshl_b32 s10, s7, 1
	v_ashrrev_i32_e32 v85, 31, v84
	v_lshl_add_u64 v[82:83], v[6:7], 0, s[10:11]
	s_waitcnt vmcnt(15)
	ds_write_b32 v63, v96
	v_add_u32_e32 v63, v126, v149
	s_waitcnt vmcnt(14)
	ds_write_b32 v63, v97
	v_add_u32_e32 v63, v126, v150
	s_waitcnt vmcnt(13)
	ds_write_b32 v63, v98
	v_add_u32_e32 v63, v126, v151
	s_waitcnt vmcnt(12)
	ds_write_b32 v63, v99
	v_add_u32_e32 v63, v126, v152
	s_waitcnt vmcnt(11)
	ds_write_b32 v63, v100
	v_add_u32_e32 v63, v126, v153
	s_waitcnt vmcnt(10)
	ds_write_b32 v63, v101
	v_add_u32_e32 v63, v126, v154
	s_waitcnt vmcnt(9)
	ds_write_b32 v63, v78
	v_add_u32_e32 v63, v126, v155
	s_waitcnt vmcnt(8)
	ds_write_b32 v63, v76
	v_add_u32_e32 v63, v126, v156
	v_lshlrev_b64 v[84:85], 9, v[84:85]
	v_lshl_add_u64 v[84:85], v[82:83], 0, v[84:85]
	s_waitcnt vmcnt(7)
	ds_write_b32 v63, v77
	v_add_u32_e32 v63, v126, v157
	s_waitcnt vmcnt(6)
	ds_write_b32 v63, v79
	v_add_u32_e32 v63, v126, v158
	s_waitcnt vmcnt(5)
	ds_write_b32 v63, v70
	v_add_u32_e32 v63, v126, v159
	s_waitcnt vmcnt(4)
	ds_write_b32 v63, v68
	v_add_u32_e32 v63, v126, v160
	s_waitcnt vmcnt(3)
	ds_write_b32 v63, v69
	v_add_u32_e32 v63, v126, v161
	s_waitcnt vmcnt(2)
	ds_write_b32 v63, v71
	v_add_u32_e32 v63, v126, v162
	s_waitcnt vmcnt(1)
	ds_write_b32 v63, v66
	v_add_u32_e32 v63, v126, v163
	s_waitcnt vmcnt(0)
	ds_write_b32 v63, v62
	s_waitcnt lgkmcnt(0)
	ds_read2_b32 v[66:67], v128 offset0:33 offset1:41
	ds_read2_b32 v[68:69], v128 offset1:8
	ds_read2_b32 v[70:71], v128 offset0:66 offset1:74
	ds_read2_b32 v[72:73], v128 offset0:99 offset1:107
	ds_read2_b32 v[74:75], v128 offset0:132 offset1:140
	ds_read2_b32 v[76:77], v128 offset0:165 offset1:173
	ds_read2_b32 v[78:79], v128 offset0:198 offset1:206
	ds_read2_b32 v[80:81], v128 offset0:231 offset1:239
	s_waitcnt lgkmcnt(6)
	v_cvt_pk_bf16_f32 v62, v68, v66
	v_add_u32_e32 v66, s6, v129
	s_waitcnt lgkmcnt(4)
	v_cvt_pk_bf16_f32 v63, v70, v72
	s_waitcnt lgkmcnt(2)
	v_cvt_pk_bf16_f32 v64, v74, v76
	s_waitcnt lgkmcnt(0)
	v_cvt_pk_bf16_f32 v65, v78, v80
	global_store_dwordx4 v[84:85], v[62:65], off
	s_nop 1
	v_cvt_pk_bf16_f32 v62, v69, v67
	v_ashrrev_i32_e32 v67, 31, v66
	v_lshlrev_b64 v[66:67], 9, v[66:67]
	v_cvt_pk_bf16_f32 v63, v71, v73
	v_cvt_pk_bf16_f32 v64, v75, v77
	v_cvt_pk_bf16_f32 v65, v79, v81
	v_lshl_add_u64 v[66:67], v[82:83], 0, v[66:67]
	ds_read2_b32 v[68:69], v128 offset0:16 offset1:24
	ds_read2_b32 v[70:71], v128 offset0:49 offset1:57
	ds_read2_b32 v[72:73], v128 offset0:82 offset1:90
	ds_read2_b32 v[74:75], v128 offset0:115 offset1:123
	ds_read2_b32 v[76:77], v128 offset0:148 offset1:156
	ds_read2_b32 v[78:79], v128 offset0:181 offset1:189
	ds_read2_b32 v[80:81], v128 offset0:214 offset1:222
	ds_read2_b32 v[84:85], v128 offset0:247 offset1:255
	global_store_dwordx4 v[66:67], v[62:65], off
	v_add_u32_e32 v66, s6, v130
	v_ashrrev_i32_e32 v67, 31, v66
	v_lshlrev_b64 v[66:67], 9, v[66:67]
	v_lshl_add_u64 v[66:67], v[82:83], 0, v[66:67]
	s_waitcnt lgkmcnt(6)
	v_cvt_pk_bf16_f32 v62, v68, v70
	s_waitcnt lgkmcnt(4)
	v_cvt_pk_bf16_f32 v63, v72, v74
	s_waitcnt lgkmcnt(2)
	v_cvt_pk_bf16_f32 v64, v76, v78
	s_waitcnt lgkmcnt(0)
	v_cvt_pk_bf16_f32 v65, v80, v84
	global_store_dwordx4 v[66:67], v[62:65], off
	v_add_u32_e32 v66, s6, v131
	v_ashrrev_i32_e32 v67, 31, v66
	v_lshlrev_b64 v[66:67], 9, v[66:67]
	v_lshl_add_u64 v[66:67], v[82:83], 0, v[66:67]
	v_cvt_pk_bf16_f32 v62, v69, v71
	v_cvt_pk_bf16_f32 v63, v73, v75
	v_cvt_pk_bf16_f32 v64, v77, v79
	v_cvt_pk_bf16_f32 v65, v81, v85
	global_store_dwordx4 v[66:67], v[62:65], off
	s_waitcnt lgkmcnt(0)

; template <bool GU>
; __device__ __forceinline__ void transpose_item(const float* W, int K, int N, bf16* WT, const float* gs, LAS float* scr, int item, int lane) {
;     const int nblk = N / 32, kb = item / nblk, nb = item % nblk, k0 = 64 * kb, n0 = 32 * nb;
; #pragma unroll 16
;     for (int i = 0; i < 32; ++i) { const int kk = 2 * i + (lane >> 5); float w = W[(size_t)(k0 + kk) * N + n0 + (lane & 31)]; if (gs) w *= gs[k0 + kk]; scr[kk * 33 + (lane & 31)] = w; }
; __device__ __forceinline__ void conv_weights(LAS unsigned char* lds, unsigned char* ws, const PIn& I, const int l, const int wave, const int lane, const int gw, const int NGW, const int r_lo, const int r_hi) {
;     ...
;         if (r < I_D) { transpose_item<false>(I.w_d + (size_t)l * FF * DM, FF, DM, (bf16*)(wb + W_D), nullptr, scr, r, lane); continue; } r -= I_D;
.LBB0_715:
	s_andn2_b64 vcc, exec, s[6:7]
	s_cbranch_vccnz .LBB0_717
	s_lshl_b32 s6, s0, 1
	s_add_i32 s6, s6, 0x1dd00
	s_and_b32 s7, s6, 0x1ffc0
	s_lshl_b32 s6, s0, 5
	s_and_b32 s6, s6, 0x3e0
	v_add_u32_e32 v66, s7, v0
	s_lshl_b32 s10, s6, 2
	v_add_u32_e32 v64, s7, v1
	v_ashrrev_i32_e32 v67, 31, v66
	v_add_u32_e32 v68, s7, v27
	v_add_u32_e32 v70, s7, v26
	v_add_u32_e32 v72, s7, v29
	v_add_u32_e32 v74, s7, v28
	v_add_u32_e32 v76, s7, v31
	v_add_u32_e32 v78, s7, v30
	v_lshl_add_u64 v[62:63], v[20:21], 0, s[10:11]
	v_ashrrev_i32_e32 v65, 31, v64
	v_lshlrev_b64 v[66:67], 12, v[66:67]
	v_ashrrev_i32_e32 v71, 31, v70
	v_ashrrev_i32_e32 v69, 31, v68
	v_ashrrev_i32_e32 v75, 31, v74
	v_ashrrev_i32_e32 v73, 31, v72
	v_ashrrev_i32_e32 v79, 31, v78
	v_ashrrev_i32_e32 v77, 31, v76
	v_lshlrev_b64 v[64:65], 12, v[64:65]
	v_lshl_add_u64 v[66:67], v[62:63], 0, v[66:67]
	v_lshlrev_b64 v[68:69], 12, v[68:69]
	v_lshlrev_b64 v[70:71], 12, v[70:71]
	v_lshlrev_b64 v[72:73], 12, v[72:73]
	v_lshlrev_b64 v[74:75], 12, v[74:75]
	v_lshlrev_b64 v[76:77], 12, v[76:77]
	v_lshlrev_b64 v[78:79], 12, v[78:79]
	v_lshl_add_u64 v[64:65], v[62:63], 0, v[64:65]
	v_lshl_add_u64 v[70:71], v[62:63], 0, v[70:71]
	v_lshl_add_u64 v[68:69], v[62:63], 0, v[68:69]
	v_lshl_add_u64 v[74:75], v[62:63], 0, v[74:75]
	v_lshl_add_u64 v[72:73], v[62:63], 0, v[72:73]
	v_lshl_add_u64 v[78:79], v[62:63], 0, v[78:79]
	v_lshl_add_u64 v[76:77], v[62:63], 0, v[76:77]
	global_load_dword v80, v[66:67], off nt
	global_load_dword v81, v[64:65], off nt
	global_load_dword v82, v[70:71], off nt
	global_load_dword v83, v[68:69], off nt
	global_load_dword v84, v[74:75], off nt
	global_load_dword v85, v[72:73], off nt
	global_load_dword v86, v[78:79], off nt
	global_load_dword v87, v[76:77], off nt
	v_add_u32_e32 v66, s7, v32
	v_add_u32_e32 v64, s7, v33
	v_ashrrev_i32_e32 v67, 31, v66
	v_add_u32_e32 v68, s7, v35
	v_add_u32_e32 v70, s7, v34
	v_add_u32_e32 v72, s7, v37
	v_add_u32_e32 v74, s7, v36
	v_add_u32_e32 v76, s7, v39
	v_add_u32_e32 v78, s7, v38
	v_ashrrev_i32_e32 v65, 31, v64
	v_lshlrev_b64 v[66:67], 12, v[66:67]
	v_ashrrev_i32_e32 v71, 31, v70
	v_ashrrev_i32_e32 v69, 31, v68
	v_ashrrev_i32_e32 v75, 31, v74
	v_ashrrev_i32_e32 v73, 31, v72
	v_ashrrev_i32_e32 v79, 31, v78
	v_ashrrev_i32_e32 v77, 31, v76
	v_lshlrev_b64 v[64:65], 12, v[64:65]
	v_lshl_add_u64 v[66:67], v[62:63], 0, v[66:67]
	v_lshlrev_b64 v[68:69], 12, v[68:69]
	v_lshlrev_b64 v[70:71], 12, v[70:71]
	v_lshlrev_b64 v[72:73], 12, v[72:73]
	v_lshlrev_b64 v[74:75], 12, v[74:75]
	v_lshlrev_b64 v[76:77], 12, v[76:77]
	v_lshlrev_b64 v[78:79], 12, v[78:79]
	v_lshl_add_u64 v[64:65], v[62:63], 0, v[64:65]
	v_lshl_add_u64 v[70:71], v[62:63], 0, v[70:71]
	v_lshl_add_u64 v[68:69], v[62:63], 0, v[68:69]
	v_lshl_add_u64 v[74:75], v[62:63], 0, v[74:75]
	v_lshl_add_u64 v[72:73], v[62:63], 0, v[72:73]
	v_lshl_add_u64 v[78:79], v[62:63], 0, v[78:79]
	v_lshl_add_u64 v[76:77], v[62:63], 0, v[76:77]
	global_load_dword v88, v[66:67], off nt
	global_load_dword v89, v[64:65], off nt
	global_load_dword v90, v[70:71], off nt
	global_load_dword v91, v[68:69], off nt
	global_load_dword v92, v[74:75], off nt
	global_load_dword v93, v[72:73], off nt
	global_load_dword v94, v[78:79], off nt
	global_load_dword v95, v[76:77], off nt
	v_add_u32_e32 v66, s7, v40
	v_add_u32_e32 v68, s7, v43
	v_add_u32_e32 v70, s7, v42
	v_add_u32_e32 v76, s7, v47
	v_add_u32_e32 v78, s7, v46
	v_add_u32_e32 v64, s7, v41
	v_ashrrev_i32_e32 v67, 31, v66
	v_ashrrev_i32_e32 v71, 31, v70
	v_ashrrev_i32_e32 v69, 31, v68
	v_add_u32_e32 v72, s7, v45
	v_add_u32_e32 v74, s7, v44
	v_ashrrev_i32_e32 v79, 31, v78
	v_ashrrev_i32_e32 v77, 31, v76
	v_ashrrev_i32_e32 v65, 31, v64
	v_lshlrev_b64 v[66:67], 12, v[66:67]
	v_lshlrev_b64 v[68:69], 12, v[68:69]
	v_lshlrev_b64 v[70:71], 12, v[70:71]
	v_ashrrev_i32_e32 v75, 31, v74
	v_ashrrev_i32_e32 v73, 31, v72
	v_lshlrev_b64 v[76:77], 12, v[76:77]
	v_lshlrev_b64 v[78:79], 12, v[78:79]
	v_lshlrev_b64 v[64:65], 12, v[64:65]
	v_lshl_add_u64 v[66:67], v[62:63], 0, v[66:67]
	v_lshl_add_u64 v[70:71], v[62:63], 0, v[70:71]
	v_lshl_add_u64 v[68:69], v[62:63], 0, v[68:69]
	v_lshlrev_b64 v[72:73], 12, v[72:73]
	v_lshlrev_b64 v[74:75], 12, v[74:75]
	v_lshl_add_u64 v[78:79], v[62:63], 0, v[78:79]
	v_lshl_add_u64 v[76:77], v[62:63], 0, v[76:77]
	v_lshl_add_u64 v[64:65], v[62:63], 0, v[64:65]
	v_lshl_add_u64 v[74:75], v[62:63], 0, v[74:75]
	v_lshl_add_u64 v[72:73], v[62:63], 0, v[72:73]
	global_load_dword v96, v[66:67], off nt
	global_load_dword v97, v[64:65], off nt
	global_load_dword v98, v[70:71], off nt
	global_load_dword v99, v[68:69], off nt
	global_load_dword v100, v[74:75], off nt
	global_load_dword v101, v[72:73], off nt
	s_nop 0
	global_load_dword v78, v[78:79], off nt
	s_nop 0
	global_load_dword v76, v[76:77], off nt
	v_add_u32_e32 v66, s7, v48
	v_add_u32_e32 v68, s7, v51
	v_add_u32_e32 v70, s7, v50
	v_add_u32_e32 v64, s7, v49
	v_ashrrev_i32_e32 v67, 31, v66
	v_ashrrev_i32_e32 v71, 31, v70
	v_ashrrev_i32_e32 v69, 31, v68
	v_add_u32_e32 v72, s7, v53
	v_add_u32_e32 v74, s7, v52
	v_ashrrev_i32_e32 v65, 31, v64
	v_lshlrev_b64 v[66:67], 12, v[66:67]
	v_lshlrev_b64 v[68:69], 12, v[68:69]
	v_lshlrev_b64 v[70:71], 12, v[70:71]
	v_ashrrev_i32_e32 v75, 31, v74
	v_ashrrev_i32_e32 v73, 31, v72
	v_lshlrev_b64 v[64:65], 12, v[64:65]
	v_lshl_add_u64 v[66:67], v[62:63], 0, v[66:67]
	v_lshl_add_u64 v[70:71], v[62:63], 0, v[70:71]
	v_lshl_add_u64 v[68:69], v[62:63], 0, v[68:69]
	v_lshlrev_b64 v[72:73], 12, v[72:73]
	v_lshlrev_b64 v[74:75], 12, v[74:75]
	v_lshl_add_u64 v[64:65], v[62:63], 0, v[64:65]
	v_lshl_add_u64 v[74:75], v[62:63], 0, v[74:75]
	v_lshl_add_u64 v[72:73], v[62:63], 0, v[72:73]
	global_load_dword v77, v[66:67], off nt
	global_load_dword v79, v[64:65], off nt
	s_nop 0
	global_load_dword v70, v[70:71], off nt
	s_nop 0
	global_load_dword v68, v[68:69], off nt
	s_nop 0
	global_load_dword v69, v[74:75], off nt
	global_load_dword v71, v[72:73], off nt
	v_add_u32_e32 v66, s7, v54
	v_add_u32_e32 v64, s7, v55
	v_ashrrev_i32_e32 v67, 31, v66
	v_ashrrev_i32_e32 v65, 31, v64
	v_lshlrev_b64 v[66:67], 12, v[66:67]
	v_lshlrev_b64 v[64:65], 12, v[64:65]
	v_lshl_add_u64 v[66:67], v[62:63], 0, v[66:67]
	global_load_dword v66, v[66:67], off nt
	v_lshl_add_u64 v[62:63], v[62:63], 0, v[64:65]
	global_load_dword v62, v[62:63], off nt
	v_add_u32_e32 v63, v126, v132
	s_waitcnt vmcnt(31)
; #define LAS __attribute__((address_space(3)))
; __device__ __forceinline__ unsigned cvt_pk(float lo, float hi) { unsigned r; asm("v_cvt_pk_bf16_f32 %0, %1, %2" : "=v"(r) : "v"(lo), "v"(hi)); return r; }
; template <bool GU>
; __device__ __forceinline__ void transpose_item(const float* W, int K, int N, bf16* WT, const float* gs, LAS float* scr, int item, int lane) {
;     ...
;     for (int i = 0; i < 32; ++i) { const int kk = 2 * i + (lane >> 5); float w = W[(size_t)(k0 + kk) * N + n0 + (lane & 31)]; if (gs) w *= gs[k0 + kk]; scr[kk * 33 + (lane & 31)] = w; }
;     asm volatile("s_waitcnt lgkmcnt(0)" ::: "memory");
;     int d0 = n0;
;     if (GU) { const int f = (n0 < FF) ? n0 : n0 - FF; d0 = 256 * (f >> 7) + (f & 127) + ((n0 < FF) ? 0 : 128); }
;     const int c = lane & 7;
; #pragma unroll
;     for (int j = 0; j < 4; ++j) { const int n = (lane >> 3) + 8 * j; const LAS float* s = scr + (8 * c) * 33 + n;
;         v4u o; o.x = cvt_pk(s[0 * 33], s[1 * 33]); o.y = cvt_pk(s[2 * 33], s[3 * 33]); o.z = cvt_pk(s[4 * 33], s[5 * 33]); o.w = cvt_pk(s[6 * 33], s[7 * 33]);
;         *(v4u*)(WT + (size_t)(d0 + n) * K + k0 + 8 * c) = o; }
;     asm volatile("s_waitcnt lgkmcnt(0)" ::: "memory");
	ds_write_b32 v63, v80
	v_add_u32_e32 v63, v126, v133
	s_waitcnt vmcnt(30)
	ds_write_b32 v63, v81
	v_add_u32_e32 v63, v126, v134
	s_waitcnt vmcnt(29)
	ds_write_b32 v63, v82
	v_add_u32_e32 v63, v126, v135
	s_waitcnt vmcnt(28)
	ds_write_b32 v63, v83
	v_add_u32_e32 v63, v126, v136
	s_waitcnt vmcnt(27)
	ds_write_b32 v63, v84
	v_add_u32_e32 v63, v126, v137
	s_waitcnt vmcnt(26)
	ds_write_b32 v63, v85
	v_add_u32_e32 v63, v126, v138
	s_waitcnt vmcnt(25)
	ds_write_b32 v63, v86
	v_add_u32_e32 v63, v126, v139
	s_waitcnt vmcnt(24)
	ds_write_b32 v63, v87
	v_add_u32_e32 v63, v126, v140
	s_waitcnt vmcnt(23)
	ds_write_b32 v63, v88
	v_add_u32_e32 v63, v126, v141
	s_waitcnt vmcnt(22)
	ds_write_b32 v63, v89
	v_add_u32_e32 v63, v126, v142
	s_waitcnt vmcnt(21)
	ds_write_b32 v63, v90
	v_add_u32_e32 v63, v126, v143
	s_waitcnt vmcnt(20)
	ds_write_b32 v63, v91
	v_add_u32_e32 v63, v126, v144
	s_waitcnt vmcnt(19)
	ds_write_b32 v63, v92
	v_add_u32_e32 v63, v126, v145
	s_waitcnt vmcnt(18)
	ds_write_b32 v63, v93
	v_add_u32_e32 v63, v126, v146
	s_waitcnt vmcnt(17)
	ds_write_b32 v63, v94
	v_add_u32_e32 v63, v126, v147
	s_waitcnt vmcnt(16)
	ds_write_b32 v63, v95
	v_add_u32_e32 v63, v126, v148
	s_lshl_b32 s10, s7, 1
	v_lshl_add_u64 v[82:83], v[8:9], 0, s[10:11]
	s_waitcnt vmcnt(15)
	ds_write_b32 v63, v96
	v_add_u32_e32 v63, v126, v149
	s_waitcnt vmcnt(14)
	ds_write_b32 v63, v97
	v_add_u32_e32 v63, v126, v150
	s_waitcnt vmcnt(13)
	ds_write_b32 v63, v98
	v_add_u32_e32 v63, v126, v151
	s_waitcnt vmcnt(12)
	ds_write_b32 v63, v99
	v_add_u32_e32 v63, v126, v152
	s_waitcnt vmcnt(11)
	ds_write_b32 v63, v100
	v_add_u32_e32 v63, v126, v153
	s_waitcnt vmcnt(10)
	ds_write_b32 v63, v101
	v_add_u32_e32 v63, v126, v154
	s_waitcnt vmcnt(9)
	ds_write_b32 v63, v78
	v_add_u32_e32 v63, v126, v155
	s_waitcnt vmcnt(8)
	ds_write_b32 v63, v76
	v_add_u32_e32 v63, v126, v156
	s_waitcnt vmcnt(7)
	ds_write_b32 v63, v77
	v_add_u32_e32 v63, v126, v157
	s_waitcnt vmcnt(6)
	ds_write_b32 v63, v79
	v_add_u32_e32 v63, v126, v158
	s_waitcnt vmcnt(5)
	ds_write_b32 v63, v70
	v_add_u32_e32 v63, v126, v159
	s_waitcnt vmcnt(4)
	ds_write_b32 v63, v68
	v_add_u32_e32 v63, v126, v160
	s_waitcnt vmcnt(3)
	ds_write_b32 v63, v69
	v_add_u32_e32 v63, v126, v161
	s_waitcnt vmcnt(2)
	ds_write_b32 v63, v71
	v_add_u32_e32 v63, v126, v162
	s_waitcnt vmcnt(1)
	ds_write_b32 v63, v66
	v_add_u32_e32 v63, v126, v163
	s_waitcnt vmcnt(0)
	ds_write_b32 v63, v62
	s_waitcnt lgkmcnt(0)
	ds_read2_b32 v[66:67], v128 offset0:33 offset1:41
	ds_read2_b32 v[68:69], v128 offset1:8
	ds_read2_b32 v[70:71], v128 offset0:66 offset1:74
	ds_read2_b32 v[72:73], v128 offset0:99 offset1:107
	ds_read2_b32 v[74:75], v128 offset0:132 offset1:140
	ds_read2_b32 v[76:77], v128 offset0:165 offset1:173
	ds_read2_b32 v[78:79], v128 offset0:198 offset1:206
	ds_read2_b32 v[80:81], v128 offset0:231 offset1:239
	s_waitcnt lgkmcnt(6)
	v_cvt_pk_bf16_f32 v62, v68, v66
	v_add_u32_e32 v66, s6, v127
	v_mad_i64_i32 v[84:85], s[40:41], v66, s19, v[82:83]
	s_waitcnt lgkmcnt(4)
	v_cvt_pk_bf16_f32 v63, v70, v72
	s_waitcnt lgkmcnt(2)
	v_cvt_pk_bf16_f32 v64, v74, v76
	s_waitcnt lgkmcnt(0)
	v_cvt_pk_bf16_f32 v65, v78, v80
	global_store_dwordx4 v[84:85], v[62:65], off
	v_add_u32_e32 v66, s6, v129
	s_nop 0
	v_cvt_pk_bf16_f32 v62, v69, v67
	v_cvt_pk_bf16_f32 v63, v71, v73
	v_cvt_pk_bf16_f32 v64, v75, v77
	v_cvt_pk_bf16_f32 v65, v79, v81
	ds_read2_b32 v[68:69], v128 offset0:16 offset1:24
	ds_read2_b32 v[70:71], v128 offset0:49 offset1:57
	ds_read2_b32 v[72:73], v128 offset0:82 offset1:90
	ds_read2_b32 v[74:75], v128 offset0:115 offset1:123
	ds_read2_b32 v[76:77], v128 offset0:148 offset1:156
	ds_read2_b32 v[78:79], v128 offset0:181 offset1:189
	ds_read2_b32 v[80:81], v128 offset0:214 offset1:222
	ds_read2_b32 v[84:85], v128 offset0:247 offset1:255
	v_mad_i64_i32 v[66:67], s[40:41], v66, s19, v[82:83]
	global_store_dwordx4 v[66:67], v[62:65], off
	v_add_u32_e32 v66, s6, v130
	v_mad_i64_i32 v[66:67], s[40:41], v66, s19, v[82:83]
	s_waitcnt lgkmcnt(6)
	v_cvt_pk_bf16_f32 v62, v68, v70
	s_waitcnt lgkmcnt(4)
	v_cvt_pk_bf16_f32 v63, v72, v74
	s_waitcnt lgkmcnt(2)
	v_cvt_pk_bf16_f32 v64, v76, v78
	s_waitcnt lgkmcnt(0)
	v_cvt_pk_bf16_f32 v65, v80, v84
	global_store_dwordx4 v[66:67], v[62:65], off
	v_add_u32_e32 v66, s6, v131
	v_mad_i64_i32 v[66:67], s[6:7], v66, s19, v[82:83]
	v_cvt_pk_bf16_f32 v62, v69, v71
	v_cvt_pk_bf16_f32 v63, v73, v75
	v_cvt_pk_bf16_f32 v64, v77, v79
	v_cvt_pk_bf16_f32 v65, v81, v85
	global_store_dwordx4 v[66:67], v[62:65], off
	s_waitcnt lgkmcnt(0)

; #define LAS __attribute__((address_space(3)))
; template <bool GU>
; __device__ __forceinline__ void transpose_item(const float* W, int K, int N, bf16* WT, const float* gs, LAS float* scr, int item, int lane) {
;     const int nblk = N / 32, kb = item / nblk, nb = item % nblk, k0 = 64 * kb, n0 = 32 * nb;
; #pragma unroll 16
;     for (int i = 0; i < 32; ++i) { const int kk = 2 * i + (lane >> 5); float w = W[(size_t)(k0 + kk) * N + n0 + (lane & 31)]; if (gs) w *= gs[k0 + kk]; scr[kk * 33 + (lane & 31)] = w; }
; __device__ __forceinline__ void conv_weights(LAS unsigned char* lds, unsigned char* ws, const PIn& I, const int l, const int wave, const int lane, const int gw, const int NGW, const int r_lo, const int r_hi) {
;     ...
;         if (r < I_GU) { transpose_item<true>(I.w_gu + (size_t)l * DM * 2 * FF, DM, 2 * FF, (bf16*)(wb + W_GU), I.g_ffn + l * DM, scr, r, lane); continue; } r -= I_GU;
.LBB0_718:
	s_andn2_b64 vcc, exec, s[6:7]
	s_cbranch_vccnz .LBB0_754
	s_add_i32 s6, s0, 0xf980
	s_and_b32 s10, s6, 0xffff
	s_mul_i32 s7, s10, 0xba2f
	s_lshr_b32 s7, s7, 23
	s_mul_i32 s40, s7, 0xb0
	s_sub_i32 s41, s6, s40
	s_lshl_b32 s6, s41, 7
	s_lshl_b32 s40, s7, 6
	s_lshl_b32 s50, s41, 5
	s_and_b32 s48, s6, 0x3ff80
	s_add_u32 s6, s2, s48
	v_add_u32_e32 v64, s40, v39
	s_addc_u32 s7, s3, 0
	v_add_u32_e32 v68, s40, v38
	v_add_u32_e32 v72, s40, v37
	v_add_u32_e32 v76, s40, v36
	v_add_u32_e32 v80, s40, v35
	v_add_u32_e32 v84, s40, v34
	v_add_u32_e32 v88, s40, v33
	v_add_u32_e32 v92, s40, v32
	v_add_u32_e32 v96, s40, v31
	v_add_u32_e32 v100, s40, v30
	v_add_u32_e32 v104, s40, v29
	v_add_u32_e32 v108, s40, v28
	v_add_u32_e32 v112, s40, v27
	v_add_u32_e32 v116, s40, v26
	v_ashrrev_i32_e32 v65, 31, v64
	v_mov_b64_e32 v[120:121], s[6:7]
	v_ashrrev_i32_e32 v69, 31, v68
	v_ashrrev_i32_e32 v73, 31, v72
	v_ashrrev_i32_e32 v77, 31, v76
	v_ashrrev_i32_e32 v81, 31, v80
	v_ashrrev_i32_e32 v85, 31, v84
	v_ashrrev_i32_e32 v89, 31, v88
	v_ashrrev_i32_e32 v93, 31, v92
	v_ashrrev_i32_e32 v97, 31, v96
	v_ashrrev_i32_e32 v101, 31, v100
	v_ashrrev_i32_e32 v105, 31, v104
	v_ashrrev_i32_e32 v109, 31, v108
	v_ashrrev_i32_e32 v113, 31, v112
	v_ashrrev_i32_e32 v117, 31, v116
	v_add_u32_e32 v122, s40, v1
	v_lshl_add_u64 v[62:63], v[64:65], 2, s[30:31]
	v_mad_i64_i32 v[64:65], s[6:7], v64, s18, v[120:121]
	v_lshl_add_u64 v[66:67], v[68:69], 2, s[30:31]
	v_mad_i64_i32 v[68:69], s[6:7], v68, s18, v[120:121]
	v_lshl_add_u64 v[70:71], v[72:73], 2, s[30:31]
	v_mad_i64_i32 v[72:73], s[6:7], v72, s18, v[120:121]
	v_lshl_add_u64 v[74:75], v[76:77], 2, s[30:31]
	v_mad_i64_i32 v[76:77], s[6:7], v76, s18, v[120:121]
	v_lshl_add_u64 v[78:79], v[80:81], 2, s[30:31]
	v_mad_i64_i32 v[80:81], s[6:7], v80, s18, v[120:121]
	v_lshl_add_u64 v[82:83], v[84:85], 2, s[30:31]
	v_mad_i64_i32 v[84:85], s[6:7], v84, s18, v[120:121]
	v_lshl_add_u64 v[86:87], v[88:89], 2, s[30:31]
	v_mad_i64_i32 v[88:89], s[6:7], v88, s18, v[120:121]
	v_lshl_add_u64 v[90:91], v[92:93], 2, s[30:31]
	v_mad_i64_i32 v[92:93], s[6:7], v92, s18, v[120:121]
	v_lshl_add_u64 v[94:95], v[96:97], 2, s[30:31]
	v_mad_i64_i32 v[96:97], s[6:7], v96, s18, v[120:121]
	v_lshl_add_u64 v[98:99], v[100:101], 2, s[30:31]
	v_mad_i64_i32 v[100:101], s[6:7], v100, s18, v[120:121]
	v_lshl_add_u64 v[102:103], v[104:105], 2, s[30:31]
	v_mad_i64_i32 v[104:105], s[6:7], v104, s18, v[120:121]
	v_lshl_add_u64 v[106:107], v[108:109], 2, s[30:31]
	v_mad_i64_i32 v[108:109], s[6:7], v108, s18, v[120:121]
	v_lshl_add_u64 v[110:111], v[112:113], 2, s[30:31]
	v_mad_i64_i32 v[112:113], s[6:7], v112, s18, v[120:121]
	v_lshl_add_u64 v[114:115], v[116:117], 2, s[30:31]
	v_mad_i64_i32 v[116:117], s[6:7], v116, s18, v[120:121]
	v_mad_i64_i32 v[120:121], s[6:7], v122, s18, v[120:121]
	s_mul_hi_u32 s6, s10, 0x1745d18
	v_ashrrev_i32_e32 v123, 31, v122
	s_lshl_b32 s10, s6, 8
	s_mul_i32 s6, s6, 0x160000
	v_lshl_add_u64 v[118:119], v[122:123], 2, s[30:31]
	v_lshl_add_u64 v[122:123], v[58:59], 0, s[10:11]
	s_or_b32 s10, s6, s48
	v_lshl_add_u64 v[124:125], v[60:61], 0, s[10:11]
	s_mov_b64 s[48:49], 0
	v_mov_b32_e32 v165, v164
	s_andn2_b64 vcc, exec, s[12:13]
	s_cbranch_vccnz .LBB0_721
	s_mov_b64 s[58:59], 0xb000
	v_lshl_add_u64 v[234:235], v[124:125], 0, v[2:3]
	v_mov_b32_e32 v236, v122
	v_mov_b32_e32 v237, v123
	global_load_dword v166, v[234:235], off nt
	v_lshl_add_u64 v[234:235], v[234:235], 0, s[58:59]
	global_load_dword v167, v[234:235], off nt
	v_lshl_add_u64 v[234:235], v[234:235], 0, s[58:59]
	global_load_dword v168, v[234:235], off nt
	v_lshl_add_u64 v[234:235], v[234:235], 0, s[58:59]
	global_load_dword v169, v[234:235], off nt
	v_lshl_add_u64 v[234:235], v[234:235], 0, s[58:59]
	global_load_dword v170, v[234:235], off nt
	v_lshl_add_u64 v[234:235], v[234:235], 0, s[58:59]
	global_load_dword v171, v[234:235], off nt
	v_lshl_add_u64 v[234:235], v[234:235], 0, s[58:59]
	global_load_dword v172, v[234:235], off nt
	v_lshl_add_u64 v[234:235], v[234:235], 0, s[58:59]
	global_load_dword v173, v[234:235], off nt
	v_lshl_add_u64 v[234:235], v[234:235], 0, s[58:59]
	global_load_dword v174, v[234:235], off nt
	v_lshl_add_u64 v[234:235], v[234:235], 0, s[58:59]
	global_load_dword v175, v[234:235], off nt
	v_lshl_add_u64 v[234:235], v[234:235], 0, s[58:59]
	global_load_dword v176, v[234:235], off nt
	v_lshl_add_u64 v[234:235], v[234:235], 0, s[58:59]
	global_load_dword v177, v[234:235], off nt
	v_lshl_add_u64 v[234:235], v[234:235], 0, s[58:59]
	global_load_dword v178, v[234:235], off nt
	v_lshl_add_u64 v[234:235], v[234:235], 0, s[58:59]
	global_load_dword v179, v[234:235], off nt
	v_lshl_add_u64 v[234:235], v[234:235], 0, s[58:59]
	global_load_dword v180, v[234:235], off nt
	v_lshl_add_u64 v[234:235], v[234:235], 0, s[58:59]
	global_load_dword v181, v[234:235], off nt
	v_lshl_add_u64 v[234:235], v[234:235], 0, s[58:59]
	global_load_dword v182, v[234:235], off nt
	v_lshl_add_u64 v[234:235], v[234:235], 0, s[58:59]
	global_load_dword v183, v[234:235], off nt
	v_lshl_add_u64 v[234:235], v[234:235], 0, s[58:59]
	global_load_dword v184, v[234:235], off nt
	v_lshl_add_u64 v[234:235], v[234:235], 0, s[58:59]
	global_load_dword v185, v[234:235], off nt
	v_lshl_add_u64 v[234:235], v[234:235], 0, s[58:59]
	global_load_dword v186, v[234:235], off nt
	v_lshl_add_u64 v[234:235], v[234:235], 0, s[58:59]
	global_load_dword v187, v[234:235], off nt
	v_lshl_add_u64 v[234:235], v[234:235], 0, s[58:59]
; template <bool GU>
; __device__ __forceinline__ void transpose_item(const float* W, int K, int N, bf16* WT, const float* gs, LAS float* scr, int item, int lane) {
;     ...
; #pragma unroll 16
;     for (int i = 0; i < 32; ++i) { const int kk = 2 * i + (lane >> 5); float w = W[(size_t)(k0 + kk) * N + n0 + (lane & 31)]; if (gs) w *= gs[k0 + kk]; scr[kk * 33 + (lane & 31)] = w; }
;     asm volatile("s_waitcnt lgkmcnt(0)" ::: "memory");
	global_load_dword v188, v[234:235], off nt
	v_lshl_add_u64 v[234:235], v[234:235], 0, s[58:59]
	global_load_dword v189, v[234:235], off nt
	v_lshl_add_u64 v[234:235], v[234:235], 0, s[58:59]
	global_load_dword v190, v[234:235], off nt
	v_lshl_add_u64 v[234:235], v[234:235], 0, s[58:59]
	global_load_dword v191, v[234:235], off nt
	v_lshl_add_u64 v[234:235], v[234:235], 0, s[58:59]
	global_load_dword v192, v[234:235], off nt
	v_lshl_add_u64 v[234:235], v[234:235], 0, s[58:59]
	global_load_dword v193, v[234:235], off nt
	v_lshl_add_u64 v[234:235], v[234:235], 0, s[58:59]
	global_load_dword v194, v[234:235], off nt
	v_lshl_add_u64 v[234:235], v[234:235], 0, s[58:59]
	global_load_dword v195, v[234:235], off nt
	v_lshl_add_u64 v[234:235], v[234:235], 0, s[58:59]
	global_load_dword v199, v[234:235], off nt
	v_lshl_add_u64 v[234:235], v[234:235], 0, s[58:59]
	global_load_dword v200, v[234:235], off nt
	global_load_dword v201, v[236:237], off nt
	global_load_dword v202, v[236:237], off offset:8
	global_load_dword v203, v[236:237], off offset:16
	global_load_dword v204, v[236:237], off offset:24
	global_load_dword v205, v[236:237], off offset:32
	global_load_dword v206, v[236:237], off offset:40
	global_load_dword v207, v[236:237], off offset:48
	global_load_dword v208, v[236:237], off offset:56
	global_load_dword v209, v[236:237], off offset:64
	global_load_dword v210, v[236:237], off offset:72
	global_load_dword v211, v[236:237], off offset:80
	global_load_dword v212, v[236:237], off offset:88
	global_load_dword v213, v[236:237], off offset:96
	global_load_dword v214, v[236:237], off offset:104
	global_load_dword v215, v[236:237], off offset:112
	global_load_dword v216, v[236:237], off offset:120
	global_load_dword v217, v[236:237], off offset:128
	global_load_dword v218, v[236:237], off offset:136
	global_load_dword v219, v[236:237], off offset:144
	global_load_dword v220, v[236:237], off offset:152
	global_load_dword v221, v[236:237], off offset:160
	global_load_dword v222, v[236:237], off offset:168
	global_load_dword v223, v[236:237], off offset:176
	global_load_dword v224, v[236:237], off offset:184
	global_load_dword v225, v[236:237], off offset:192
	global_load_dword v226, v[236:237], off offset:200
	global_load_dword v227, v[236:237], off offset:208
	global_load_dword v228, v[236:237], off offset:216
	global_load_dword v229, v[236:237], off offset:224
	global_load_dword v230, v[236:237], off offset:232
	global_load_dword v231, v[236:237], off offset:240
	global_load_dword v232, v[236:237], off offset:248
	s_waitcnt vmcnt(31)
	v_mul_f32_e32 v166, v166, v201
	ds_write_b32 v165, v166
	s_waitcnt vmcnt(30)
	v_mul_f32_e32 v167, v167, v202
	ds_write_b32 v165, v167 offset:264
	s_waitcnt vmcnt(29)
	v_mul_f32_e32 v168, v168, v203
	ds_write_b32 v165, v168 offset:528
	s_waitcnt vmcnt(28)
	v_mul_f32_e32 v169, v169, v204
	ds_write_b32 v165, v169 offset:792
	s_waitcnt vmcnt(27)
	v_mul_f32_e32 v170, v170, v205
	ds_write_b32 v165, v170 offset:1056
	s_waitcnt vmcnt(26)
	v_mul_f32_e32 v171, v171, v206
	ds_write_b32 v165, v171 offset:1320
	s_waitcnt vmcnt(25)
	v_mul_f32_e32 v172, v172, v207
	ds_write_b32 v165, v172 offset:1584
	s_waitcnt vmcnt(24)
	v_mul_f32_e32 v173, v173, v208
	ds_write_b32 v165, v173 offset:1848
	s_waitcnt vmcnt(23)
	v_mul_f32_e32 v174, v174, v209
	ds_write_b32 v165, v174 offset:2112
	s_waitcnt vmcnt(22)
	v_mul_f32_e32 v175, v175, v210
	ds_write_b32 v165, v175 offset:2376
	s_waitcnt vmcnt(21)
	v_mul_f32_e32 v176, v176, v211
	ds_write_b32 v165, v176 offset:2640
	s_waitcnt vmcnt(20)
	v_mul_f32_e32 v177, v177, v212
	ds_write_b32 v165, v177 offset:2904
	s_waitcnt vmcnt(19)
	v_mul_f32_e32 v178, v178, v213
	ds_write_b32 v165, v178 offset:3168
	s_waitcnt vmcnt(18)
	v_mul_f32_e32 v179, v179, v214
	ds_write_b32 v165, v179 offset:3432
	s_waitcnt vmcnt(17)
	v_mul_f32_e32 v180, v180, v215
	ds_write_b32 v165, v180 offset:3696
	s_waitcnt vmcnt(16)
	v_mul_f32_e32 v181, v181, v216
	ds_write_b32 v165, v181 offset:3960
	s_waitcnt vmcnt(15)
	v_mul_f32_e32 v182, v182, v217
	ds_write_b32 v165, v182 offset:4224
	s_waitcnt vmcnt(14)
	v_mul_f32_e32 v183, v183, v218
	ds_write_b32 v165, v183 offset:4488
	s_waitcnt vmcnt(13)
	v_mul_f32_e32 v184, v184, v219
	ds_write_b32 v165, v184 offset:4752
	s_waitcnt vmcnt(12)
	v_mul_f32_e32 v185, v185, v220
	ds_write_b32 v165, v185 offset:5016
	s_waitcnt vmcnt(11)
	v_mul_f32_e32 v186, v186, v221
	ds_write_b32 v165, v186 offset:5280
	s_waitcnt vmcnt(10)
	v_mul_f32_e32 v187, v187, v222
	ds_write_b32 v165, v187 offset:5544
	s_waitcnt vmcnt(9)
	v_mul_f32_e32 v188, v188, v223
	ds_write_b32 v165, v188 offset:5808
	s_waitcnt vmcnt(8)
	v_mul_f32_e32 v189, v189, v224
	ds_write_b32 v165, v189 offset:6072
	s_waitcnt vmcnt(7)
	v_mul_f32_e32 v190, v190, v225
	ds_write_b32 v165, v190 offset:6336
	s_waitcnt vmcnt(6)
	v_mul_f32_e32 v191, v191, v226
	ds_write_b32 v165, v191 offset:6600
	s_waitcnt vmcnt(5)
	v_mul_f32_e32 v192, v192, v227
	ds_write_b32 v165, v192 offset:6864
	s_waitcnt vmcnt(4)
	v_mul_f32_e32 v193, v193, v228
	ds_write_b32 v165, v193 offset:7128
	s_waitcnt vmcnt(3)
	v_mul_f32_e32 v194, v194, v229
	ds_write_b32 v165, v194 offset:7392
	s_waitcnt vmcnt(2)
	v_mul_f32_e32 v195, v195, v230
	ds_write_b32 v165, v195 offset:7656
	s_waitcnt vmcnt(1)
	v_mul_f32_e32 v199, v199, v231
	ds_write_b32 v165, v199 offset:7920
	s_waitcnt vmcnt(0)
	v_mul_f32_e32 v200, v200, v232
	ds_write_b32 v165, v200 offset:8184
	s_branch .LBB0_753

; template <bool GU>
; __device__ __forceinline__ void transpose_item(const float* W, int K, int N, bf16* WT, const float* gs, LAS float* scr, int item, int lane) {
;     ...
; #pragma unroll 16
;     for (int i = 0; i < 32; ++i) { const int kk = 2 * i + (lane >> 5); float w = W[(size_t)(k0 + kk) * N + n0 + (lane & 31)]; if (gs) w *= gs[k0 + kk]; scr[kk * 33 + (lane & 31)] = w; }
.LBB0_721:
	v_lshl_add_u64 v[166:167], v[124:125], 0, v[2:3]
	global_load_dword v166, v[166:167], off nt
	v_cndmask_b32_e64 v167, 0, 1, s[12:13]
	v_cmp_ne_u32_e64 s[6:7], 1, v167
	s_andn2_b64 vcc, exec, s[12:13]
	s_cbranch_vccnz .LBB0_723
	v_lshl_add_u64 v[168:169], v[122:123], 0, s[48:49]
	global_load_dword v167, v[168:169], off nt
	s_waitcnt vmcnt(0)
	v_mul_f32_e32 v166, v166, v167
.LBB0_723:
	v_lshl_add_u64 v[168:169], v[120:121], 0, v[2:3]
	global_load_dword v167, v[168:169], off nt
	s_and_b64 vcc, exec, s[6:7]
	s_waitcnt vmcnt(1)
	ds_write_b32 v165, v166
	s_cbranch_vccnz .LBB0_725
	v_lshl_add_u64 v[168:169], v[118:119], 0, s[48:49]
	global_load_dword v166, v[168:169], off nt
	s_waitcnt vmcnt(0)
	v_mul_f32_e32 v167, v167, v166
.LBB0_725:
	v_lshl_add_u64 v[168:169], v[116:117], 0, v[2:3]
	global_load_dword v166, v[168:169], off nt
	s_and_b64 vcc, exec, s[6:7]
	s_waitcnt vmcnt(1)
	ds_write_b32 v165, v167 offset:264
	s_cbranch_vccnz .LBB0_727
	v_lshl_add_u64 v[168:169], v[114:115], 0, s[48:49]
	global_load_dword v167, v[168:169], off nt
	s_waitcnt vmcnt(0)
	v_mul_f32_e32 v166, v166, v167
.LBB0_727:
	v_lshl_add_u64 v[168:169], v[112:113], 0, v[2:3]
	global_load_dword v167, v[168:169], off nt
	s_and_b64 vcc, exec, s[6:7]
	s_waitcnt vmcnt(1)
	ds_write_b32 v165, v166 offset:528
	s_cbranch_vccnz .LBB0_729
	v_lshl_add_u64 v[168:169], v[110:111], 0, s[48:49]
	global_load_dword v166, v[168:169], off nt
	s_waitcnt vmcnt(0)
	v_mul_f32_e32 v167, v167, v166
.LBB0_729:
	v_lshl_add_u64 v[168:169], v[108:109], 0, v[2:3]
	global_load_dword v166, v[168:169], off nt
	s_and_b64 vcc, exec, s[6:7]
	s_waitcnt vmcnt(1)
	ds_write_b32 v165, v167 offset:792
	s_cbranch_vccnz .LBB0_731
	v_lshl_add_u64 v[168:169], v[106:107], 0, s[48:49]
	global_load_dword v167, v[168:169], off nt
	s_waitcnt vmcnt(0)
	v_mul_f32_e32 v166, v166, v167
.LBB0_731:
	v_lshl_add_u64 v[168:169], v[104:105], 0, v[2:3]
	global_load_dword v167, v[168:169], off nt
	s_and_b64 vcc, exec, s[6:7]
	s_waitcnt vmcnt(1)
	ds_write_b32 v165, v166 offset:1056
	s_cbranch_vccnz .LBB0_733
	v_lshl_add_u64 v[168:169], v[102:103], 0, s[48:49]
	global_load_dword v166, v[168:169], off nt
	s_waitcnt vmcnt(0)
	v_mul_f32_e32 v167, v167, v166
.LBB0_733:
	v_lshl_add_u64 v[168:169], v[100:101], 0, v[2:3]
	global_load_dword v166, v[168:169], off nt
	s_and_b64 vcc, exec, s[6:7]
	s_waitcnt vmcnt(1)
	ds_write_b32 v165, v167 offset:1320
	s_cbranch_vccnz .LBB0_735
	v_lshl_add_u64 v[168:169], v[98:99], 0, s[48:49]
	global_load_dword v167, v[168:169], off nt
	s_waitcnt vmcnt(0)
	v_mul_f32_e32 v166, v166, v167
.LBB0_735:
	v_lshl_add_u64 v[168:169], v[96:97], 0, v[2:3]
	global_load_dword v167, v[168:169], off nt
	s_and_b64 vcc, exec, s[6:7]
	s_waitcnt vmcnt(1)
	ds_write_b32 v165, v166 offset:1584
	s_cbranch_vccnz .LBB0_737
	v_lshl_add_u64 v[168:169], v[94:95], 0, s[48:49]
	global_load_dword v166, v[168:169], off nt
	s_waitcnt vmcnt(0)
	v_mul_f32_e32 v167, v167, v166
.LBB0_737:
	v_lshl_add_u64 v[168:169], v[92:93], 0, v[2:3]
	global_load_dword v166, v[168:169], off nt
	s_and_b64 vcc, exec, s[6:7]
	s_waitcnt vmcnt(1)
	ds_write_b32 v165, v167 offset:1848
	s_cbranch_vccnz .LBB0_739
	v_lshl_add_u64 v[168:169], v[90:91], 0, s[48:49]
	global_load_dword v167, v[168:169], off nt
	s_waitcnt vmcnt(0)
	v_mul_f32_e32 v166, v166, v167
.LBB0_739:
	v_lshl_add_u64 v[168:169], v[88:89], 0, v[2:3]
	global_load_dword v167, v[168:169], off nt
	s_and_b64 vcc, exec, s[6:7]
	s_waitcnt vmcnt(1)
	ds_write_b32 v165, v166 offset:2112
	s_cbranch_vccnz .LBB0_741
	v_lshl_add_u64 v[168:169], v[86:87], 0, s[48:49]
	global_load_dword v166, v[168:169], off nt
	s_waitcnt vmcnt(0)
	v_mul_f32_e32 v167, v167, v166
.LBB0_741:
	v_lshl_add_u64 v[168:169], v[84:85], 0, v[2:3]
	global_load_dword v166, v[168:169], off nt
	s_and_b64 vcc, exec, s[6:7]
	s_waitcnt vmcnt(1)
	ds_write_b32 v165, v167 offset:2376
	s_cbranch_vccnz .LBB0_743
	v_lshl_add_u64 v[168:169], v[82:83], 0, s[48:49]
	global_load_dword v167, v[168:169], off nt
	s_waitcnt vmcnt(0)
	v_mul_f32_e32 v166, v166, v167
.LBB0_743:
	v_lshl_add_u64 v[168:169], v[80:81], 0, v[2:3]
	global_load_dword v167, v[168:169], off nt
	s_and_b64 vcc, exec, s[6:7]
	s_waitcnt vmcnt(1)
	ds_write_b32 v165, v166 offset:2640
	s_cbranch_vccnz .LBB0_745
	v_lshl_add_u64 v[168:169], v[78:79], 0, s[48:49]
	global_load_dword v166, v[168:169], off nt
	s_waitcnt vmcnt(0)
	v_mul_f32_e32 v167, v167, v166
.LBB0_745:
	v_lshl_add_u64 v[168:169], v[76:77], 0, v[2:3]
	global_load_dword v166, v[168:169], off nt
	s_and_b64 vcc, exec, s[6:7]
	s_waitcnt vmcnt(1)
	ds_write_b32 v165, v167 offset:2904
	s_cbranch_vccnz .LBB0_747
	v_lshl_add_u64 v[168:169], v[74:75], 0, s[48:49]
	global_load_dword v167, v[168:169], off nt
	s_waitcnt vmcnt(0)
	v_mul_f32_e32 v166, v166, v167
.LBB0_747:
	v_lshl_add_u64 v[168:169], v[72:73], 0, v[2:3]
	global_load_dword v167, v[168:169], off nt
	s_and_b64 vcc, exec, s[6:7]
	s_waitcnt vmcnt(1)
	ds_write_b32 v165, v166 offset:3168
	s_cbranch_vccnz .LBB0_749
	v_lshl_add_u64 v[168:169], v[70:71], 0, s[48:49]
	global_load_dword v166, v[168:169], off nt
	s_waitcnt vmcnt(0)
	v_mul_f32_e32 v167, v167, v166
.LBB0_749:
	v_lshl_add_u64 v[168:169], v[68:69], 0, v[2:3]
	global_load_dword v166, v[168:169], off nt
	s_and_b64 vcc, exec, s[6:7]
	s_waitcnt vmcnt(1)
	ds_write_b32 v165, v167 offset:3432
	s_cbranch_vccnz .LBB0_751
	v_lshl_add_u64 v[168:169], v[66:67], 0, s[48:49]
	global_load_dword v167, v[168:169], off nt
	s_waitcnt vmcnt(0)
	v_mul_f32_e32 v166, v166, v167
.LBB0_751:
	v_lshl_add_u64 v[168:169], v[64:65], 0, v[2:3]
	global_load_dword v167, v[168:169], off nt
	s_and_b64 vcc, exec, s[6:7]
	s_waitcnt vmcnt(1)
	ds_write_b32 v165, v166 offset:3696
	s_cbranch_vccnz .LBB0_720
	v_lshl_add_u64 v[168:169], v[62:63], 0, s[48:49]
	global_load_dword v166, v[168:169], off nt
	s_waitcnt vmcnt(0)
	v_mul_f32_e32 v167, v167, v166
	s_branch .LBB0_720

; template <bool GU>
; __device__ __forceinline__ void transpose_item(const float* W, int K, int N, bf16* WT, const float* gs, LAS float* scr, int item, int lane) {
;     const int nblk = N / 32, kb = item / nblk, nb = item % nblk, k0 = 64 * kb, n0 = 32 * nb;
; #pragma unroll 16
;     for (int i = 0; i < 32; ++i) { const int kk = 2 * i + (lane >> 5); float w = W[(size_t)(k0 + kk) * N + n0 + (lane & 31)]; if (gs) w *= gs[k0 + kk]; scr[kk * 33 + (lane & 31)] = w; }
; __device__ __forceinline__ void conv_weights(LAS unsigned char* lds, unsigned char* ws, const PIn& I, const int l, const int wave, const int lane, const int gw, const int NGW, const int r_lo, const int r_hi) {
;     ...
;         if (r < I_OUT) { transpose_item<false>(I.w_out + (size_t)l * DM * DM, DM, DM, (bf16*)(wb + W_OUT), nullptr, scr, r, lane); continue; } r -= I_OUT;
.LBB0_755:
	s_andn2_b64 vcc, exec, s[6:7]
	s_cbranch_vccnz .LBB0_757
	s_lshl_b32 s6, s0, 1
	s_add_i32 s6, s6, 0x1f700
	s_and_b32 s7, s6, 0x1ffc0
	s_lshl_b32 s6, s0, 5
	s_and_b32 s6, s6, 0x3e0
	v_add_u32_e32 v66, s7, v0
	s_lshl_b32 s10, s6, 2
	v_add_u32_e32 v64, s7, v1
	v_ashrrev_i32_e32 v67, 31, v66
	v_add_u32_e32 v68, s7, v27
	v_add_u32_e32 v70, s7, v26
	v_add_u32_e32 v72, s7, v29
	v_add_u32_e32 v74, s7, v28
	v_add_u32_e32 v76, s7, v31
	v_add_u32_e32 v78, s7, v30
	v_lshl_add_u64 v[62:63], v[22:23], 0, s[10:11]
	v_ashrrev_i32_e32 v65, 31, v64
	v_lshlrev_b64 v[66:67], 12, v[66:67]
	v_ashrrev_i32_e32 v71, 31, v70
	v_ashrrev_i32_e32 v69, 31, v68
	v_ashrrev_i32_e32 v75, 31, v74
	v_ashrrev_i32_e32 v73, 31, v72
	v_ashrrev_i32_e32 v79, 31, v78
	v_ashrrev_i32_e32 v77, 31, v76
	v_lshlrev_b64 v[64:65], 12, v[64:65]
	v_lshl_add_u64 v[66:67], v[62:63], 0, v[66:67]
	v_lshlrev_b64 v[68:69], 12, v[68:69]
	v_lshlrev_b64 v[70:71], 12, v[70:71]
	v_lshlrev_b64 v[72:73], 12, v[72:73]
	v_lshlrev_b64 v[74:75], 12, v[74:75]
	v_lshlrev_b64 v[76:77], 12, v[76:77]
	v_lshlrev_b64 v[78:79], 12, v[78:79]
	v_lshl_add_u64 v[64:65], v[62:63], 0, v[64:65]
	v_lshl_add_u64 v[70:71], v[62:63], 0, v[70:71]
	v_lshl_add_u64 v[68:69], v[62:63], 0, v[68:69]
	v_lshl_add_u64 v[74:75], v[62:63], 0, v[74:75]
	v_lshl_add_u64 v[72:73], v[62:63], 0, v[72:73]
	v_lshl_add_u64 v[78:79], v[62:63], 0, v[78:79]
	v_lshl_add_u64 v[76:77], v[62:63], 0, v[76:77]
	global_load_dword v80, v[66:67], off nt
	global_load_dword v81, v[64:65], off nt
	global_load_dword v82, v[70:71], off nt
	global_load_dword v83, v[68:69], off nt
	global_load_dword v84, v[74:75], off nt
	global_load_dword v85, v[72:73], off nt
	global_load_dword v86, v[78:79], off nt
	global_load_dword v87, v[76:77], off nt
	v_add_u32_e32 v66, s7, v32
	v_add_u32_e32 v64, s7, v33
	v_ashrrev_i32_e32 v67, 31, v66
	v_add_u32_e32 v68, s7, v35
	v_add_u32_e32 v70, s7, v34
	v_add_u32_e32 v72, s7, v37
	v_add_u32_e32 v74, s7, v36
	v_add_u32_e32 v76, s7, v39
	v_add_u32_e32 v78, s7, v38
	v_ashrrev_i32_e32 v65, 31, v64
	v_lshlrev_b64 v[66:67], 12, v[66:67]
	v_ashrrev_i32_e32 v71, 31, v70
	v_ashrrev_i32_e32 v69, 31, v68
	v_ashrrev_i32_e32 v75, 31, v74
	v_ashrrev_i32_e32 v73, 31, v72
	v_ashrrev_i32_e32 v79, 31, v78
	v_ashrrev_i32_e32 v77, 31, v76
	v_lshlrev_b64 v[64:65], 12, v[64:65]
	v_lshl_add_u64 v[66:67], v[62:63], 0, v[66:67]
	v_lshlrev_b64 v[68:69], 12, v[68:69]
	v_lshlrev_b64 v[70:71], 12, v[70:71]
	v_lshlrev_b64 v[72:73], 12, v[72:73]
	v_lshlrev_b64 v[74:75], 12, v[74:75]
	v_lshlrev_b64 v[76:77], 12, v[76:77]
	v_lshlrev_b64 v[78:79], 12, v[78:79]
	v_lshl_add_u64 v[64:65], v[62:63], 0, v[64:65]
	v_lshl_add_u64 v[70:71], v[62:63], 0, v[70:71]
	v_lshl_add_u64 v[68:69], v[62:63], 0, v[68:69]
	v_lshl_add_u64 v[74:75], v[62:63], 0, v[74:75]
	v_lshl_add_u64 v[72:73], v[62:63], 0, v[72:73]
	v_lshl_add_u64 v[78:79], v[62:63], 0, v[78:79]
	v_lshl_add_u64 v[76:77], v[62:63], 0, v[76:77]
	global_load_dword v88, v[66:67], off nt
	global_load_dword v89, v[64:65], off nt
	global_load_dword v90, v[70:71], off nt
	global_load_dword v91, v[68:69], off nt
	global_load_dword v92, v[74:75], off nt
	global_load_dword v93, v[72:73], off nt
	global_load_dword v94, v[78:79], off nt
	global_load_dword v95, v[76:77], off nt
	v_add_u32_e32 v66, s7, v40
	v_add_u32_e32 v68, s7, v43
	v_add_u32_e32 v70, s7, v42
	v_add_u32_e32 v76, s7, v47
	v_add_u32_e32 v78, s7, v46
	v_add_u32_e32 v64, s7, v41
	v_ashrrev_i32_e32 v67, 31, v66
	v_ashrrev_i32_e32 v71, 31, v70
	v_ashrrev_i32_e32 v69, 31, v68
	v_add_u32_e32 v72, s7, v45
	v_add_u32_e32 v74, s7, v44
	v_ashrrev_i32_e32 v79, 31, v78
	v_ashrrev_i32_e32 v77, 31, v76
	v_ashrrev_i32_e32 v65, 31, v64
	v_lshlrev_b64 v[66:67], 12, v[66:67]
	v_lshlrev_b64 v[68:69], 12, v[68:69]
	v_lshlrev_b64 v[70:71], 12, v[70:71]
	v_ashrrev_i32_e32 v75, 31, v74
	v_ashrrev_i32_e32 v73, 31, v72
	v_lshlrev_b64 v[76:77], 12, v[76:77]
	v_lshlrev_b64 v[78:79], 12, v[78:79]
	v_lshlrev_b64 v[64:65], 12, v[64:65]
	v_lshl_add_u64 v[66:67], v[62:63], 0, v[66:67]
	v_lshl_add_u64 v[70:71], v[62:63], 0, v[70:71]
	v_lshl_add_u64 v[68:69], v[62:63], 0, v[68:69]
	v_lshlrev_b64 v[72:73], 12, v[72:73]
	v_lshlrev_b64 v[74:75], 12, v[74:75]
	v_lshl_add_u64 v[78:79], v[62:63], 0, v[78:79]
	v_lshl_add_u64 v[76:77], v[62:63], 0, v[76:77]
	v_lshl_add_u64 v[64:65], v[62:63], 0, v[64:65]
	v_lshl_add_u64 v[74:75], v[62:63], 0, v[74:75]
	v_lshl_add_u64 v[72:73], v[62:63], 0, v[72:73]
	global_load_dword v96, v[66:67], off nt
	global_load_dword v97, v[64:65], off nt
	global_load_dword v98, v[70:71], off nt
	global_load_dword v99, v[68:69], off nt
	global_load_dword v100, v[74:75], off nt
	global_load_dword v101, v[72:73], off nt
	s_nop 0
	global_load_dword v78, v[78:79], off nt
	s_nop 0
	global_load_dword v76, v[76:77], off nt
	v_add_u32_e32 v66, s7, v48
	v_add_u32_e32 v68, s7, v51
	v_add_u32_e32 v70, s7, v50
	v_add_u32_e32 v64, s7, v49
	v_ashrrev_i32_e32 v67, 31, v66
	v_ashrrev_i32_e32 v71, 31, v70
	v_ashrrev_i32_e32 v69, 31, v68
	v_add_u32_e32 v72, s7, v53
	v_add_u32_e32 v74, s7, v52
	v_ashrrev_i32_e32 v65, 31, v64
	v_lshlrev_b64 v[66:67], 12, v[66:67]
	v_lshlrev_b64 v[68:69], 12, v[68:69]
	v_lshlrev_b64 v[70:71], 12, v[70:71]
	v_ashrrev_i32_e32 v75, 31, v74
	v_ashrrev_i32_e32 v73, 31, v72
	v_lshlrev_b64 v[64:65], 12, v[64:65]
	v_lshl_add_u64 v[66:67], v[62:63], 0, v[66:67]
	v_lshl_add_u64 v[70:71], v[62:63], 0, v[70:71]
	v_lshl_add_u64 v[68:69], v[62:63], 0, v[68:69]
	v_lshlrev_b64 v[72:73], 12, v[72:73]
	v_lshlrev_b64 v[74:75], 12, v[74:75]
	v_lshl_add_u64 v[64:65], v[62:63], 0, v[64:65]
	v_lshl_add_u64 v[74:75], v[62:63], 0, v[74:75]
	v_lshl_add_u64 v[72:73], v[62:63], 0, v[72:73]
	global_load_dword v77, v[66:67], off nt
	global_load_dword v79, v[64:65], off nt
	s_nop 0
	global_load_dword v70, v[70:71], off nt
	s_nop 0
	global_load_dword v68, v[68:69], off nt
	s_nop 0
	global_load_dword v69, v[74:75], off nt
	global_load_dword v71, v[72:73], off nt
	v_add_u32_e32 v66, s7, v54
	v_add_u32_e32 v64, s7, v55
	v_ashrrev_i32_e32 v67, 31, v66
	v_ashrrev_i32_e32 v65, 31, v64
	v_lshlrev_b64 v[66:67], 12, v[66:67]
	v_lshlrev_b64 v[64:65], 12, v[64:65]
	v_lshl_add_u64 v[66:67], v[62:63], 0, v[66:67]
	global_load_dword v66, v[66:67], off nt
	v_lshl_add_u64 v[62:63], v[62:63], 0, v[64:65]
	global_load_dword v62, v[62:63], off nt
	v_add_u32_e32 v63, v126, v132
	s_waitcnt vmcnt(31)
; #define LAS __attribute__((address_space(3)))
; __device__ __forceinline__ unsigned cvt_pk(float lo, float hi) { unsigned r; asm("v_cvt_pk_bf16_f32 %0, %1, %2" : "=v"(r) : "v"(lo), "v"(hi)); return r; }
; template <bool GU>
; __device__ __forceinline__ void transpose_item(const float* W, int K, int N, bf16* WT, const float* gs, LAS float* scr, int item, int lane) {
;     ...
;     for (int i = 0; i < 32; ++i) { const int kk = 2 * i + (lane >> 5); float w = W[(size_t)(k0 + kk) * N + n0 + (lane & 31)]; if (gs) w *= gs[k0 + kk]; scr[kk * 33 + (lane & 31)] = w; }
;     asm volatile("s_waitcnt lgkmcnt(0)" ::: "memory");
;     int d0 = n0;
;     if (GU) { const int f = (n0 < FF) ? n0 : n0 - FF; d0 = 256 * (f >> 7) + (f & 127) + ((n0 < FF) ? 0 : 128); }
;     const int c = lane & 7;
; #pragma unroll
;     for (int j = 0; j < 4; ++j) { const int n = (lane >> 3) + 8 * j; const LAS float* s = scr + (8 * c) * 33 + n;
;         v4u o; o.x = cvt_pk(s[0 * 33], s[1 * 33]); o.y = cvt_pk(s[2 * 33], s[3 * 33]); o.z = cvt_pk(s[4 * 33], s[5 * 33]); o.w = cvt_pk(s[6 * 33], s[7 * 33]);
;         *(v4u*)(WT + (size_t)(d0 + n) * K + k0 + 8 * c) = o; }
;     asm volatile("s_waitcnt lgkmcnt(0)" ::: "memory");
	ds_write_b32 v63, v80
	v_add_u32_e32 v63, v126, v133
	s_waitcnt vmcnt(30)
	ds_write_b32 v63, v81
	v_add_u32_e32 v63, v126, v134
	s_waitcnt vmcnt(29)
	ds_write_b32 v63, v82
	v_add_u32_e32 v63, v126, v135
	s_waitcnt vmcnt(28)
	ds_write_b32 v63, v83
	v_add_u32_e32 v63, v126, v136
	s_waitcnt vmcnt(27)
	ds_write_b32 v63, v84
	v_add_u32_e32 v63, v126, v137
	s_waitcnt vmcnt(26)
	ds_write_b32 v63, v85
	v_add_u32_e32 v63, v126, v138
	s_waitcnt vmcnt(25)
	ds_write_b32 v63, v86
	v_add_u32_e32 v63, v126, v139
	s_waitcnt vmcnt(24)
	ds_write_b32 v63, v87
	v_add_u32_e32 v63, v126, v140
	s_waitcnt vmcnt(23)
	ds_write_b32 v63, v88
	v_add_u32_e32 v63, v126, v141
	s_waitcnt vmcnt(22)
	ds_write_b32 v63, v89
	v_add_u32_e32 v63, v126, v142
	s_waitcnt vmcnt(21)
	ds_write_b32 v63, v90
	v_add_u32_e32 v63, v126, v143
	s_waitcnt vmcnt(20)
	ds_write_b32 v63, v91
	v_add_u32_e32 v63, v126, v144
	s_waitcnt vmcnt(19)
	ds_write_b32 v63, v92
	v_add_u32_e32 v63, v126, v145
	s_waitcnt vmcnt(18)
	ds_write_b32 v63, v93
	v_add_u32_e32 v63, v126, v146
	s_waitcnt vmcnt(17)
	ds_write_b32 v63, v94
	v_add_u32_e32 v63, v126, v147
	s_waitcnt vmcnt(16)
	ds_write_b32 v63, v95
	v_add_u32_e32 v63, v126, v148
	v_add_u32_e32 v84, s6, v127
	s_lshl_b32 s10, s7, 1
	v_ashrrev_i32_e32 v85, 31, v84
	v_lshl_add_u64 v[82:83], v[12:13], 0, s[10:11]
	s_waitcnt vmcnt(15)
	ds_write_b32 v63, v96
	v_add_u32_e32 v63, v126, v149
	s_waitcnt vmcnt(14)
	ds_write_b32 v63, v97
	v_add_u32_e32 v63, v126, v150
	s_waitcnt vmcnt(13)
	ds_write_b32 v63, v98
	v_add_u32_e32 v63, v126, v151
	s_waitcnt vmcnt(12)
	ds_write_b32 v63, v99
	v_add_u32_e32 v63, v126, v152
	s_waitcnt vmcnt(11)
	ds_write_b32 v63, v100
	v_add_u32_e32 v63, v126, v153
	s_waitcnt vmcnt(10)
	ds_write_b32 v63, v101
	v_add_u32_e32 v63, v126, v154
	s_waitcnt vmcnt(9)
	ds_write_b32 v63, v78
	v_add_u32_e32 v63, v126, v155
	s_waitcnt vmcnt(8)
	ds_write_b32 v63, v76
	v_add_u32_e32 v63, v126, v156
	v_lshlrev_b64 v[84:85], 11, v[84:85]
	v_lshl_add_u64 v[84:85], v[82:83], 0, v[84:85]
	s_waitcnt vmcnt(7)
	ds_write_b32 v63, v77
	v_add_u32_e32 v63, v126, v157
	s_waitcnt vmcnt(6)
	ds_write_b32 v63, v79
	v_add_u32_e32 v63, v126, v158
	s_waitcnt vmcnt(5)
	ds_write_b32 v63, v70
	v_add_u32_e32 v63, v126, v159
	s_waitcnt vmcnt(4)
	ds_write_b32 v63, v68
	v_add_u32_e32 v63, v126, v160
	s_waitcnt vmcnt(3)
	ds_write_b32 v63, v69
	v_add_u32_e32 v63, v126, v161
	s_waitcnt vmcnt(2)
	ds_write_b32 v63, v71
	v_add_u32_e32 v63, v126, v162
	s_waitcnt vmcnt(1)
	ds_write_b32 v63, v66
	v_add_u32_e32 v63, v126, v163
	s_waitcnt vmcnt(0)
	ds_write_b32 v63, v62
	s_waitcnt lgkmcnt(0)
	ds_read2_b32 v[66:67], v128 offset0:33 offset1:41
	ds_read2_b32 v[68:69], v128 offset1:8
	ds_read2_b32 v[70:71], v128 offset0:66 offset1:74
	ds_read2_b32 v[72:73], v128 offset0:99 offset1:107
	ds_read2_b32 v[74:75], v128 offset0:132 offset1:140
	ds_read2_b32 v[76:77], v128 offset0:165 offset1:173
	ds_read2_b32 v[78:79], v128 offset0:198 offset1:206
	ds_read2_b32 v[80:81], v128 offset0:231 offset1:239
	s_waitcnt lgkmcnt(6)
	v_cvt_pk_bf16_f32 v62, v68, v66
	v_add_u32_e32 v66, s6, v129
	s_waitcnt lgkmcnt(4)
	v_cvt_pk_bf16_f32 v63, v70, v72
	s_waitcnt lgkmcnt(2)
	v_cvt_pk_bf16_f32 v64, v74, v76
	s_waitcnt lgkmcnt(0)
	v_cvt_pk_bf16_f32 v65, v78, v80
	global_store_dwordx4 v[84:85], v[62:65], off
	s_nop 1
	v_cvt_pk_bf16_f32 v62, v69, v67
	v_ashrrev_i32_e32 v67, 31, v66
	v_lshlrev_b64 v[66:67], 11, v[66:67]
	v_cvt_pk_bf16_f32 v63, v71, v73
	v_cvt_pk_bf16_f32 v64, v75, v77
	v_cvt_pk_bf16_f32 v65, v79, v81
	v_lshl_add_u64 v[66:67], v[82:83], 0, v[66:67]
	ds_read2_b32 v[68:69], v128 offset0:16 offset1:24
	ds_read2_b32 v[70:71], v128 offset0:49 offset1:57
	ds_read2_b32 v[72:73], v128 offset0:82 offset1:90
	ds_read2_b32 v[74:75], v128 offset0:115 offset1:123
	ds_read2_b32 v[76:77], v128 offset0:148 offset1:156
	ds_read2_b32 v[78:79], v128 offset0:181 offset1:189
	ds_read2_b32 v[80:81], v128 offset0:214 offset1:222
	ds_read2_b32 v[84:85], v128 offset0:247 offset1:255
	global_store_dwordx4 v[66:67], v[62:65], off
	v_add_u32_e32 v66, s6, v130
	v_ashrrev_i32_e32 v67, 31, v66
	v_lshlrev_b64 v[66:67], 11, v[66:67]
	v_lshl_add_u64 v[66:67], v[82:83], 0, v[66:67]
	s_waitcnt lgkmcnt(6)
	v_cvt_pk_bf16_f32 v62, v68, v70
	s_waitcnt lgkmcnt(4)
	v_cvt_pk_bf16_f32 v63, v72, v74
	s_waitcnt lgkmcnt(2)
	v_cvt_pk_bf16_f32 v64, v76, v78
	s_waitcnt lgkmcnt(0)
	v_cvt_pk_bf16_f32 v65, v80, v84
	global_store_dwordx4 v[66:67], v[62:65], off
	v_add_u32_e32 v66, s6, v131
	v_ashrrev_i32_e32 v67, 31, v66
	v_lshlrev_b64 v[66:67], 11, v[66:67]
	v_lshl_add_u64 v[66:67], v[82:83], 0, v[66:67]
	v_cvt_pk_bf16_f32 v62, v69, v71
	v_cvt_pk_bf16_f32 v63, v73, v75
	v_cvt_pk_bf16_f32 v64, v77, v79
	v_cvt_pk_bf16_f32 v65, v81, v85
	global_store_dwordx4 v[66:67], v[62:65], off
	s_waitcnt lgkmcnt(0)

; template <bool GU>
; __device__ __forceinline__ void transpose_item(const float* W, int K, int N, bf16* WT, const float* gs, LAS float* scr, int item, int lane) {
;     const int nblk = N / 32, kb = item / nblk, nb = item % nblk, k0 = 64 * kb, n0 = 32 * nb;
; #pragma unroll 16
;     for (int i = 0; i < 32; ++i) { const int kk = 2 * i + (lane >> 5); float w = W[(size_t)(k0 + kk) * N + n0 + (lane & 31)]; if (gs) w *= gs[k0 + kk]; scr[kk * 33 + (lane & 31)] = w; }
; __device__ __forceinline__ void conv_weights(LAS unsigned char* lds, unsigned char* ws, const PIn& I, const int l, const int wave, const int lane, const int gw, const int NGW, const int r_lo, const int r_hi) {
;     ...
;         if (r < I_IN) { transpose_item<false>(I.w_in + (size_t)l * DM * NIN, DM, NIN, (bf16*)(wb + W_IN), I.g_mix + l * DM, scr, r, lane); continue; } r -= I_IN;
.LBB0_758:
	s_mul_hi_i32 s6, s0, 0x38e38e39
	s_lshr_b32 s7, s6, 31
	s_ashr_i32 s6, s6, 4
	s_add_i32 s6, s6, s7
	s_mul_i32 s7, s6, 0x48
	s_sub_i32 s7, s0, s7
	s_lshl_b32 s48, s7, 5
	s_lshl_b32 s50, s6, 6
	s_ashr_i32 s49, s48, 31
	s_lshl_b64 s[6:7], s[48:49], 2
	s_ashr_i32 s51, s50, 31
	v_lshl_add_u64 v[66:67], v[56:57], 0, s[50:51]
	v_mov_b64_e32 v[68:69], s[6:7]
	v_lshl_add_u64 v[62:63], v[24:25], 0, s[6:7]
	v_mad_u64_u32 v[68:69], s[6:7], v66, s29, v[68:69]
	v_mad_i32_i24 v69, v67, s29, v69
	v_add_u32_e32 v70, s50, v56
	v_lshl_add_u64 v[64:65], v[66:67], 2, s[14:15]
	v_lshl_add_u64 v[66:67], v[24:25], 0, v[68:69]
	s_mov_b32 s10, 0
	v_mov_b32_e32 v71, v164
	s_andn2_b64 vcc, exec, s[16:17]
	s_cbranch_vccnz .LBB0_760
	s_mov_b64 s[58:59], 0x4800
	v_mov_b32_e32 v234, v66
	v_mov_b32_e32 v235, v67
	v_mov_b32_e32 v236, v64
	v_mov_b32_e32 v237, v65
	global_load_dword v166, v[234:235], off nt
	v_lshl_add_u64 v[234:235], v[234:235], 0, s[58:59]
	global_load_dword v167, v[234:235], off nt
	v_lshl_add_u64 v[234:235], v[234:235], 0, s[58:59]
	global_load_dword v168, v[234:235], off nt
	v_lshl_add_u64 v[234:235], v[234:235], 0, s[58:59]
	global_load_dword v169, v[234:235], off nt
	v_lshl_add_u64 v[234:235], v[234:235], 0, s[58:59]
	global_load_dword v170, v[234:235], off nt
	v_lshl_add_u64 v[234:235], v[234:235], 0, s[58:59]
	global_load_dword v171, v[234:235], off nt
	v_lshl_add_u64 v[234:235], v[234:235], 0, s[58:59]
	global_load_dword v172, v[234:235], off nt
	v_lshl_add_u64 v[234:235], v[234:235], 0, s[58:59]
	global_load_dword v173, v[234:235], off nt
	v_lshl_add_u64 v[234:235], v[234:235], 0, s[58:59]
	global_load_dword v174, v[234:235], off nt
	v_lshl_add_u64 v[234:235], v[234:235], 0, s[58:59]
	global_load_dword v175, v[234:235], off nt
	v_lshl_add_u64 v[234:235], v[234:235], 0, s[58:59]
	global_load_dword v176, v[234:235], off nt
	v_lshl_add_u64 v[234:235], v[234:235], 0, s[58:59]
	global_load_dword v177, v[234:235], off nt
	v_lshl_add_u64 v[234:235], v[234:235], 0, s[58:59]
	global_load_dword v178, v[234:235], off nt
	v_lshl_add_u64 v[234:235], v[234:235], 0, s[58:59]
	global_load_dword v179, v[234:235], off nt
	v_lshl_add_u64 v[234:235], v[234:235], 0, s[58:59]
	global_load_dword v180, v[234:235], off nt
	v_lshl_add_u64 v[234:235], v[234:235], 0, s[58:59]
	global_load_dword v181, v[234:235], off nt
	v_lshl_add_u64 v[234:235], v[234:235], 0, s[58:59]
	global_load_dword v182, v[234:235], off nt
	v_lshl_add_u64 v[234:235], v[234:235], 0, s[58:59]
	global_load_dword v183, v[234:235], off nt
	v_lshl_add_u64 v[234:235], v[234:235], 0, s[58:59]
	global_load_dword v184, v[234:235], off nt
	v_lshl_add_u64 v[234:235], v[234:235], 0, s[58:59]
	global_load_dword v185, v[234:235], off nt
	v_lshl_add_u64 v[234:235], v[234:235], 0, s[58:59]
	global_load_dword v186, v[234:235], off nt
	v_lshl_add_u64 v[234:235], v[234:235], 0, s[58:59]
	global_load_dword v187, v[234:235], off nt
	v_lshl_add_u64 v[234:235], v[234:235], 0, s[58:59]
	global_load_dword v188, v[234:235], off nt
	v_lshl_add_u64 v[234:235], v[234:235], 0, s[58:59]
	global_load_dword v189, v[234:235], off nt
	v_lshl_add_u64 v[234:235], v[234:235], 0, s[58:59]
	global_load_dword v190, v[234:235], off nt
	v_lshl_add_u64 v[234:235], v[234:235], 0, s[58:59]
	global_load_dword v191, v[234:235], off nt
	v_lshl_add_u64 v[234:235], v[234:235], 0, s[58:59]
	global_load_dword v192, v[234:235], off nt
	v_lshl_add_u64 v[234:235], v[234:235], 0, s[58:59]
	global_load_dword v193, v[234:235], off nt
	v_lshl_add_u64 v[234:235], v[234:235], 0, s[58:59]
	global_load_dword v194, v[234:235], off nt
	v_lshl_add_u64 v[234:235], v[234:235], 0, s[58:59]
	global_load_dword v195, v[234:235], off nt
	v_lshl_add_u64 v[234:235], v[234:235], 0, s[58:59]
	global_load_dword v199, v[234:235], off nt
	v_lshl_add_u64 v[234:235], v[234:235], 0, s[58:59]
	global_load_dword v200, v[234:235], off nt
	global_load_dword v201, v[236:237], off nt
	global_load_dword v202, v[236:237], off offset:8
	global_load_dword v203, v[236:237], off offset:16
	global_load_dword v204, v[236:237], off offset:24
	global_load_dword v205, v[236:237], off offset:32
	global_load_dword v206, v[236:237], off offset:40
	global_load_dword v207, v[236:237], off offset:48
	global_load_dword v208, v[236:237], off offset:56
	global_load_dword v209, v[236:237], off offset:64
	global_load_dword v210, v[236:237], off offset:72
	global_load_dword v211, v[236:237], off offset:80
	global_load_dword v212, v[236:237], off offset:88
	global_load_dword v213, v[236:237], off offset:96
	global_load_dword v214, v[236:237], off offset:104
	global_load_dword v215, v[236:237], off offset:112
	global_load_dword v216, v[236:237], off offset:120
	global_load_dword v217, v[236:237], off offset:128
	global_load_dword v218, v[236:237], off offset:136
	global_load_dword v219, v[236:237], off offset:144
	global_load_dword v220, v[236:237], off offset:152
	global_load_dword v221, v[236:237], off offset:160
	global_load_dword v222, v[236:237], off offset:168
	global_load_dword v223, v[236:237], off offset:176
	global_load_dword v224, v[236:237], off offset:184
	global_load_dword v225, v[236:237], off offset:192
	global_load_dword v226, v[236:237], off offset:200
	global_load_dword v227, v[236:237], off offset:208
	global_load_dword v228, v[236:237], off offset:216
	global_load_dword v229, v[236:237], off offset:224
	global_load_dword v230, v[236:237], off offset:232
	global_load_dword v231, v[236:237], off offset:240
	global_load_dword v232, v[236:237], off offset:248
	s_waitcnt vmcnt(31)
; template <bool GU>
; __device__ __forceinline__ void transpose_item(const float* W, int K, int N, bf16* WT, const float* gs, LAS float* scr, int item, int lane) {
;     ...
;     for (int i = 0; i < 32; ++i) { const int kk = 2 * i + (lane >> 5); float w = W[(size_t)(k0 + kk) * N + n0 + (lane & 31)]; if (gs) w *= gs[k0 + kk]; scr[kk * 33 + (lane & 31)] = w; }
;     asm volatile("s_waitcnt lgkmcnt(0)" ::: "memory");
	v_mul_f32_e32 v166, v166, v201
	ds_write_b32 v71, v166
	s_waitcnt vmcnt(30)
	v_mul_f32_e32 v167, v167, v202
	ds_write_b32 v71, v167 offset:264
	s_waitcnt vmcnt(29)
	v_mul_f32_e32 v168, v168, v203
	ds_write_b32 v71, v168 offset:528
	s_waitcnt vmcnt(28)
	v_mul_f32_e32 v169, v169, v204
	ds_write_b32 v71, v169 offset:792
	s_waitcnt vmcnt(27)
	v_mul_f32_e32 v170, v170, v205
	ds_write_b32 v71, v170 offset:1056
	s_waitcnt vmcnt(26)
	v_mul_f32_e32 v171, v171, v206
	ds_write_b32 v71, v171 offset:1320
	s_waitcnt vmcnt(25)
	v_mul_f32_e32 v172, v172, v207
	ds_write_b32 v71, v172 offset:1584
	s_waitcnt vmcnt(24)
	v_mul_f32_e32 v173, v173, v208
	ds_write_b32 v71, v173 offset:1848
	s_waitcnt vmcnt(23)
	v_mul_f32_e32 v174, v174, v209
	ds_write_b32 v71, v174 offset:2112
	s_waitcnt vmcnt(22)
	v_mul_f32_e32 v175, v175, v210
	ds_write_b32 v71, v175 offset:2376
	s_waitcnt vmcnt(21)
	v_mul_f32_e32 v176, v176, v211
	ds_write_b32 v71, v176 offset:2640
	s_waitcnt vmcnt(20)
	v_mul_f32_e32 v177, v177, v212
	ds_write_b32 v71, v177 offset:2904
	s_waitcnt vmcnt(19)
	v_mul_f32_e32 v178, v178, v213
	ds_write_b32 v71, v178 offset:3168
	s_waitcnt vmcnt(18)
	v_mul_f32_e32 v179, v179, v214
	ds_write_b32 v71, v179 offset:3432
	s_waitcnt vmcnt(17)
	v_mul_f32_e32 v180, v180, v215
	ds_write_b32 v71, v180 offset:3696
	s_waitcnt vmcnt(16)
	v_mul_f32_e32 v181, v181, v216
	ds_write_b32 v71, v181 offset:3960
	s_waitcnt vmcnt(15)
	v_mul_f32_e32 v182, v182, v217
	ds_write_b32 v71, v182 offset:4224
	s_waitcnt vmcnt(14)
	v_mul_f32_e32 v183, v183, v218
	ds_write_b32 v71, v183 offset:4488
	s_waitcnt vmcnt(13)
	v_mul_f32_e32 v184, v184, v219
	ds_write_b32 v71, v184 offset:4752
	s_waitcnt vmcnt(12)
	v_mul_f32_e32 v185, v185, v220
	ds_write_b32 v71, v185 offset:5016
	s_waitcnt vmcnt(11)
	v_mul_f32_e32 v186, v186, v221
	ds_write_b32 v71, v186 offset:5280
	s_waitcnt vmcnt(10)
	v_mul_f32_e32 v187, v187, v222
	ds_write_b32 v71, v187 offset:5544
	s_waitcnt vmcnt(9)
	v_mul_f32_e32 v188, v188, v223
	ds_write_b32 v71, v188 offset:5808
	s_waitcnt vmcnt(8)
	v_mul_f32_e32 v189, v189, v224
	ds_write_b32 v71, v189 offset:6072
	s_waitcnt vmcnt(7)
	v_mul_f32_e32 v190, v190, v225
	ds_write_b32 v71, v190 offset:6336
	s_waitcnt vmcnt(6)
	v_mul_f32_e32 v191, v191, v226
	ds_write_b32 v71, v191 offset:6600
	s_waitcnt vmcnt(5)
	v_mul_f32_e32 v192, v192, v227
	ds_write_b32 v71, v192 offset:6864
	s_waitcnt vmcnt(4)
	v_mul_f32_e32 v193, v193, v228
	ds_write_b32 v71, v193 offset:7128
	s_waitcnt vmcnt(3)
	v_mul_f32_e32 v194, v194, v229
	ds_write_b32 v71, v194 offset:7392
	s_waitcnt vmcnt(2)
	v_mul_f32_e32 v195, v195, v230
	ds_write_b32 v71, v195 offset:7656
	s_waitcnt vmcnt(1)
	v_mul_f32_e32 v199, v199, v231
	ds_write_b32 v71, v199 offset:7920
	s_waitcnt vmcnt(0)
	v_mul_f32_e32 v200, v200, v232
	ds_write_b32 v71, v200 offset:8184
	s_branch .LBB0_703

; template <bool GU>
; __device__ __forceinline__ void transpose_item(const float* W, int K, int N, bf16* WT, const float* gs, LAS float* scr, int item, int lane) {
;     ...
; #pragma unroll 16
;     for (int i = 0; i < 32; ++i) { const int kk = 2 * i + (lane >> 5); float w = W[(size_t)(k0 + kk) * N + n0 + (lane & 31)]; if (gs) w *= gs[k0 + kk]; scr[kk * 33 + (lane & 31)] = w; }
.LBB0_760:
	global_load_dword v69, v[66:67], off nt
	v_cndmask_b32_e64 v68, 0, 1, s[16:17]
	v_cmp_ne_u32_e64 s[6:7], 1, v68
	s_andn2_b64 vcc, exec, s[16:17]
	s_cbranch_vccnz .LBB0_762
	global_load_dword v68, v[64:65], off nt
	s_waitcnt vmcnt(0)
	v_mul_f32_e32 v69, v69, v68
.LBB0_762:
	v_add_u32_e32 v72, s10, v70
	v_add_u32_e32 v68, 2, v72
	v_mad_i64_i32 v[74:75], s[40:41], v68, s29, v[62:63]
	global_load_dword v73, v[74:75], off nt
	s_and_b64 vcc, exec, s[6:7]
	s_waitcnt vmcnt(1)
	ds_write_b32 v71, v69
	s_cbranch_vccnz .LBB0_764
	v_ashrrev_i32_e32 v69, 31, v68
	v_lshl_add_u64 v[68:69], v[68:69], 2, s[14:15]
	global_load_dword v68, v[68:69], off nt
	s_waitcnt vmcnt(0)
	v_mul_f32_e32 v73, v73, v68
.LBB0_764:
	v_add_u32_e32 v68, 4, v72
	v_mad_i64_i32 v[74:75], s[40:41], v68, s29, v[62:63]
	global_load_dword v74, v[74:75], off nt
	s_and_b64 vcc, exec, s[6:7]
	s_waitcnt vmcnt(1)
	ds_write_b32 v71, v73 offset:264
	s_cbranch_vccnz .LBB0_766
	v_ashrrev_i32_e32 v69, 31, v68
	v_lshl_add_u64 v[68:69], v[68:69], 2, s[14:15]
	global_load_dword v68, v[68:69], off nt
	s_waitcnt vmcnt(0)
	v_mul_f32_e32 v74, v74, v68
.LBB0_766:
	v_add_u32_e32 v68, 6, v72
	v_mad_i64_i32 v[76:77], s[40:41], v68, s29, v[62:63]
	global_load_dword v73, v[76:77], off nt
	s_and_b64 vcc, exec, s[6:7]
	s_waitcnt vmcnt(1)
	ds_write_b32 v71, v74 offset:528
	s_cbranch_vccnz .LBB0_768
	v_ashrrev_i32_e32 v69, 31, v68
	v_lshl_add_u64 v[68:69], v[68:69], 2, s[14:15]
	global_load_dword v68, v[68:69], off nt
	s_waitcnt vmcnt(0)
	v_mul_f32_e32 v73, v73, v68
.LBB0_768:
	v_add_u32_e32 v68, 8, v72
	v_mad_i64_i32 v[74:75], s[40:41], v68, s29, v[62:63]
	global_load_dword v74, v[74:75], off nt
	s_and_b64 vcc, exec, s[6:7]
	s_waitcnt vmcnt(1)
	ds_write_b32 v71, v73 offset:792
	s_cbranch_vccnz .LBB0_770
	v_ashrrev_i32_e32 v69, 31, v68
	v_lshl_add_u64 v[68:69], v[68:69], 2, s[14:15]
	global_load_dword v68, v[68:69], off nt
	s_waitcnt vmcnt(0)
	v_mul_f32_e32 v74, v74, v68
.LBB0_770:
	v_add_u32_e32 v68, 10, v72
	v_mad_i64_i32 v[76:77], s[40:41], v68, s29, v[62:63]
	global_load_dword v73, v[76:77], off nt
	s_and_b64 vcc, exec, s[6:7]
	s_waitcnt vmcnt(1)
	ds_write_b32 v71, v74 offset:1056
	s_cbranch_vccnz .LBB0_772
	v_ashrrev_i32_e32 v69, 31, v68
	v_lshl_add_u64 v[68:69], v[68:69], 2, s[14:15]
	global_load_dword v68, v[68:69], off nt
	s_waitcnt vmcnt(0)
	v_mul_f32_e32 v73, v73, v68
.LBB0_772:
	v_add_u32_e32 v68, 12, v72
	v_mad_i64_i32 v[74:75], s[40:41], v68, s29, v[62:63]
	global_load_dword v74, v[74:75], off nt
	s_and_b64 vcc, exec, s[6:7]
	s_waitcnt vmcnt(1)
	ds_write_b32 v71, v73 offset:1320
	s_cbranch_vccnz .LBB0_774
	v_ashrrev_i32_e32 v69, 31, v68
	v_lshl_add_u64 v[68:69], v[68:69], 2, s[14:15]
	global_load_dword v68, v[68:69], off nt
	s_waitcnt vmcnt(0)
	v_mul_f32_e32 v74, v74, v68
.LBB0_774:
	v_add_u32_e32 v68, 14, v72
	v_mad_i64_i32 v[76:77], s[40:41], v68, s29, v[62:63]
	global_load_dword v73, v[76:77], off nt
	s_and_b64 vcc, exec, s[6:7]
	s_waitcnt vmcnt(1)
	ds_write_b32 v71, v74 offset:1584
	s_cbranch_vccnz .LBB0_776
	v_ashrrev_i32_e32 v69, 31, v68
	v_lshl_add_u64 v[68:69], v[68:69], 2, s[14:15]
	global_load_dword v68, v[68:69], off nt
	s_waitcnt vmcnt(0)
	v_mul_f32_e32 v73, v73, v68
.LBB0_776:
	v_add_u32_e32 v68, 16, v72
	v_mad_i64_i32 v[74:75], s[40:41], v68, s29, v[62:63]
	global_load_dword v74, v[74:75], off nt
	s_and_b64 vcc, exec, s[6:7]
	s_waitcnt vmcnt(1)
	ds_write_b32 v71, v73 offset:1848
	s_cbranch_vccnz .LBB0_778
	v_ashrrev_i32_e32 v69, 31, v68
	v_lshl_add_u64 v[68:69], v[68:69], 2, s[14:15]
	global_load_dword v68, v[68:69], off nt
	s_waitcnt vmcnt(0)
	v_mul_f32_e32 v74, v74, v68
.LBB0_778:
	v_add_u32_e32 v68, 18, v72
	v_mad_i64_i32 v[76:77], s[40:41], v68, s29, v[62:63]
	global_load_dword v73, v[76:77], off nt
	s_and_b64 vcc, exec, s[6:7]
	s_waitcnt vmcnt(1)
	ds_write_b32 v71, v74 offset:2112
	s_cbranch_vccnz .LBB0_780
	v_ashrrev_i32_e32 v69, 31, v68
	v_lshl_add_u64 v[68:69], v[68:69], 2, s[14:15]
	global_load_dword v68, v[68:69], off nt
	s_waitcnt vmcnt(0)
	v_mul_f32_e32 v73, v73, v68
.LBB0_780:
	v_add_u32_e32 v68, 20, v72
	v_mad_i64_i32 v[74:75], s[40:41], v68, s29, v[62:63]
	global_load_dword v74, v[74:75], off nt
	s_and_b64 vcc, exec, s[6:7]
	s_waitcnt vmcnt(1)
	ds_write_b32 v71, v73 offset:2376
	s_cbranch_vccnz .LBB0_782
	v_ashrrev_i32_e32 v69, 31, v68
	v_lshl_add_u64 v[68:69], v[68:69], 2, s[14:15]
	global_load_dword v68, v[68:69], off nt
	s_waitcnt vmcnt(0)
	v_mul_f32_e32 v74, v74, v68
.LBB0_782:
	v_add_u32_e32 v68, 22, v72
	v_mad_i64_i32 v[76:77], s[40:41], v68, s29, v[62:63]
	global_load_dword v73, v[76:77], off nt
	s_and_b64 vcc, exec, s[6:7]
	s_waitcnt vmcnt(1)
	ds_write_b32 v71, v74 offset:2640
	s_cbranch_vccnz .LBB0_784
	v_ashrrev_i32_e32 v69, 31, v68
	v_lshl_add_u64 v[68:69], v[68:69], 2, s[14:15]
	global_load_dword v68, v[68:69], off nt
	s_waitcnt vmcnt(0)
	v_mul_f32_e32 v73, v73, v68
.LBB0_784:
	v_add_u32_e32 v68, 24, v72
	v_mad_i64_i32 v[74:75], s[40:41], v68, s29, v[62:63]
	global_load_dword v74, v[74:75], off nt
	s_and_b64 vcc, exec, s[6:7]
	s_waitcnt vmcnt(1)
	ds_write_b32 v71, v73 offset:2904
	s_cbranch_vccnz .LBB0_786
	v_ashrrev_i32_e32 v69, 31, v68
	v_lshl_add_u64 v[68:69], v[68:69], 2, s[14:15]
	global_load_dword v68, v[68:69], off nt
	s_waitcnt vmcnt(0)
	v_mul_f32_e32 v74, v74, v68
.LBB0_786:
	v_add_u32_e32 v68, 26, v72
	v_mad_i64_i32 v[76:77], s[40:41], v68, s29, v[62:63]
	global_load_dword v73, v[76:77], off nt
	s_and_b64 vcc, exec, s[6:7]
	s_waitcnt vmcnt(1)
	ds_write_b32 v71, v74 offset:3168
	s_cbranch_vccnz .LBB0_788
	v_ashrrev_i32_e32 v69, 31, v68
	v_lshl_add_u64 v[68:69], v[68:69], 2, s[14:15]
	global_load_dword v68, v[68:69], off nt
	s_waitcnt vmcnt(0)
	v_mul_f32_e32 v73, v73, v68
.LBB0_788:
	v_add_u32_e32 v68, 28, v72
	v_mad_i64_i32 v[74:75], s[40:41], v68, s29, v[62:63]
	global_load_dword v74, v[74:75], off nt
	s_and_b64 vcc, exec, s[6:7]
	s_waitcnt vmcnt(1)
	ds_write_b32 v71, v73 offset:3432
	s_cbranch_vccnz .LBB0_790
	v_ashrrev_i32_e32 v69, 31, v68
	v_lshl_add_u64 v[68:69], v[68:69], 2, s[14:15]
	global_load_dword v68, v[68:69], off nt
	s_waitcnt vmcnt(0)
	v_mul_f32_e32 v74, v74, v68
.LBB0_790:
	v_add_u32_e32 v68, 30, v72
	v_mad_i64_i32 v[72:73], s[40:41], v68, s29, v[62:63]
	global_load_dword v72, v[72:73], off nt
	s_and_b64 vcc, exec, s[6:7]
	s_waitcnt vmcnt(1)
	ds_write_b32 v71, v74 offset:3696
	s_cbranch_vccnz .LBB0_759
	v_ashrrev_i32_e32 v69, 31, v68
	v_lshl_add_u64 v[68:69], v[68:69], 2, s[14:15]
	global_load_dword v68, v[68:69], off nt
	s_waitcnt vmcnt(0)
	v_mul_f32_e32 v72, v72, v68
	s_branch .LBB0_759

; __device__ __forceinline__ unsigned cvt_pk(float lo, float hi) { unsigned r; asm("v_cvt_pk_bf16_f32 %0, %1, %2" : "=v"(r) : "v"(lo), "v"(hi)); return r; }
;     ...
;     for (size_t i = gtid * 8; i < NA; i += gth * 8) {
;         const size_t gi = (size_t)l * NA + i;
;         const f32x4 a = *(const f32x4*)(I.cak + gi), b = *(const f32x4*)(I.cak + gi + 4), c = *(const f32x4*)(I.cav + gi), d = *(const f32x4*)(I.cav + gi + 4);
;         v4u w; w.x = cvt_pk(a[0], a[1]); w.y = cvt_pk(a[2], a[3]); w.z = cvt_pk(b[0], b[1]); w.w = cvt_pk(b[2], b[3]);
;         *(v4u*)((bf16*)(ws + WS_CKA) + gi) = w;
;         w.x = cvt_pk(c[0], c[1]); w.y = cvt_pk(c[2], c[3]); w.z = cvt_pk(d[0], d[1]); w.w = cvt_pk(d[2], d[3]);
;         *(v4u*)((bf16*)(ws + WS_CVA) + gi) = w;
;         if (((i >> 9) & 511) >= 64) { float* dk = out + O_AKS + gi - 32768; float* dv = out + O_AVS + gi - 32768;
;             *(f32x4*)dk = a; *(f32x4*)(dk + 4) = b; *(f32x4*)dv = c; *(f32x4*)(dv + 4) = d; }
;     }
.LBB0_857:
	v_lshl_add_u64 v[0:1], s[20:21], 0, v[18:19]
	v_lshl_add_u64 v[4:5], v[0:1], 0, s[16:17]
	v_add_co_u32_e32 v0, vcc, 0x1000000, v0
	v_lshl_add_u64 v[12:13], s[22:23], 0, v[18:19]
	s_nop 0
	v_addc_co_u32_e32 v1, vcc, 0, v1, vcc
	v_add_co_u32_e32 v8, vcc, s2, v12
	global_load_dwordx4 v[0:3], v[0:1], off nt
	s_nop 0
	global_load_dwordx4 v[4:7], v[4:5], off offset:16 nt
	v_addc_co_u32_e32 v9, vcc, 0, v13, vcc
	v_lshl_add_u64 v[12:13], v[12:13], 0, s[16:17]
	global_load_dwordx4 v[8:11], v[8:9], off nt
	v_add_co_u32_e32 v32, vcc, s3, v22
	global_load_dwordx4 v[12:15], v[12:13], off offset:16 nt
	v_and_b32_e32 v24, 0x38000, v26
	v_addc_co_u32_e32 v33, vcc, -1, v23, vcc
	v_cmp_ne_u64_e32 vcc, 0, v[24:25]
	s_waitcnt vmcnt(3)
	v_cvt_pk_bf16_f32 v28, v0, v1
	v_cvt_pk_bf16_f32 v29, v2, v3
	s_waitcnt vmcnt(2)
	v_cvt_pk_bf16_f32 v30, v4, v5
	v_cvt_pk_bf16_f32 v31, v6, v7
	global_store_dwordx4 v[32:33], v[28:31], off
	s_waitcnt vmcnt(2)
	s_nop 0
	v_cvt_pk_bf16_f32 v28, v8, v9
	v_cvt_pk_bf16_f32 v29, v10, v11
	s_waitcnt vmcnt(1)
	v_cvt_pk_bf16_f32 v30, v12, v13
	v_cvt_pk_bf16_f32 v31, v14, v15
	global_store_dwordx4 v[22:23], v[28:31], off
	s_and_saveexec_b64 s[38:39], vcc
	s_cbranch_execz .LBB0_856
	v_lshl_add_u64 v[28:29], s[36:37], 0, v[18:19]
	v_add_co_u32_e32 v30, vcc, 0x9c60000, v28
	s_nop 1
	v_addc_co_u32_e32 v31, vcc, 0, v29, vcc
	global_store_dwordx4 v[30:31], v[0:3], off nt
	global_store_dwordx4 v[30:31], v[4:7], off offset:16 nt
	s_nop 0
	v_add_co_u32_e32 v0, vcc, 0xbc60000, v28
	s_nop 1
	v_addc_co_u32_e32 v1, vcc, 0, v29, vcc
	global_store_dwordx4 v[0:1], v[8:11], off nt
	global_store_dwordx4 v[0:1], v[12:15], off offset:16 nt
	s_branch .LBB0_856

; __device__ __forceinline__ unsigned cvt_pk(float lo, float hi) { unsigned r; asm("v_cvt_pk_bf16_f32 %0, %1, %2" : "=v"(r) : "v"(lo), "v"(hi)); return r; }
;     ...
;     for (size_t i = gtid * 8; i < NB; i += gth * 8) {
;         const size_t gi = (size_t)l * NB + i;
;         const f32x4 a = *(const f32x4*)(I.cbk + gi), b = *(const f32x4*)(I.cbk + gi + 4), c = *(const f32x4*)(I.cbv + gi), d = *(const f32x4*)(I.cbv + gi + 4);
;         v4u w; w.x = cvt_pk(a[0], a[1]); w.y = cvt_pk(a[2], a[3]); w.z = cvt_pk(b[0], b[1]); w.w = cvt_pk(b[2], b[3]);
;         *(v4u*)((bf16*)(ws + WS_CKB) + gi) = w;
;         w.x = cvt_pk(c[0], c[1]); w.y = cvt_pk(c[2], c[3]); w.z = cvt_pk(d[0], d[1]); w.w = cvt_pk(d[2], d[3]);
;         *(v4u*)((bf16*)(ws + WS_CVB) + gi) = w;
;         if (((i >> 7) & 127) >= 64) { float* dk = out + O_BKS + gi - 8192; float* dv = out + O_BVS + gi - 8192;
;             *(f32x4*)dk = a; *(f32x4*)(dk + 4) = b; *(f32x4*)dv = c; *(f32x4*)(dv + 4) = d; }
;     }
.LBB0_862:
	v_lshl_add_u64 v[0:1], s[24:25], 0, v[18:19]
	v_lshl_add_u64 v[4:5], v[0:1], 0, s[14:15]
	v_add_co_u32_e32 v0, vcc, 0x100000, v0
	v_lshl_add_u64 v[12:13], s[26:27], 0, v[18:19]
	s_nop 0
	v_addc_co_u32_e32 v1, vcc, 0, v1, vcc
	v_add_co_u32_e32 v8, vcc, s2, v12
	global_load_dwordx4 v[0:3], v[0:1], off nt
	s_nop 0
	global_load_dwordx4 v[4:7], v[4:5], off offset:16 nt
	v_addc_co_u32_e32 v9, vcc, 0, v13, vcc
	v_lshl_add_u64 v[12:13], v[12:13], 0, s[14:15]
	global_load_dwordx4 v[8:11], v[8:9], off nt
	v_add_co_u32_e32 v26, vcc, s3, v20
	global_load_dwordx4 v[12:15], v[12:13], off offset:16 nt
	v_and_b32_e32 v28, 0x2000, v16
	v_addc_co_u32_e32 v27, vcc, -1, v21, vcc
	v_cmp_ne_u32_e32 vcc, 0, v28
	s_waitcnt vmcnt(3)
	v_cvt_pk_bf16_f32 v22, v0, v1
	v_cvt_pk_bf16_f32 v23, v2, v3
	s_waitcnt vmcnt(2)
	v_cvt_pk_bf16_f32 v24, v4, v5
	v_cvt_pk_bf16_f32 v25, v6, v7
	global_store_dwordx4 v[26:27], v[22:25], off
	s_waitcnt vmcnt(2)
	s_nop 0
	v_cvt_pk_bf16_f32 v22, v8, v9
	v_cvt_pk_bf16_f32 v23, v10, v11
	s_waitcnt vmcnt(1)
	v_cvt_pk_bf16_f32 v24, v12, v13
	v_cvt_pk_bf16_f32 v25, v14, v15
	global_store_dwordx4 v[20:21], v[22:25], off
	s_and_saveexec_b64 s[20:21], vcc
	s_cbranch_execz .LBB0_861
	v_lshl_add_u64 v[22:23], s[46:47], 0, v[18:19]
	v_add_co_u32_e32 v24, vcc, 0xcd78000, v22
	s_nop 1
	v_addc_co_u32_e32 v25, vcc, 0, v23, vcc
	global_store_dwordx4 v[24:25], v[0:3], off nt
	global_store_dwordx4 v[24:25], v[4:7], off offset:16 nt
	s_nop 0
	v_add_co_u32_e32 v0, vcc, 0xcf78000, v22
	s_nop 1
	v_addc_co_u32_e32 v1, vcc, 0, v23, vcc
	global_store_dwordx4 v[0:1], v[8:11], off nt
	global_store_dwordx4 v[0:1], v[12:15], off offset:16 nt
	s_branch .LBB0_861

; __global__ void __launch_bounds__(NWAVES * 64, 2) mega_fwd(Args args) {
;     ...
;         for (int m = gw; m < MT; m += NGW) {
;             const float rstd = __builtin_amdgcn_rsqf(ssq[m] * (1.0f / DM) + EPS);
;             float* yr = H + (size_t)m * DM;
; #pragma unroll
;             for (int j = 0; j < 2; ++j) {
;                 const v4u w = *(const v4u*)(XB + (size_t)m * DM + j * 512 + lane * 8);
;                 const f32x4 a = (f32x4){bf_lo(w.x), bf_hi(w.x), bf_lo(w.y), bf_hi(w.y)}, b2 = (f32x4){bf_lo(w.z), bf_hi(w.z), bf_lo(w.w), bf_hi(w.w)};
;                 *(f32x4*)(yr + j * 512 + lane * 8) = a * rstd * gf[j][0]; *(f32x4*)(yr + j * 512 + lane * 8 + 4) = b2 * rstd * gf[j][1];
.LBB0_1411:
	global_load_dword v34, v20, s[0:1]
	global_load_dwordx4 v[36:39], v[16:17], off nt
	global_load_dwordx4 v[40:43], v[16:17], off offset:1024 nt
	s_add_i32 s34, s34, s12
	s_add_u32 s0, s0, s2
	s_addc_u32 s1, s1, s3
	v_lshl_add_u64 v[16:17], v[16:17], 0, s[4:5]
	s_cmp_lt_u32 s34, 0x8000
	s_cbranch_scc1 .Lfin_np1
	s_cmp_gt_u32 s34, 0x83ff
	s_cbranch_scc1 .Lfin_np1
	s_cmp_lg_u32 s64, 0x100
	s_cbranch_scc1 .Lfin_np1
	v_readlane_b32 s14, v249, 1
	v_readlane_b32 s15, v249, 2
	s_nop 4

; __global__ void __launch_bounds__(NWAVES * 64, 2) mega_fwd(Args args) {
;     ...
;         for (int m = gw; m < MT; m += NGW) {
;             const float rstd = __builtin_amdgcn_rsqf(ssq[m] * (1.0f / DM) + EPS);
;             float* yr = H + (size_t)m * DM;
; #pragma unroll
;             for (int j = 0; j < 2; ++j) {
;                 const v4u w = *(const v4u*)(XB + (size_t)m * DM + j * 512 + lane * 8);
;                 const f32x4 a = (f32x4){bf_lo(w.x), bf_hi(w.x), bf_lo(w.y), bf_hi(w.y)}, b2 = (f32x4){bf_lo(w.z), bf_hi(w.z), bf_lo(w.w), bf_hi(w.w)};
;                 *(f32x4*)(yr + j * 512 + lane * 8) = a * rstd * gf[j][0]; *(f32x4*)(yr + j * 512 + lane * 8 + 4) = b2 * rstd * gf[j][1];
;             }
.Lfin_np1:
	s_cmp_gt_i32 s34, 0x83ff
	s_cbranch_scc1 .Lfin_tailA
	global_load_dword v35, v20, s[0:1]
	global_load_dwordx4 v[44:47], v[16:17], off nt
	global_load_dwordx4 v[48:51], v[16:17], off offset:1024 nt
	s_waitcnt vmcnt(3)
	v_fmamk_f32 v30, v34, 0x3a800000, v21
	v_rsq_f32_e32 v30, v30
	v_lshlrev_b32_e32 v26, 16, v36
	v_and_b32_e32 v27, 0xffff0000, v36
	v_lshlrev_b32_e32 v22, 16, v37
	v_and_b32_e32 v23, 0xffff0000, v37
	v_lshlrev_b32_e32 v28, 16, v38
	v_and_b32_e32 v29, 0xffff0000, v38
	v_lshlrev_b32_e32 v24, 16, v39
	v_and_b32_e32 v25, 0xffff0000, v39
	v_pk_mul_f32 v[26:27], v[30:31], v[26:27] op_sel_hi:[0,1]
	v_pk_mul_f32 v[22:23], v[30:31], v[22:23] op_sel_hi:[0,1]
	v_pk_mul_f32 v[32:33], v[30:31], v[28:29] op_sel_hi:[0,1]
	v_pk_mul_f32 v[28:29], v[30:31], v[24:25] op_sel_hi:[0,1]
	v_pk_mul_f32 v[24:25], v[2:3], v[22:23]
	v_pk_mul_f32 v[22:23], v[0:1], v[26:27]
	v_pk_mul_f32 v[28:29], v[10:11], v[28:29]
	v_pk_mul_f32 v[26:27], v[8:9], v[32:33]
	global_store_dwordx4 v[18:19], v[22:25], off offset:-2048 nt
	global_store_dwordx4 v[18:19], v[26:29], off offset:-2032 nt
	v_lshlrev_b32_e32 v56, 16, v40
	v_and_b32_e32 v57, 0xffff0000, v40
	v_lshlrev_b32_e32 v52, 16, v41
	v_and_b32_e32 v53, 0xffff0000, v41
	v_lshlrev_b32_e32 v58, 16, v42
	v_and_b32_e32 v59, 0xffff0000, v42
	v_lshlrev_b32_e32 v54, 16, v43
	v_and_b32_e32 v55, 0xffff0000, v43
	v_pk_mul_f32 v[56:57], v[30:31], v[56:57] op_sel_hi:[0,1]
	v_pk_mul_f32 v[52:53], v[30:31], v[52:53] op_sel_hi:[0,1]
	v_pk_mul_f32 v[62:63], v[30:31], v[58:59] op_sel_hi:[0,1]
	v_pk_mul_f32 v[58:59], v[30:31], v[54:55] op_sel_hi:[0,1]
	v_pk_mul_f32 v[54:55], v[14:15], v[52:53]
	v_pk_mul_f32 v[52:53], v[12:13], v[56:57]
	v_pk_mul_f32 v[58:59], v[6:7], v[58:59]
	v_pk_mul_f32 v[56:57], v[4:5], v[62:63]
	global_store_dwordx4 v[18:19], v[52:55], off nt
	global_store_dwordx4 v[18:19], v[56:59], off offset:16 nt
	v_lshl_add_u64 v[18:19], v[18:19], 0, s[6:7]

; __global__ void __launch_bounds__(NWAVES * 64, 2) mega_fwd(Args args) {
;     ...
;         for (int m = gw; m < MT; m += NGW) {
;             const float rstd = __builtin_amdgcn_rsqf(ssq[m] * (1.0f / DM) + EPS);
;             float* yr = H + (size_t)m * DM;
; #pragma unroll
;             for (int j = 0; j < 2; ++j) {
;                 const v4u w = *(const v4u*)(XB + (size_t)m * DM + j * 512 + lane * 8);
;                 const f32x4 a = (f32x4){bf_lo(w.x), bf_hi(w.x), bf_lo(w.y), bf_hi(w.y)}, b2 = (f32x4){bf_lo(w.z), bf_hi(w.z), bf_lo(w.w), bf_hi(w.w)};
;                 *(f32x4*)(yr + j * 512 + lane * 8) = a * rstd * gf[j][0]; *(f32x4*)(yr + j * 512 + lane * 8 + 4) = b2 * rstd * gf[j][1];
;             }
.Lfin_np2:
	s_cmp_gt_i32 s34, 0x83ff
	s_cbranch_scc1 .Lfin_tailB
	global_load_dword v34, v20, s[0:1]
	global_load_dwordx4 v[36:39], v[16:17], off nt
	global_load_dwordx4 v[40:43], v[16:17], off offset:1024 nt
	s_waitcnt vmcnt(7)
	v_fmamk_f32 v30, v35, 0x3a800000, v21
	v_rsq_f32_e32 v30, v30
	v_lshlrev_b32_e32 v26, 16, v44
	v_and_b32_e32 v27, 0xffff0000, v44
	v_lshlrev_b32_e32 v22, 16, v45
	v_and_b32_e32 v23, 0xffff0000, v45
	v_lshlrev_b32_e32 v28, 16, v46
	v_and_b32_e32 v29, 0xffff0000, v46
	v_lshlrev_b32_e32 v24, 16, v47
	v_and_b32_e32 v25, 0xffff0000, v47
	v_pk_mul_f32 v[26:27], v[30:31], v[26:27] op_sel_hi:[0,1]
	v_pk_mul_f32 v[22:23], v[30:31], v[22:23] op_sel_hi:[0,1]
	v_pk_mul_f32 v[32:33], v[30:31], v[28:29] op_sel_hi:[0,1]
	v_pk_mul_f32 v[28:29], v[30:31], v[24:25] op_sel_hi:[0,1]
	v_pk_mul_f32 v[24:25], v[2:3], v[22:23]
	v_pk_mul_f32 v[22:23], v[0:1], v[26:27]
	v_pk_mul_f32 v[28:29], v[10:11], v[28:29]
	v_pk_mul_f32 v[26:27], v[8:9], v[32:33]
	global_store_dwordx4 v[18:19], v[22:25], off offset:-2048 nt
	global_store_dwordx4 v[18:19], v[26:29], off offset:-2032 nt
	v_lshlrev_b32_e32 v56, 16, v48
	v_and_b32_e32 v57, 0xffff0000, v48
	v_lshlrev_b32_e32 v52, 16, v49
	v_and_b32_e32 v53, 0xffff0000, v49
	v_lshlrev_b32_e32 v58, 16, v50
	v_and_b32_e32 v59, 0xffff0000, v50
	v_lshlrev_b32_e32 v54, 16, v51
	v_and_b32_e32 v55, 0xffff0000, v51
	v_pk_mul_f32 v[56:57], v[30:31], v[56:57] op_sel_hi:[0,1]
	v_pk_mul_f32 v[52:53], v[30:31], v[52:53] op_sel_hi:[0,1]
	v_pk_mul_f32 v[62:63], v[30:31], v[58:59] op_sel_hi:[0,1]
	v_pk_mul_f32 v[58:59], v[30:31], v[54:55] op_sel_hi:[0,1]
	v_pk_mul_f32 v[54:55], v[14:15], v[52:53]
	v_pk_mul_f32 v[52:53], v[12:13], v[56:57]
	v_pk_mul_f32 v[58:59], v[6:7], v[58:59]
	v_pk_mul_f32 v[56:57], v[4:5], v[62:63]
	global_store_dwordx4 v[18:19], v[52:55], off nt
	global_store_dwordx4 v[18:19], v[56:59], off offset:16 nt
	v_lshl_add_u64 v[18:19], v[18:19], 0, s[6:7]
	s_add_i32 s34, s34, s12
	s_add_u32 s0, s0, s2
	s_addc_u32 s1, s1, s3
	v_lshl_add_u64 v[16:17], v[16:17], 0, s[4:5]
	s_cmp_lt_u32 s34, 0x8000
	s_cbranch_scc1 .Lfin_np3
	s_cmp_gt_u32 s34, 0x83ff
	s_cbranch_scc1 .Lfin_np3
	s_cmp_lg_u32 s64, 0x100
	s_cbranch_scc1 .Lfin_np3
	v_readlane_b32 s14, v249, 1
	v_readlane_b32 s15, v249, 2
	s_nop 4

; __global__ void __launch_bounds__(NWAVES * 64, 2) mega_fwd(Args args) {
;     ...
;         for (int m = gw; m < MT; m += NGW) {
;             const float rstd = __builtin_amdgcn_rsqf(ssq[m] * (1.0f / DM) + EPS);
;             float* yr = H + (size_t)m * DM;
; #pragma unroll
;             for (int j = 0; j < 2; ++j) {
;                 const v4u w = *(const v4u*)(XB + (size_t)m * DM + j * 512 + lane * 8);
;                 const f32x4 a = (f32x4){bf_lo(w.x), bf_hi(w.x), bf_lo(w.y), bf_hi(w.y)}, b2 = (f32x4){bf_lo(w.z), bf_hi(w.z), bf_lo(w.w), bf_hi(w.w)};
;                 *(f32x4*)(yr + j * 512 + lane * 8) = a * rstd * gf[j][0]; *(f32x4*)(yr + j * 512 + lane * 8 + 4) = b2 * rstd * gf[j][1];
;             }
.Lfin_np3:
	s_cmp_gt_i32 s34, 0x83ff
	s_cbranch_scc1 .Lfin_tailA
	global_load_dword v35, v20, s[0:1]
	global_load_dwordx4 v[44:47], v[16:17], off nt
	global_load_dwordx4 v[48:51], v[16:17], off offset:1024 nt
	s_waitcnt vmcnt(7)
	v_fmamk_f32 v30, v34, 0x3a800000, v21
	v_rsq_f32_e32 v30, v30
	v_lshlrev_b32_e32 v26, 16, v36
	v_and_b32_e32 v27, 0xffff0000, v36
	v_lshlrev_b32_e32 v22, 16, v37
	v_and_b32_e32 v23, 0xffff0000, v37
	v_lshlrev_b32_e32 v28, 16, v38
	v_and_b32_e32 v29, 0xffff0000, v38
	v_lshlrev_b32_e32 v24, 16, v39
	v_and_b32_e32 v25, 0xffff0000, v39
	v_pk_mul_f32 v[26:27], v[30:31], v[26:27] op_sel_hi:[0,1]
	v_pk_mul_f32 v[22:23], v[30:31], v[22:23] op_sel_hi:[0,1]
	v_pk_mul_f32 v[32:33], v[30:31], v[28:29] op_sel_hi:[0,1]
	v_pk_mul_f32 v[28:29], v[30:31], v[24:25] op_sel_hi:[0,1]
	v_pk_mul_f32 v[24:25], v[2:3], v[22:23]
	v_pk_mul_f32 v[22:23], v[0:1], v[26:27]
	v_pk_mul_f32 v[28:29], v[10:11], v[28:29]
	v_pk_mul_f32 v[26:27], v[8:9], v[32:33]
	global_store_dwordx4 v[18:19], v[22:25], off offset:-2048 nt
	global_store_dwordx4 v[18:19], v[26:29], off offset:-2032 nt
	v_lshlrev_b32_e32 v56, 16, v40
	v_and_b32_e32 v57, 0xffff0000, v40
	v_lshlrev_b32_e32 v52, 16, v41
	v_and_b32_e32 v53, 0xffff0000, v41
	v_lshlrev_b32_e32 v58, 16, v42
	v_and_b32_e32 v59, 0xffff0000, v42
	v_lshlrev_b32_e32 v54, 16, v43
	v_and_b32_e32 v55, 0xffff0000, v43
	v_pk_mul_f32 v[56:57], v[30:31], v[56:57] op_sel_hi:[0,1]
	v_pk_mul_f32 v[52:53], v[30:31], v[52:53] op_sel_hi:[0,1]
	v_pk_mul_f32 v[62:63], v[30:31], v[58:59] op_sel_hi:[0,1]
	v_pk_mul_f32 v[58:59], v[30:31], v[54:55] op_sel_hi:[0,1]
	v_pk_mul_f32 v[54:55], v[14:15], v[52:53]
	v_pk_mul_f32 v[52:53], v[12:13], v[56:57]
	v_pk_mul_f32 v[58:59], v[6:7], v[58:59]
	v_pk_mul_f32 v[56:57], v[4:5], v[62:63]
	global_store_dwordx4 v[18:19], v[52:55], off nt
	global_store_dwordx4 v[18:19], v[56:59], off offset:16 nt
	v_lshl_add_u64 v[18:19], v[18:19], 0, s[6:7]
	s_branch .Lfin_loop
.Lfin_tailA:
	s_waitcnt vmcnt(0)
	v_fmamk_f32 v30, v34, 0x3a800000, v21
	v_rsq_f32_e32 v30, v30
	v_lshlrev_b32_e32 v26, 16, v36
	v_and_b32_e32 v27, 0xffff0000, v36
	v_lshlrev_b32_e32 v22, 16, v37
	v_and_b32_e32 v23, 0xffff0000, v37
	v_lshlrev_b32_e32 v28, 16, v38
	v_and_b32_e32 v29, 0xffff0000, v38
	v_lshlrev_b32_e32 v24, 16, v39
	v_and_b32_e32 v25, 0xffff0000, v39
	v_pk_mul_f32 v[26:27], v[30:31], v[26:27] op_sel_hi:[0,1]
	v_pk_mul_f32 v[22:23], v[30:31], v[22:23] op_sel_hi:[0,1]
	v_pk_mul_f32 v[32:33], v[30:31], v[28:29] op_sel_hi:[0,1]
	v_pk_mul_f32 v[28:29], v[30:31], v[24:25] op_sel_hi:[0,1]
	v_pk_mul_f32 v[24:25], v[2:3], v[22:23]
	v_pk_mul_f32 v[22:23], v[0:1], v[26:27]
	v_pk_mul_f32 v[28:29], v[10:11], v[28:29]
	v_pk_mul_f32 v[26:27], v[8:9], v[32:33]
	global_store_dwordx4 v[18:19], v[22:25], off offset:-2048 nt
	global_store_dwordx4 v[18:19], v[26:29], off offset:-2032 nt
	v_lshlrev_b32_e32 v56, 16, v40
	v_and_b32_e32 v57, 0xffff0000, v40
	v_lshlrev_b32_e32 v52, 16, v41
	v_and_b32_e32 v53, 0xffff0000, v41
	v_lshlrev_b32_e32 v58, 16, v42
	v_and_b32_e32 v59, 0xffff0000, v42
	v_lshlrev_b32_e32 v54, 16, v43
	v_and_b32_e32 v55, 0xffff0000, v43
	v_pk_mul_f32 v[56:57], v[30:31], v[56:57] op_sel_hi:[0,1]
	v_pk_mul_f32 v[52:53], v[30:31], v[52:53] op_sel_hi:[0,1]
	v_pk_mul_f32 v[62:63], v[30:31], v[58:59] op_sel_hi:[0,1]
	v_pk_mul_f32 v[58:59], v[30:31], v[54:55] op_sel_hi:[0,1]
	v_pk_mul_f32 v[54:55], v[14:15], v[52:53]
	v_pk_mul_f32 v[52:53], v[12:13], v[56:57]
	v_pk_mul_f32 v[58:59], v[6:7], v[58:59]
	v_pk_mul_f32 v[56:57], v[4:5], v[62:63]
	global_store_dwordx4 v[18:19], v[52:55], off nt
	global_store_dwordx4 v[18:19], v[56:59], off offset:16 nt
	v_lshl_add_u64 v[18:19], v[18:19], 0, s[6:7]
	s_branch .LBB0_1412
.Lfin_tailB:
	s_waitcnt vmcnt(0)
	v_fmamk_f32 v30, v35, 0x3a800000, v21
	v_rsq_f32_e32 v30, v30
	v_lshlrev_b32_e32 v26, 16, v44
	v_and_b32_e32 v27, 0xffff0000, v44
	v_lshlrev_b32_e32 v22, 16, v45
	v_and_b32_e32 v23, 0xffff0000, v45
	v_lshlrev_b32_e32 v28, 16, v46
	v_and_b32_e32 v29, 0xffff0000, v46
	v_lshlrev_b32_e32 v24, 16, v47
	v_and_b32_e32 v25, 0xffff0000, v47
	v_pk_mul_f32 v[26:27], v[30:31], v[26:27] op_sel_hi:[0,1]
	v_pk_mul_f32 v[22:23], v[30:31], v[22:23] op_sel_hi:[0,1]
	v_pk_mul_f32 v[32:33], v[30:31], v[28:29] op_sel_hi:[0,1]
	v_pk_mul_f32 v[28:29], v[30:31], v[24:25] op_sel_hi:[0,1]
	v_pk_mul_f32 v[24:25], v[2:3], v[22:23]
	v_pk_mul_f32 v[22:23], v[0:1], v[26:27]
	v_pk_mul_f32 v[28:29], v[10:11], v[28:29]
	v_pk_mul_f32 v[26:27], v[8:9], v[32:33]
	global_store_dwordx4 v[18:19], v[22:25], off offset:-2048 nt
	global_store_dwordx4 v[18:19], v[26:29], off offset:-2032 nt
	v_lshlrev_b32_e32 v56, 16, v48
	v_and_b32_e32 v57, 0xffff0000, v48
	v_lshlrev_b32_e32 v52, 16, v49
	v_and_b32_e32 v53, 0xffff0000, v49
	v_lshlrev_b32_e32 v58, 16, v50
	v_and_b32_e32 v59, 0xffff0000, v50
	v_lshlrev_b32_e32 v54, 16, v51
	v_and_b32_e32 v55, 0xffff0000, v51
	v_pk_mul_f32 v[56:57], v[30:31], v[56:57] op_sel_hi:[0,1]
	v_pk_mul_f32 v[52:53], v[30:31], v[52:53] op_sel_hi:[0,1]
	v_pk_mul_f32 v[62:63], v[30:31], v[58:59] op_sel_hi:[0,1]
	v_pk_mul_f32 v[58:59], v[30:31], v[54:55] op_sel_hi:[0,1]
	v_pk_mul_f32 v[54:55], v[14:15], v[52:53]
	v_pk_mul_f32 v[52:53], v[12:13], v[56:57]
	v_pk_mul_f32 v[58:59], v[6:7], v[58:59]
	v_pk_mul_f32 v[56:57], v[4:5], v[62:63]
	global_store_dwordx4 v[18:19], v[52:55], off nt
	global_store_dwordx4 v[18:19], v[56:59], off offset:16 nt
	v_lshl_add_u64 v[18:19], v[18:19], 0, s[6:7]
